# row scales via v_rsq_f32 instead of IEEE sqrt+div expansions (on top of v26)
# speedup vs baseline: 1.0045x; 1.0045x over previous
; __device__ __forceinline__ void load_row_scales(const float* ssp, int row0, int fq, float (&rs)[2][4]) {
;     f32x4 part[2][4];
;     const float* sp = ssp + (size_t)row0 * 16 + 4 * fq;
; #pragma unroll
;     for (int ai = 0; ai < 2; ++ai)
; #pragma unroll
;         for (int m = 0; m < 4; ++m) part[ai][m] = *(const f32x4*)(sp + (size_t)(ai * HALF + m * 16) * 16);
; #pragma unroll
;     for (int ai = 0; ai < 2; ++ai)
; #pragma unroll
;         for (int m = 0; m < 4; ++m) { float t = (part[ai][m][0] + part[ai][m][1]) + (part[ai][m][2] + part[ai][m][3]);
;             t += __shfl_xor(t, 16); t += __shfl_xor(t, 32);
;             rs[ai][m] = 1.0f / sqrtf(t * (1.0f / 1024.0f) + 1e-6f); }
; }
;     __device__ __forceinline__ void operator()(f32x4 (&acc)[2][2][4][2], const Unit& u, int wr, int wc, int fr, int fq) const {
;     ...
;             bf16_t* rowp = R + (size_t)row0 * ldr + (colt - r_col0);
;             float rsa[2][4];
;             if (ssp) load_row_scales(ssp, row0, fq, rsa);
.LBB0_271:
	s_and_b64 vcc, exec, s[6:7]
	s_cbranch_vccnz .LBB0_273
	v_lshlrev_b64 v[130:131], 6, v[172:173]
	v_lshl_add_u64 v[130:131], v[166:167], 0, v[130:131]
	global_load_dwordx4 v[182:185], v[130:131], off
	global_load_dwordx4 v[154:157], v[130:131], off offset:1024
	global_load_dwordx4 v[150:153], v[130:131], off offset:2048
	global_load_dwordx4 v[146:149], v[130:131], off offset:3072
	v_add_co_u32_e32 v130, vcc, 0x2000, v130
	v_and_b32_e32 v175, 64, v229
	s_nop 0
	v_addc_co_u32_e32 v131, vcc, 0, v131, vcc
	v_xor_b32_e32 v0, 16, v229
	v_add_u32_e32 v180, 64, v175
	v_cmp_lt_i32_e32 vcc, v0, v180
	global_load_dwordx4 v[142:145], v[130:131], off
	global_load_dwordx4 v[138:141], v[130:131], off offset:1024
	global_load_dwordx4 v[134:137], v[130:131], off offset:2048
	s_nop 0
	global_load_dwordx4 v[130:133], v[130:131], off offset:3072
	v_cndmask_b32_e32 v0, v229, v0, vcc
	v_lshlrev_b32_e32 v175, 2, v0
	v_xor_b32_e32 v0, 32, v229
	v_cmp_lt_i32_e32 vcc, v0, v180
	s_waitcnt vmcnt(0)
	v_mov_b32_e32 v188, v183
	v_mov_b32_e32 v189, v184
	v_mov_b32_e32 v183, v185
	v_cndmask_b32_e32 v0, v229, v0, vcc
	v_pk_add_f32 v[182:183], v[188:189], v[182:183]
	v_lshlrev_b32_e32 v180, 2, v0
	v_add_f32_e32 v0, v182, v183
	ds_bpermute_b32 v181, v175, v0
	s_waitcnt lgkmcnt(0)
	v_add_f32_e32 v0, v0, v181
	ds_bpermute_b32 v181, v180, v0
	s_waitcnt lgkmcnt(0)
	v_add_f32_e32 v0, v0, v181
	v_fmamk_f32 v0, v0, 0x3a800000, v230
	v_mov_b32_e32 v182, v155
	v_mov_b32_e32 v183, v156
	v_mov_b32_e32 v155, v157
	v_pk_add_f32 v[154:155], v[182:183], v[154:155]
	v_rsq_f32_e32 v0, v0
	s_nop 0
	v_add_f32_e32 v154, v154, v155
	ds_bpermute_b32 v155, v175, v154
	s_waitcnt lgkmcnt(0)
	v_add_f32_e32 v154, v154, v155
	ds_bpermute_b32 v155, v180, v154
	s_waitcnt lgkmcnt(0)
	v_add_f32_e32 v154, v154, v155
	v_fmamk_f32 v154, v154, 0x3a800000, v230
	v_mov_b32_e32 v156, v151
	v_mov_b32_e32 v157, v152
	v_mov_b32_e32 v151, v153
	v_pk_add_f32 v[150:151], v[156:157], v[150:151]
	v_rsq_f32_e32 v154, v154
	s_nop 0
	v_add_f32_e32 v150, v150, v151
	ds_bpermute_b32 v151, v175, v150
	s_waitcnt lgkmcnt(0)
	v_add_f32_e32 v150, v150, v151
	ds_bpermute_b32 v151, v180, v150
	s_waitcnt lgkmcnt(0)
	v_add_f32_e32 v150, v150, v151
	v_fmamk_f32 v150, v150, 0x3a800000, v230
	v_mov_b32_e32 v152, v147
	v_mov_b32_e32 v153, v148
	v_mov_b32_e32 v147, v149
	v_pk_add_f32 v[146:147], v[152:153], v[146:147]
	v_rsq_f32_e32 v150, v150
	s_nop 0
	v_add_f32_e32 v146, v146, v147
	ds_bpermute_b32 v147, v175, v146
	s_waitcnt lgkmcnt(0)
	v_add_f32_e32 v146, v146, v147
	ds_bpermute_b32 v147, v180, v146
	s_waitcnt lgkmcnt(0)
	v_add_f32_e32 v146, v146, v147
	v_fmamk_f32 v146, v146, 0x3a800000, v230
	v_mov_b32_e32 v148, v143
	v_mov_b32_e32 v149, v144
	v_mov_b32_e32 v143, v145
	v_pk_add_f32 v[142:143], v[148:149], v[142:143]
	v_rsq_f32_e32 v146, v146
	s_nop 0
	v_add_f32_e32 v142, v142, v143
	ds_bpermute_b32 v143, v175, v142
	s_waitcnt lgkmcnt(0)
	v_add_f32_e32 v142, v142, v143
	ds_bpermute_b32 v143, v180, v142
	s_waitcnt lgkmcnt(0)
	v_add_f32_e32 v142, v142, v143
	v_fmamk_f32 v142, v142, 0x3a800000, v230
	v_mov_b32_e32 v144, v139
	v_mov_b32_e32 v145, v140
	v_mov_b32_e32 v139, v141
	v_pk_add_f32 v[138:139], v[144:145], v[138:139]
	v_rsq_f32_e32 v142, v142
	s_nop 0
	v_add_f32_e32 v138, v138, v139
	ds_bpermute_b32 v139, v175, v138
	s_waitcnt lgkmcnt(0)
	v_add_f32_e32 v138, v138, v139
	ds_bpermute_b32 v139, v180, v138
	s_waitcnt lgkmcnt(0)
	v_add_f32_e32 v138, v138, v139
	v_fmamk_f32 v138, v138, 0x3a800000, v230
	v_mov_b32_e32 v140, v135
	v_mov_b32_e32 v141, v136
	v_mov_b32_e32 v135, v137
	v_pk_add_f32 v[134:135], v[140:141], v[134:135]
	v_rsq_f32_e32 v138, v138
	s_nop 0
	v_add_f32_e32 v134, v134, v135
	ds_bpermute_b32 v135, v175, v134
	s_waitcnt lgkmcnt(0)
	v_add_f32_e32 v134, v134, v135
	ds_bpermute_b32 v135, v180, v134
	s_waitcnt lgkmcnt(0)
	v_add_f32_e32 v134, v134, v135
	v_fmamk_f32 v134, v134, 0x3a800000, v230
	v_mov_b32_e32 v136, v131
	v_mov_b32_e32 v137, v132
	v_mov_b32_e32 v131, v133
	v_pk_add_f32 v[130:131], v[136:137], v[130:131]
	v_rsq_f32_e32 v134, v134
	s_nop 0
	v_add_f32_e32 v130, v130, v131
	ds_bpermute_b32 v131, v175, v130
	s_waitcnt lgkmcnt(0)
	v_add_f32_e32 v130, v130, v131
	ds_bpermute_b32 v131, v180, v130
	s_waitcnt lgkmcnt(0)
	v_add_f32_e32 v130, v130, v131
	v_fmamk_f32 v130, v130, 0x3a800000, v230
	v_rsq_f32_e32 v130, v130
	s_nop 0
	s_branch .LBB0_274

; __device__ __forceinline__ void load_row_scales(const float* ssp, int row0, int fq, float (&rs)[2][4]) {
;     f32x4 part[2][4];
;     const float* sp = ssp + (size_t)row0 * 16 + 4 * fq;
; #pragma unroll
;     for (int ai = 0; ai < 2; ++ai)
; #pragma unroll
;         for (int m = 0; m < 4; ++m) part[ai][m] = *(const f32x4*)(sp + (size_t)(ai * HALF + m * 16) * 16);
; #pragma unroll
;     for (int ai = 0; ai < 2; ++ai)
; #pragma unroll
;         for (int m = 0; m < 4; ++m) { float t = (part[ai][m][0] + part[ai][m][1]) + (part[ai][m][2] + part[ai][m][3]);
;             t += __shfl_xor(t, 16); t += __shfl_xor(t, 32);
;             rs[ai][m] = 1.0f / sqrtf(t * (1.0f / 1024.0f) + 1e-6f); }
; }
;     __device__ __forceinline__ void operator()(f32x4 (&acc)[2][2][4][2], const Unit& u, int wr, int wc, int fr, int fq) const {
;     ...
;             if (ssp) { float rs[2][4]; load_row_scales(ssp, row0, fq, rs);
; #pragma unroll
;                 for (int ai = 0; ai < 2; ++ai)
; #pragma unroll
;                     for (int m = 0; m < 4; ++m)
; #pragma unroll
;                         for (int bj = 0; bj < 2; ++bj)
; #pragma unroll
;                             for (int n = 0; n < 2; ++n) acc[ai][bj][m][n] = acc[ai][bj][m][n] * rs[ai][m];
;             }
.LBB0_275:
	s_and_b64 vcc, exec, s[6:7]
	s_cbranch_vccnz .LBB0_277
	v_lshlrev_b64 v[130:131], 6, v[172:173]
	v_lshl_add_u64 v[130:131], v[166:167], 0, v[130:131]
	global_load_dwordx4 v[182:185], v[130:131], off
	global_load_dwordx4 v[154:157], v[130:131], off offset:1024
	global_load_dwordx4 v[150:153], v[130:131], off offset:2048
	global_load_dwordx4 v[146:149], v[130:131], off offset:3072
	v_add_co_u32_e32 v130, vcc, 0x2000, v130
	v_and_b32_e32 v175, 64, v229
	s_nop 0
	v_addc_co_u32_e32 v131, vcc, 0, v131, vcc
	v_xor_b32_e32 v0, 16, v229
	v_add_u32_e32 v180, 64, v175
	v_cmp_lt_i32_e32 vcc, v0, v180
	global_load_dwordx4 v[142:145], v[130:131], off
	global_load_dwordx4 v[138:141], v[130:131], off offset:1024
	global_load_dwordx4 v[134:137], v[130:131], off offset:2048
	s_nop 0
	global_load_dwordx4 v[130:133], v[130:131], off offset:3072
	v_cndmask_b32_e32 v0, v229, v0, vcc
	v_lshlrev_b32_e32 v175, 2, v0
	v_xor_b32_e32 v0, 32, v229
	v_cmp_lt_i32_e32 vcc, v0, v180
	s_waitcnt vmcnt(0)
	v_mov_b32_e32 v188, v183
	v_mov_b32_e32 v189, v184
	v_mov_b32_e32 v183, v185
	v_cndmask_b32_e32 v0, v229, v0, vcc
	v_pk_add_f32 v[182:183], v[188:189], v[182:183]
	v_lshlrev_b32_e32 v180, 2, v0
	v_add_f32_e32 v0, v182, v183
	ds_bpermute_b32 v181, v175, v0
	s_waitcnt lgkmcnt(0)
	v_add_f32_e32 v0, v0, v181
	ds_bpermute_b32 v181, v180, v0
	s_waitcnt lgkmcnt(0)
	v_add_f32_e32 v0, v0, v181
	v_fmamk_f32 v0, v0, 0x3a800000, v230
	v_mov_b32_e32 v182, v155
	v_mov_b32_e32 v183, v156
	v_mov_b32_e32 v155, v157
	v_pk_add_f32 v[154:155], v[182:183], v[154:155]
	v_rsq_f32_e32 v0, v0
	s_nop 0
	v_add_f32_e32 v154, v154, v155
	ds_bpermute_b32 v155, v175, v154
	v_pk_mul_f32 v[128:129], v[128:129], v[0:1] op_sel_hi:[1,0]
	v_pk_mul_f32 v[126:127], v[126:127], v[0:1] op_sel_hi:[1,0]
	v_pk_mul_f32 v[96:97], v[96:97], v[0:1] op_sel_hi:[1,0]
	v_pk_mul_f32 v[94:95], v[94:95], v[0:1] op_sel_hi:[1,0]
	s_waitcnt lgkmcnt(0)
	v_add_f32_e32 v154, v154, v155
	ds_bpermute_b32 v155, v180, v154
	v_pk_mul_f32 v[64:65], v[64:65], v[0:1] op_sel_hi:[1,0]
	v_pk_mul_f32 v[62:63], v[62:63], v[0:1] op_sel_hi:[1,0]
	v_pk_mul_f32 v[32:33], v[32:33], v[0:1] op_sel_hi:[1,0]
	v_pk_mul_f32 v[30:31], v[30:31], v[0:1] op_sel_hi:[1,0]
	s_waitcnt lgkmcnt(0)
	v_add_f32_e32 v154, v154, v155
	v_fmamk_f32 v154, v154, 0x3a800000, v230
	v_mov_b32_e32 v156, v151
	v_mov_b32_e32 v157, v152
	v_mov_b32_e32 v151, v153
	v_pk_add_f32 v[150:151], v[156:157], v[150:151]
	v_rsq_f32_e32 v154, v154
	s_nop 0
	v_add_f32_e32 v150, v150, v151
	ds_bpermute_b32 v151, v175, v150
	s_waitcnt lgkmcnt(0)
	v_add_f32_e32 v150, v150, v151
	ds_bpermute_b32 v151, v180, v150
	s_waitcnt lgkmcnt(0)
	v_add_f32_e32 v150, v150, v151
	v_fmamk_f32 v150, v150, 0x3a800000, v230
	v_mov_b32_e32 v152, v147
	v_mov_b32_e32 v153, v148
	v_mov_b32_e32 v147, v149
	v_pk_add_f32 v[146:147], v[152:153], v[146:147]
	v_rsq_f32_e32 v150, v150
	s_nop 0
	v_add_f32_e32 v146, v146, v147
	ds_bpermute_b32 v147, v175, v146
	v_pk_mul_f32 v[124:125], v[124:125], v[154:155] op_sel_hi:[1,0]
	v_pk_mul_f32 v[122:123], v[122:123], v[154:155] op_sel_hi:[1,0]
	v_pk_mul_f32 v[92:93], v[92:93], v[154:155] op_sel_hi:[1,0]
	v_pk_mul_f32 v[90:91], v[90:91], v[154:155] op_sel_hi:[1,0]
	s_waitcnt lgkmcnt(0)
	v_add_f32_e32 v146, v146, v147
	ds_bpermute_b32 v147, v180, v146
	v_pk_mul_f32 v[60:61], v[60:61], v[154:155] op_sel_hi:[1,0]
	v_pk_mul_f32 v[58:59], v[58:59], v[154:155] op_sel_hi:[1,0]
	v_pk_mul_f32 v[28:29], v[28:29], v[154:155] op_sel_hi:[1,0]
	v_pk_mul_f32 v[26:27], v[26:27], v[154:155] op_sel_hi:[1,0]
	s_waitcnt lgkmcnt(0)
	v_add_f32_e32 v146, v146, v147
	v_fmamk_f32 v146, v146, 0x3a800000, v230
	v_mov_b32_e32 v148, v143
	v_mov_b32_e32 v149, v144
	v_mov_b32_e32 v143, v145
	v_pk_add_f32 v[142:143], v[148:149], v[142:143]
	v_rsq_f32_e32 v146, v146
	s_nop 0
	v_add_f32_e32 v142, v142, v143
	ds_bpermute_b32 v143, v175, v142
	v_pk_mul_f32 v[120:121], v[120:121], v[150:151] op_sel_hi:[1,0]
	v_pk_mul_f32 v[118:119], v[118:119], v[150:151] op_sel_hi:[1,0]
	v_pk_mul_f32 v[88:89], v[88:89], v[150:151] op_sel_hi:[1,0]
	v_pk_mul_f32 v[86:87], v[86:87], v[150:151] op_sel_hi:[1,0]
	s_waitcnt lgkmcnt(0)
; __device__ __forceinline__ void load_row_scales(const float* ssp, int row0, int fq, float (&rs)[2][4]) {
;     f32x4 part[2][4];
;     const float* sp = ssp + (size_t)row0 * 16 + 4 * fq;
; #pragma unroll
;     for (int ai = 0; ai < 2; ++ai)
; #pragma unroll
;         for (int m = 0; m < 4; ++m) part[ai][m] = *(const f32x4*)(sp + (size_t)(ai * HALF + m * 16) * 16);
; #pragma unroll
;     for (int ai = 0; ai < 2; ++ai)
; #pragma unroll
;         for (int m = 0; m < 4; ++m) { float t = (part[ai][m][0] + part[ai][m][1]) + (part[ai][m][2] + part[ai][m][3]);
;             t += __shfl_xor(t, 16); t += __shfl_xor(t, 32);
;             rs[ai][m] = 1.0f / sqrtf(t * (1.0f / 1024.0f) + 1e-6f); }
; }
;     __device__ __forceinline__ void operator()(f32x4 (&acc)[2][2][4][2], const Unit& u, int wr, int wc, int fr, int fq) const {
;     ...
;             if (ssp) { float rs[2][4]; load_row_scales(ssp, row0, fq, rs);
; #pragma unroll
;                 for (int ai = 0; ai < 2; ++ai)
; #pragma unroll
;                     for (int m = 0; m < 4; ++m)
; #pragma unroll
;                         for (int bj = 0; bj < 2; ++bj)
; #pragma unroll
;                             for (int n = 0; n < 2; ++n) acc[ai][bj][m][n] = acc[ai][bj][m][n] * rs[ai][m];
;             }
	v_add_f32_e32 v142, v142, v143
	ds_bpermute_b32 v143, v180, v142
	v_pk_mul_f32 v[56:57], v[56:57], v[150:151] op_sel_hi:[1,0]
	v_pk_mul_f32 v[54:55], v[54:55], v[150:151] op_sel_hi:[1,0]
	v_pk_mul_f32 v[24:25], v[24:25], v[150:151] op_sel_hi:[1,0]
	v_pk_mul_f32 v[22:23], v[22:23], v[150:151] op_sel_hi:[1,0]
	s_waitcnt lgkmcnt(0)
	v_add_f32_e32 v142, v142, v143
	v_fmamk_f32 v142, v142, 0x3a800000, v230
	v_mov_b32_e32 v144, v139
	v_mov_b32_e32 v145, v140
	v_mov_b32_e32 v139, v141
	v_pk_add_f32 v[138:139], v[144:145], v[138:139]
	v_rsq_f32_e32 v142, v142
	s_nop 0
	v_add_f32_e32 v138, v138, v139
	ds_bpermute_b32 v139, v175, v138
	v_pk_mul_f32 v[116:117], v[116:117], v[146:147] op_sel_hi:[1,0]
	v_pk_mul_f32 v[114:115], v[114:115], v[146:147] op_sel_hi:[1,0]
	v_pk_mul_f32 v[84:85], v[84:85], v[146:147] op_sel_hi:[1,0]
	v_pk_mul_f32 v[82:83], v[82:83], v[146:147] op_sel_hi:[1,0]
	s_waitcnt lgkmcnt(0)
	v_add_f32_e32 v138, v138, v139
	ds_bpermute_b32 v139, v180, v138
	v_pk_mul_f32 v[52:53], v[52:53], v[146:147] op_sel_hi:[1,0]
	v_pk_mul_f32 v[50:51], v[50:51], v[146:147] op_sel_hi:[1,0]
	v_pk_mul_f32 v[20:21], v[20:21], v[146:147] op_sel_hi:[1,0]
	v_pk_mul_f32 v[18:19], v[18:19], v[146:147] op_sel_hi:[1,0]
	s_waitcnt lgkmcnt(0)
	v_add_f32_e32 v138, v138, v139
	v_fmamk_f32 v138, v138, 0x3a800000, v230
	v_mov_b32_e32 v140, v135
	v_mov_b32_e32 v141, v136
	v_mov_b32_e32 v135, v137
	v_pk_add_f32 v[134:135], v[140:141], v[134:135]
	v_rsq_f32_e32 v138, v138
	s_nop 0
	v_add_f32_e32 v134, v134, v135
	ds_bpermute_b32 v135, v175, v134
	v_pk_mul_f32 v[112:113], v[112:113], v[142:143] op_sel_hi:[1,0]
	v_pk_mul_f32 v[110:111], v[110:111], v[142:143] op_sel_hi:[1,0]
	v_pk_mul_f32 v[80:81], v[80:81], v[142:143] op_sel_hi:[1,0]
	v_pk_mul_f32 v[78:79], v[78:79], v[142:143] op_sel_hi:[1,0]
	s_waitcnt lgkmcnt(0)
	v_add_f32_e32 v134, v134, v135
	ds_bpermute_b32 v135, v180, v134
	v_pk_mul_f32 v[48:49], v[48:49], v[142:143] op_sel_hi:[1,0]
	v_pk_mul_f32 v[46:47], v[46:47], v[142:143] op_sel_hi:[1,0]
	v_pk_mul_f32 v[16:17], v[16:17], v[142:143] op_sel_hi:[1,0]
	v_pk_mul_f32 v[14:15], v[14:15], v[142:143] op_sel_hi:[1,0]
	s_waitcnt lgkmcnt(0)
	v_add_f32_e32 v134, v134, v135
	v_fmamk_f32 v134, v134, 0x3a800000, v230
	v_mov_b32_e32 v136, v131
	v_mov_b32_e32 v137, v132
	v_mov_b32_e32 v131, v133
	v_pk_add_f32 v[130:131], v[136:137], v[130:131]
	v_rsq_f32_e32 v134, v134
	s_nop 0
	v_add_f32_e32 v130, v130, v131
	ds_bpermute_b32 v131, v175, v130
	v_pk_mul_f32 v[108:109], v[108:109], v[138:139] op_sel_hi:[1,0]
	v_pk_mul_f32 v[106:107], v[106:107], v[138:139] op_sel_hi:[1,0]
	v_pk_mul_f32 v[76:77], v[76:77], v[138:139] op_sel_hi:[1,0]
	v_pk_mul_f32 v[74:75], v[74:75], v[138:139] op_sel_hi:[1,0]
	s_waitcnt lgkmcnt(0)
	v_add_f32_e32 v130, v130, v131
	ds_bpermute_b32 v131, v180, v130
	v_pk_mul_f32 v[44:45], v[44:45], v[138:139] op_sel_hi:[1,0]
	v_pk_mul_f32 v[42:43], v[42:43], v[138:139] op_sel_hi:[1,0]
	v_pk_mul_f32 v[12:13], v[12:13], v[138:139] op_sel_hi:[1,0]
	v_pk_mul_f32 v[10:11], v[10:11], v[138:139] op_sel_hi:[1,0]
	s_waitcnt lgkmcnt(0)
	v_add_f32_e32 v130, v130, v131
	v_fmamk_f32 v130, v130, 0x3a800000, v230
	v_rsq_f32_e32 v130, v130
	s_nop 0
	v_pk_mul_f32 v[104:105], v[104:105], v[134:135] op_sel_hi:[1,0]
	v_pk_mul_f32 v[102:103], v[102:103], v[134:135] op_sel_hi:[1,0]
	v_pk_mul_f32 v[72:73], v[72:73], v[134:135] op_sel_hi:[1,0]
	v_pk_mul_f32 v[70:71], v[70:71], v[134:135] op_sel_hi:[1,0]
	v_pk_mul_f32 v[40:41], v[40:41], v[134:135] op_sel_hi:[1,0]
	v_pk_mul_f32 v[38:39], v[38:39], v[134:135] op_sel_hi:[1,0]
	v_pk_mul_f32 v[8:9], v[8:9], v[134:135] op_sel_hi:[1,0]
	v_pk_mul_f32 v[6:7], v[6:7], v[134:135] op_sel_hi:[1,0]
	v_pk_mul_f32 v[100:101], v[100:101], v[130:131] op_sel_hi:[1,0]
	v_pk_mul_f32 v[98:99], v[98:99], v[130:131] op_sel_hi:[1,0]
	v_pk_mul_f32 v[68:69], v[68:69], v[130:131] op_sel_hi:[1,0]
	v_pk_mul_f32 v[66:67], v[66:67], v[130:131] op_sel_hi:[1,0]
	v_pk_mul_f32 v[36:37], v[36:37], v[130:131] op_sel_hi:[1,0]
	v_pk_mul_f32 v[34:35], v[34:35], v[130:131] op_sel_hi:[1,0]
	v_pk_mul_f32 v[4:5], v[4:5], v[130:131] op_sel_hi:[1,0]
	v_pk_mul_f32 v[2:3], v[2:3], v[130:131] op_sel_hi:[1,0]

; __device__ __forceinline__ float swap32_add(float v) { auto rr = __builtin_amdgcn_permlane32_swap(__float_as_uint(v), __float_as_uint(v), false, false); return __uint_as_float(rr[0]) + __uint_as_float(rr[1]); }
; template <int D, int DV, bool TAB, bool BITS, int KT> ...
;     ...
;     const float lt = swap32_add(l_run);
;     if (hi == 0) wsf[r32] = 1.0f / fmaxf(lt, 1e-30f);
;     __builtin_amdgcn_fence(__ATOMIC_RELEASE, "wavefront"); __builtin_amdgcn_wave_barrier();
; #pragma unroll
;     for (int j = 0; j < 4; ++j) { const f32x4 a4 = *(const f32x4*)(wsf + 8 * j + 4 * hi);
; #pragma unroll
;         for (int dt = 0; dt < DV / 32; ++dt) { o[dt][4 * j + 0] *= a4[0]; o[dt][4 * j + 1] *= a4[1]; o[dt][4 * j + 2] *= a4[2]; o[dt][4 * j + 3] *= a4[3]; } }
;     __builtin_amdgcn_fence(__ATOMIC_RELEASE, "wavefront"); __builtin_amdgcn_wave_barrier();
; __device__ __forceinline__ void unitA(unsigned char* lds, const MixCtx& c, int b, int h, int qb, bool ltab) {
;     ...
;     { const float* st = c.stash + (size_t)blockIdx.x * 512 + tid_o; asm volatile("" : "+v"(st) :: "memory");
; #pragma unroll
;       for (int dt = 0; dt < 4; ++dt)
; #pragma unroll
;           for (int r = 0; r < 16; ++r) oa[dt][r] = st[(size_t)(dt * 16 + r) * c.nthr]; }
.LBB0_336:
	s_waitcnt lgkmcnt(0)
	v_mul_f32_e32 v92, v48, v80
	v_mul_f32_e32 v48, v44, v76
	v_mul_f32_e32 v44, v40, v72
	v_mul_f32_e32 v40, v36, v68
	v_mul_f32_e32 v36, v2, v66
	v_mov_b32_e32 v2, v228
	v_readlane_b32 s4, v254, 30
	v_mul_f32_e32 v96, v32, v80
	v_mul_f32_e32 v32, v30, v78
	v_mul_f32_e32 v30, v60, v76
	v_mul_f32_e32 v60, v55, v71
	v_mul_f32_e32 v55, v3, v67
	v_readlane_b32 s5, v254, 31
	v_ashrrev_i32_e32 v3, 31, v2
	v_mul_f32_e32 v91, v65, v81
	v_mul_f32_e32 v65, v28, v76
	v_mul_f32_e32 v28, v41, v73
	v_mul_f32_e32 v41, v37, v69
	v_mul_f32_e32 v37, v35, v67
	v_mul_f32_e32 v0, v34, v66
	v_lshl_add_u64 v[34:35], v[2:3], 2, s[4:5]
	v_mul_f32_e32 v94, v64, v80
	v_mul_f32_e32 v64, v59, v75
	v_mul_f32_e32 v59, v54, v70
	flat_load_dword v54, v[34:35]
	v_lshl_add_u64 v[34:35], s[66:67], 2, v[34:35]
	flat_load_dword v3, v[34:35]
	v_lshl_add_u64 v[34:35], v[34:35], 0, s[68:69]
	v_mul_f32_e32 v93, v33, v81
	v_mul_f32_e32 v33, v31, v79
	v_mul_f32_e32 v31, v61, v77
	v_mul_f32_e32 v61, v56, v72
	flat_load_dword v56, v[34:35]
	v_lshl_add_u64 v[34:35], v[34:35], 0, s[68:69]
	v_mul_f32_e32 v90, v49, v81
	s_waitcnt vmcnt(0)
	v_mul_f32_e32 v98, v46, v78
	v_mul_f32_e32 v49, v45, v77
	v_mul_f32_e32 v46, v42, v74
	v_mul_f32_e32 v42, v38, v70
	v_mul_f32_e32 v45, v25, v73
	v_mul_f32_e32 v25, v24, v72
	v_mul_f32_e32 v24, v23, v71
	v_mul_f32_e32 v23, v22, v70
	v_mul_f32_e32 v6, v6, v70
	flat_load_dword v70, v[34:35]
	v_lshl_add_u64 v[34:35], v[34:35], 0, s[68:69]
	v_mul_f32_e32 v97, v63, v79
	v_mul_f32_e32 v63, v58, v74
	flat_load_dword v58, v[34:35]
	v_lshl_add_u64 v[34:35], v[34:35], 0, s[68:69]
	v_mul_f32_e32 v22, v53, v69
	v_mul_f32_e32 v53, v21, v69
	v_mul_f32_e32 v5, v5, v69
	flat_load_dword v69, v[34:35]
	v_lshl_add_u64 v[34:35], v[34:35], 0, s[68:69]
	v_mul_f32_e32 v99, v62, v78
	v_mul_f32_e32 v14, v14, v78
	v_mul_f32_e32 v78, v29, v77
	v_mul_f32_e32 v29, v27, v75
	v_mul_f32_e32 v27, v57, v73
	v_mul_f32_e32 v57, v52, v68
	v_mul_f32_e32 v21, v20, v68
	v_mul_f32_e32 v4, v4, v68
	flat_load_dword v68, v[34:35]
	v_lshl_add_u64 v[34:35], v[34:35], 0, s[68:69]
	v_mul_f32_e32 v95, v47, v79
	v_mul_f32_e32 v47, v43, v75
	v_mul_f32_e32 v43, v39, v71
	v_mul_f32_e32 v39, v51, v67
	v_mul_f32_e32 v20, v19, v67
	flat_load_dword v67, v[34:35]
	v_lshl_add_u64 v[34:35], v[34:35], 0, s[68:69]
	flat_load_dword v62, v[34:35]
	v_lshl_add_u64 v[34:35], v[34:35], 0, s[68:69]
	v_mul_f32_e32 v38, v50, v66
	v_mul_f32_e32 v19, v18, v66
	flat_load_dword v66, v[34:35]
	v_lshl_add_u64 v[34:35], v[34:35], 0, s[68:69]
	flat_load_dword v52, v[34:35]
	v_lshl_add_u64 v[34:35], v[34:35], 0, s[68:69]
	flat_load_dword v51, v[34:35]
	v_lshl_add_u64 v[34:35], v[34:35], 0, s[68:69]
	v_mul_f32_e32 v9, v9, v73
	v_mul_f32_e32 v8, v8, v72
	v_lshl_add_u64 v[72:73], v[34:35], 0, s[68:69]
	flat_load_dword v50, v[34:35]
	v_mul_f32_e32 v7, v7, v71
	flat_load_dword v35, v[72:73]
	v_lshl_add_u64 v[72:73], v[72:73], 0, s[68:69]
	flat_load_dword v34, v[72:73]
	v_lshl_add_u64 v[72:73], v[72:73], 0, s[68:69]
	flat_load_dword v18, v[72:73]
	v_lshl_add_u64 v[72:73], v[72:73], 0, s[68:69]
	flat_load_dword v71, v[72:73]
	v_lshl_add_u64 v[72:73], v[72:73], 0, s[68:69]
	v_mul_f32_e32 v26, v26, v74
	v_mul_f32_e32 v10, v10, v74
	flat_load_dword v74, v[72:73]
	v_lshl_add_u64 v[72:73], v[72:73], 0, s[68:69]
	v_mul_f32_e32 v11, v11, v75
	flat_load_dword v75, v[72:73]
	v_lshl_add_u64 v[72:73], v[72:73], 0, s[68:69]
	v_mul_f32_e32 v12, v12, v76
	flat_load_dword v76, v[72:73]
	v_lshl_add_u64 v[72:73], v[72:73], 0, s[68:69]
	v_mul_f32_e32 v13, v13, v77
	flat_load_dword v77, v[72:73]
	v_lshl_add_u64 v[72:73], v[72:73], 0, s[68:69]
	v_mul_f32_e32 v15, v15, v79
	flat_load_dword v79, v[72:73]
	v_lshl_add_u64 v[72:73], v[72:73], 0, s[68:69]
	v_mul_f32_e32 v16, v16, v80
	flat_load_dword v80, v[72:73]
	v_lshl_add_u64 v[72:73], v[72:73], 0, s[68:69]
	v_mul_f32_e32 v17, v17, v81
	flat_load_dword v81, v[72:73]
	v_lshl_add_u64 v[72:73], v[72:73], 0, s[68:69]
	flat_load_dword v83, v[72:73]
	v_lshl_add_u64 v[72:73], v[72:73], 0, s[68:69]
	flat_load_dword v85, v[72:73]
	v_lshl_add_u64 v[72:73], v[72:73], 0, s[68:69]
	flat_load_dword v87, v[72:73]
	v_lshl_add_u64 v[72:73], v[72:73], 0, s[68:69]
	flat_load_dword v101, v[72:73]
	v_lshl_add_u64 v[72:73], v[72:73], 0, s[68:69]
	flat_load_dword v102, v[72:73]
	v_lshl_add_u64 v[72:73], v[72:73], 0, s[68:69]
	flat_load_dword v103, v[72:73]
	v_lshl_add_u64 v[72:73], v[72:73], 0, s[68:69]
	flat_load_dword v104, v[72:73]
	v_lshl_add_u64 v[72:73], v[72:73], 0, s[68:69]
	flat_load_dword v105, v[72:73]
	v_lshl_add_u64 v[72:73], v[72:73], 0, s[68:69]
	flat_load_dword v82, v[72:73]
	v_lshl_add_u64 v[72:73], v[72:73], 0, s[68:69]
	flat_load_dword v84, v[72:73]
	v_lshl_add_u64 v[72:73], v[72:73], 0, s[68:69]
	flat_load_dword v86, v[72:73]
	v_lshl_add_u64 v[72:73], v[72:73], 0, s[68:69]
	flat_load_dword v106, v[72:73]
	v_lshl_add_u64 v[72:73], v[72:73], 0, s[68:69]
	flat_load_dword v107, v[72:73]
	v_lshl_add_u64 v[72:73], v[72:73], 0, s[68:69]
	flat_load_dword v108, v[72:73]
	v_lshl_add_u64 v[72:73], v[72:73], 0, s[68:69]
	flat_load_dword v109, v[72:73]
	v_lshl_add_u64 v[72:73], v[72:73], 0, s[68:69]
	flat_load_dword v110, v[72:73]
	v_lshl_add_u64 v[72:73], v[72:73], 0, s[68:69]
	flat_load_dword v111, v[72:73]
	v_lshl_add_u64 v[72:73], v[72:73], 0, s[68:69]
	flat_load_dword v112, v[72:73]
	v_lshl_add_u64 v[72:73], v[72:73], 0, s[68:69]
	flat_load_dword v113, v[72:73]
	v_lshl_add_u64 v[72:73], v[72:73], 0, s[68:69]
	flat_load_dword v114, v[72:73]
	v_lshl_add_u64 v[72:73], v[72:73], 0, s[68:69]
	flat_load_dword v115, v[72:73]
	v_lshl_add_u64 v[72:73], v[72:73], 0, s[68:69]
	flat_load_dword v116, v[72:73]
; __device__ __forceinline__ void unitA(unsigned char* lds, const MixCtx& c, int b, int h, int qb, bool ltab) {
;     ...
;           for (int r = 0; r < 16; ++r) oa[dt][r] = st[(size_t)(dt * 16 + r) * c.nthr]; }
;     float ss[16];
; #pragma unroll
;     for (int r = 0; r < 16; ++r) { float s = 0.f;
; #pragma unroll
;         for (int dt = 0; dt < 4; ++dt) { const float v = oa[dt][r] - lam * ob[dt][r]; oa[dt][r] = v; s += v * v; }
;         ss[r] = s; }
; #pragma unroll
;     for (int r = 0; r < 16; ++r) {
; #pragma unroll
;         for (int o = 1; o < 32; o <<= 1) ss[r] += __shfl_xor(ss[r], o);
;         ss[r] = (1.0f - lam_init) / sqrtf(ss[r] * (1.f / 128.f) + EPSN); }
	v_lshl_add_u64 v[72:73], v[72:73], 0, s[68:69]
	flat_load_dword v117, v[72:73]
	v_lshl_add_u64 v[72:73], v[72:73], 0, s[68:69]
	flat_load_dword v118, v[72:73]
	v_lshl_add_u64 v[72:73], v[72:73], 0, s[68:69]
	flat_load_dword v100, v[72:73]
	v_lshl_add_u64 v[72:73], v[72:73], 0, s[68:69]
	flat_load_dword v119, v[72:73]
	v_lshl_add_u64 v[72:73], v[72:73], 0, s[68:69]
	flat_load_dword v120, v[72:73]
	v_lshl_add_u64 v[72:73], v[72:73], 0, s[68:69]
	flat_load_dword v121, v[72:73]
	v_lshl_add_u64 v[72:73], v[72:73], 0, s[68:69]
	flat_load_dword v122, v[72:73]
	v_lshl_add_u64 v[72:73], v[72:73], 0, s[68:69]
	flat_load_dword v123, v[72:73]
	v_lshl_add_u64 v[72:73], v[72:73], 0, s[68:69]
	flat_load_dword v124, v[72:73]
	v_lshl_add_u64 v[72:73], v[72:73], 0, s[68:69]
	flat_load_dword v125, v[72:73]
	v_lshl_add_u64 v[72:73], v[72:73], 0, s[68:69]
	flat_load_dword v126, v[72:73]
	v_lshl_add_u64 v[72:73], v[72:73], 0, s[68:69]
	flat_load_dword v127, v[72:73]
	v_lshl_add_u64 v[72:73], v[72:73], 0, s[68:69]
	flat_load_dword v128, v[72:73]
	v_lshl_add_u64 v[72:73], v[72:73], 0, s[68:69]
	flat_load_dword v129, v[72:73]
	v_lshl_add_u64 v[72:73], v[72:73], 0, s[68:69]
	flat_load_dword v130, v[72:73]
	v_lshl_add_u64 v[72:73], v[72:73], 0, s[68:69]
	flat_load_dword v131, v[72:73]
	v_lshl_add_u64 v[72:73], v[72:73], 0, s[68:69]
	flat_load_dword v132, v[72:73]
	v_lshl_add_u64 v[72:73], v[72:73], 0, s[68:69]
	flat_load_dword v73, v[72:73]
	s_waitcnt lgkmcnt(0)
	v_fma_f32 v54, -v36, v89, v54
	s_waitcnt vmcnt(0)
	v_fma_f32 v36, -v19, v89, v71
	v_mul_f32_e32 v133, v36, v36
	v_fma_f32 v58, -v6, v89, v58
	v_fmac_f32_e32 v133, v54, v54
	v_fma_f32 v62, -v10, v89, v62
	s_lshl_b32 s0, s0, 7
	s_ashr_i32 s1, s0, 31
	v_readlane_b32 s4, v253, 2
	s_lshl_b64 s[0:1], s[0:1], 2
	v_readlane_b32 s6, v253, 4
	v_readlane_b32 s5, v253, 3
	v_readlane_b32 s7, v253, 5
	s_add_u32 s4, s6, s0
	v_fma_f32 v55, -v55, v89, v3
	v_fma_f32 v56, -v4, v89, v56
	s_addc_u32 s5, s7, s1
	v_fma_f32 v19, -v38, v89, v82
	v_fma_f32 v38, -v20, v89, v74
	v_fma_f32 v20, -v39, v89, v84
	v_fma_f32 v39, -v21, v89, v75
	v_fma_f32 v21, -v57, v89, v86
	v_fma_f32 v57, -v5, v89, v70
	v_fmac_f32_e32 v133, v19, v19
	v_fma_f32 v22, -v22, v89, v106
	v_and_b32_e32 v2, 31, v2
	v_readlane_b32 s16, v253, 14
	v_readlane_b32 s17, v253, 15
	v_readlane_b32 s18, v253, 16
	v_readlane_b32 s19, v253, 17
	s_mov_b64 s[16:17], s[24:25]
	v_fma_f32 v27, -v27, v89, v110
	s_mov_b64 s[18:19], s[50:51]
	v_readlane_b32 s8, v253, 6
	v_readlane_b32 s9, v253, 7
	v_readlane_b32 s10, v253, 8
	v_readlane_b32 s11, v253, 9
	v_fma_f32 v30, -v30, v89, v113
	v_readlane_b32 s12, v253, 10
	v_fma_f32 v31, -v31, v89, v114
	v_readlane_b32 s13, v253, 11
	v_readlane_b32 s14, v253, 12
	v_readlane_b32 s15, v253, 13
	v_fma_f32 v0, -v0, v89, v100
	v_fmac_f32_e32 v133, v0, v0
	v_fma_f32 v3, -v37, v89, v119
	v_mul_f32_e32 v100, v38, v38
	v_fma_f32 v4, -v40, v89, v120
	v_fma_f32 v40, -v53, v89, v76
	v_fma_f32 v5, -v41, v89, v121
	v_fma_f32 v41, -v23, v89, v77
	v_fma_f32 v23, -v59, v89, v107
	v_fma_f32 v59, -v7, v89, v69
	v_fma_f32 v69, -v17, v89, v18
	v_and_b32_e32 v18, 64, v229
	v_fma_f32 v6, -v42, v89, v122
	v_fma_f32 v42, -v24, v89, v79
	v_fma_f32 v24, -v60, v89, v108
	v_fma_f32 v60, -v8, v89, v68
	v_fma_f32 v8, -v44, v89, v124
	v_fma_f32 v44, -v45, v89, v81
	v_fma_f32 v45, -v26, v89, v83
	v_add_u32_e32 v18, 64, v18
	v_xor_b32_e32 v26, 1, v229
	v_cmp_lt_i32_e32 vcc, v26, v18
	v_xor_b32_e32 v77, 2, v229
	v_fma_f32 v10, -v46, v89, v126
	v_cndmask_b32_e32 v26, v229, v26, vcc
	v_lshlrev_b32_e32 v75, 2, v26
	ds_bpermute_b32 v26, v75, v133
	v_cmp_lt_i32_e32 vcc, v77, v18
	v_fma_f32 v46, -v29, v89, v85
	v_fma_f32 v29, -v64, v89, v112
	v_cndmask_b32_e32 v77, v229, v77, vcc
	s_waitcnt lgkmcnt(0)
	v_add_f32_e32 v26, v133, v26
	v_lshlrev_b32_e32 v77, 2, v77
	v_fma_f32 v64, -v12, v89, v52
	v_fma_f32 v12, -v48, v89, v128
	v_fma_f32 v48, -v78, v89, v101
	ds_bpermute_b32 v78, v77, v26
	v_fma_f32 v7, -v43, v89, v123
	v_fma_f32 v43, -v25, v89, v80
	v_fma_f32 v17, -v90, v89, v73
	v_sub_f32_e32 v73, 1.0, v88
	s_waitcnt lgkmcnt(0)
	v_add_f32_e32 v26, v26, v78
	v_xor_b32_e32 v78, 4, v229
	v_cmp_lt_i32_e32 vcc, v78, v18
	v_fma_f32 v25, -v61, v89, v109
	v_fma_f32 v61, -v9, v89, v67
	v_cndmask_b32_e32 v78, v229, v78, vcc
	v_lshlrev_b32_e32 v78, 2, v78
	ds_bpermute_b32 v79, v78, v26
	v_fma_f32 v9, -v28, v89, v125
	v_fma_f32 v28, -v63, v89, v111
	v_fma_f32 v63, -v11, v89, v66
	v_fma_f32 v11, -v47, v89, v127
	s_waitcnt lgkmcnt(0)
	v_add_f32_e32 v26, v26, v79
	v_xor_b32_e32 v79, 8, v229
	v_cmp_lt_i32_e32 vcc, v79, v18
	v_fma_f32 v47, -v65, v89, v87
	v_fma_f32 v65, -v13, v89, v51
	v_cndmask_b32_e32 v79, v229, v79, vcc
	v_lshlrev_b32_e32 v79, 2, v79
	ds_bpermute_b32 v80, v79, v26
	v_fma_f32 v13, -v49, v89, v129
	v_fma_f32 v66, -v14, v89, v50
	v_fma_f32 v49, -v32, v89, v102
	v_fma_f32 v32, -v99, v89, v115
	s_waitcnt lgkmcnt(0)
	v_add_f32_e32 v26, v26, v80
	v_xor_b32_e32 v80, 16, v229
	v_cmp_lt_i32_e32 vcc, v80, v18
	v_fma_f32 v14, -v98, v89, v130
	v_fma_f32 v67, -v15, v89, v35
	v_cndmask_b32_e32 v18, v229, v80, vcc
	v_lshlrev_b32_e32 v80, 2, v18
	ds_bpermute_b32 v18, v80, v26
	v_fma_f32 v50, -v33, v89, v103
	v_fma_f32 v33, -v97, v89, v116
	v_fma_f32 v15, -v95, v89, v131
	v_fma_f32 v68, -v16, v89, v34
	s_waitcnt lgkmcnt(0)
	v_add_f32_e32 v18, v26, v18
	v_fmamk_f32 v18, v18, 0x3c000000, v230
	v_fma_f32 v51, -v96, v89, v104
	v_fma_f32 v34, -v94, v89, v117
	v_fma_f32 v16, -v92, v89, v132
	v_fma_f32 v52, -v93, v89, v105
	v_fma_f32 v35, -v91, v89, v118
	v_fmac_f32_e32 v100, v55, v55
	v_fmac_f32_e32 v100, v20, v20
	v_fmac_f32_e32 v100, v3, v3
	v_mul_f32_e32 v37, v39, v39
	v_fmac_f32_e32 v37, v56, v56
	v_fmac_f32_e32 v37, v21, v21
	v_fmac_f32_e32 v37, v4, v4
	v_mul_f32_e32 v53, v40, v40
	v_rsq_f32_e32 v18, v18
	s_nop 0
	v_mul_f32_e32 v18, v73, v18
	ds_bpermute_b32 v26, v75, v100
	v_fmac_f32_e32 v53, v57, v57
	v_fmac_f32_e32 v53, v22, v22
	v_fmac_f32_e32 v53, v5, v5
	v_mul_f32_e32 v70, v41, v41
	s_waitcnt lgkmcnt(0)
; __device__ __forceinline__ void unitA(unsigned char* lds, const MixCtx& c, int b, int h, int qb, bool ltab) {
;     ...
;     for (int r = 0; r < 16; ++r) {
; #pragma unroll
;         for (int o = 1; o < 32; o <<= 1) ss[r] += __shfl_xor(ss[r], o);
;         ss[r] = (1.0f - lam_init) / sqrtf(ss[r] * (1.f / 128.f) + EPSN); }
	v_add_f32_e32 v26, v100, v26
	ds_bpermute_b32 v88, v77, v26
	v_fmac_f32_e32 v70, v58, v58
	v_fmac_f32_e32 v70, v23, v23
	v_fmac_f32_e32 v70, v6, v6
	v_mul_f32_e32 v71, v42, v42
	s_waitcnt lgkmcnt(0)
	v_add_f32_e32 v26, v26, v88
	ds_bpermute_b32 v88, v78, v26
	v_fmac_f32_e32 v71, v59, v59
	v_fmac_f32_e32 v71, v24, v24
	v_fmac_f32_e32 v71, v7, v7
	v_mul_f32_e32 v76, v43, v43
	s_waitcnt lgkmcnt(0)
	v_add_f32_e32 v26, v26, v88
	ds_bpermute_b32 v88, v79, v26
	v_fmac_f32_e32 v76, v60, v60
	v_fmac_f32_e32 v76, v25, v25
	v_fmac_f32_e32 v76, v8, v8
	v_mul_f32_e32 v82, v44, v44
	s_waitcnt lgkmcnt(0)
	v_add_f32_e32 v26, v26, v88
	ds_bpermute_b32 v88, v80, v26
	v_fmac_f32_e32 v82, v61, v61
	v_fmac_f32_e32 v82, v27, v27
	v_fmac_f32_e32 v82, v9, v9
	v_mul_f32_e32 v84, v45, v45
	s_waitcnt lgkmcnt(0)
	v_add_f32_e32 v26, v26, v88
	v_fmamk_f32 v26, v26, 0x3c000000, v230
	v_fmac_f32_e32 v84, v62, v62
	v_fmac_f32_e32 v84, v28, v28
	v_fmac_f32_e32 v84, v10, v10
	v_mul_f32_e32 v86, v46, v46
	v_fmac_f32_e32 v86, v63, v63
	v_fmac_f32_e32 v86, v29, v29
	v_fmac_f32_e32 v86, v11, v11
	v_mul_f32_e32 v87, v47, v47
	v_fmac_f32_e32 v87, v64, v64
	v_fmac_f32_e32 v87, v30, v30
	v_fmac_f32_e32 v87, v12, v12
	v_mul_f32_e32 v85, v48, v48
	v_rsq_f32_e32 v26, v26
	s_nop 0
	v_mul_f32_e32 v26, v73, v26
	ds_bpermute_b32 v88, v75, v37
	v_fmac_f32_e32 v85, v65, v65
	v_fmac_f32_e32 v85, v31, v31
	v_fmac_f32_e32 v85, v13, v13
	v_mul_f32_e32 v83, v49, v49
	s_waitcnt lgkmcnt(0)
	v_add_f32_e32 v37, v37, v88
	ds_bpermute_b32 v88, v77, v37
	v_fmac_f32_e32 v83, v66, v66
	v_fmac_f32_e32 v83, v32, v32
	v_fmac_f32_e32 v83, v14, v14
	v_mul_f32_e32 v81, v50, v50
	s_waitcnt lgkmcnt(0)
	v_add_f32_e32 v37, v37, v88
	ds_bpermute_b32 v88, v78, v37
	v_fmac_f32_e32 v81, v67, v67
	v_fmac_f32_e32 v81, v33, v33
	v_fmac_f32_e32 v81, v15, v15
	v_mul_f32_e32 v74, v51, v51
	s_waitcnt lgkmcnt(0)
	v_add_f32_e32 v37, v37, v88
	ds_bpermute_b32 v88, v79, v37
	v_fmac_f32_e32 v74, v68, v68
	v_fmac_f32_e32 v74, v34, v34
	v_fmac_f32_e32 v74, v16, v16
	v_mul_f32_e32 v72, v52, v52
	s_waitcnt lgkmcnt(0)
	v_add_f32_e32 v37, v37, v88
	ds_bpermute_b32 v88, v80, v37
	v_fmac_f32_e32 v72, v69, v69
	v_fmac_f32_e32 v72, v35, v35
	v_fmac_f32_e32 v72, v17, v17
	v_mul_f32_e32 v54, v54, v18
	s_waitcnt lgkmcnt(0)
	v_add_f32_e32 v37, v37, v88
	v_fmamk_f32 v37, v37, 0x3c000000, v230
	v_mul_f32_e32 v36, v36, v18
	v_mul_f32_e32 v38, v38, v26
	v_mul_f32_e32 v19, v19, v18
	v_mul_f32_e32 v20, v20, v26
	v_mul_f32_e32 v0, v0, v18
	v_rsq_f32_e32 v37, v37
	s_nop 0
	v_mul_f32_e32 v37, v73, v37
	ds_bpermute_b32 v88, v75, v53
	v_mul_f32_e32 v39, v39, v37
	v_mul_f32_e32 v21, v21, v37
	s_waitcnt lgkmcnt(0)
	v_add_f32_e32 v53, v53, v88
	ds_bpermute_b32 v88, v77, v53
	s_waitcnt lgkmcnt(0)
	v_add_f32_e32 v53, v53, v88
	ds_bpermute_b32 v88, v78, v53
	s_waitcnt lgkmcnt(0)
	v_add_f32_e32 v53, v53, v88
	ds_bpermute_b32 v88, v79, v53
	s_waitcnt lgkmcnt(0)
	v_add_f32_e32 v53, v53, v88
	ds_bpermute_b32 v88, v80, v53
	s_waitcnt lgkmcnt(0)
	v_add_f32_e32 v53, v53, v88
	v_fmamk_f32 v53, v53, 0x3c000000, v230
	v_rsq_f32_e32 v53, v53
	s_nop 0
	v_mul_f32_e32 v53, v73, v53
	ds_bpermute_b32 v88, v75, v70
	v_mul_f32_e32 v40, v40, v53
	v_mul_f32_e32 v22, v22, v53
	s_waitcnt lgkmcnt(0)
	v_add_f32_e32 v70, v70, v88
	ds_bpermute_b32 v88, v77, v70
	s_waitcnt lgkmcnt(0)
	v_add_f32_e32 v70, v70, v88
	ds_bpermute_b32 v88, v78, v70
	s_waitcnt lgkmcnt(0)
	v_add_f32_e32 v70, v70, v88
	ds_bpermute_b32 v88, v79, v70
	s_waitcnt lgkmcnt(0)
	v_add_f32_e32 v70, v70, v88
	ds_bpermute_b32 v88, v80, v70
	s_waitcnt lgkmcnt(0)
	v_add_f32_e32 v70, v70, v88
	v_fmamk_f32 v70, v70, 0x3c000000, v230
	v_rsq_f32_e32 v70, v70
	s_nop 0
	v_mul_f32_e32 v70, v73, v70
	ds_bpermute_b32 v88, v75, v71
	v_mul_f32_e32 v41, v41, v70
	v_mul_f32_e32 v23, v23, v70
	s_waitcnt lgkmcnt(0)
	v_add_f32_e32 v71, v71, v88
	ds_bpermute_b32 v88, v77, v71
	s_waitcnt lgkmcnt(0)
	v_add_f32_e32 v71, v71, v88
	ds_bpermute_b32 v88, v78, v71
	s_waitcnt lgkmcnt(0)
	v_add_f32_e32 v71, v71, v88
	ds_bpermute_b32 v88, v79, v71
	s_waitcnt lgkmcnt(0)
	v_add_f32_e32 v71, v71, v88
	ds_bpermute_b32 v88, v80, v71
	s_waitcnt lgkmcnt(0)
	v_add_f32_e32 v71, v71, v88
	v_fmamk_f32 v71, v71, 0x3c000000, v230
	v_rsq_f32_e32 v71, v71
	s_nop 0
	v_mul_f32_e32 v71, v73, v71
	ds_bpermute_b32 v88, v75, v76
	v_mul_f32_e32 v42, v42, v71
	v_mul_f32_e32 v24, v24, v71
	s_waitcnt lgkmcnt(0)
	v_add_f32_e32 v76, v76, v88
	ds_bpermute_b32 v88, v77, v76
	s_waitcnt lgkmcnt(0)
	v_add_f32_e32 v76, v76, v88
	ds_bpermute_b32 v88, v78, v76
	s_waitcnt lgkmcnt(0)
	v_add_f32_e32 v76, v76, v88
	ds_bpermute_b32 v88, v79, v76
	s_waitcnt lgkmcnt(0)
	v_add_f32_e32 v76, v76, v88
	ds_bpermute_b32 v88, v80, v76
	s_waitcnt lgkmcnt(0)
	v_add_f32_e32 v76, v76, v88
	v_fmamk_f32 v76, v76, 0x3c000000, v230
	v_rsq_f32_e32 v76, v76
	s_nop 0
	v_mul_f32_e32 v76, v73, v76
	ds_bpermute_b32 v88, v75, v82
	v_mul_f32_e32 v43, v43, v76
	v_mul_f32_e32 v25, v25, v76
	s_waitcnt lgkmcnt(0)
	v_add_f32_e32 v82, v82, v88
	ds_bpermute_b32 v88, v77, v82
	s_waitcnt lgkmcnt(0)
	v_add_f32_e32 v82, v82, v88
	ds_bpermute_b32 v88, v78, v82
	s_waitcnt lgkmcnt(0)
	v_add_f32_e32 v82, v82, v88
	ds_bpermute_b32 v88, v79, v82
	s_waitcnt lgkmcnt(0)
	v_add_f32_e32 v82, v82, v88
	ds_bpermute_b32 v88, v80, v82
	s_waitcnt lgkmcnt(0)
	v_add_f32_e32 v82, v82, v88
	v_fmamk_f32 v82, v82, 0x3c000000, v230
	v_rsq_f32_e32 v82, v82
	s_nop 0
	v_mul_f32_e32 v82, v73, v82
	ds_bpermute_b32 v88, v75, v84
	v_mul_f32_e32 v44, v44, v82
	v_mul_f32_e32 v27, v27, v82
	s_waitcnt lgkmcnt(0)
	v_add_f32_e32 v84, v84, v88
	ds_bpermute_b32 v88, v77, v84
	s_waitcnt lgkmcnt(0)
	v_add_f32_e32 v84, v84, v88
	ds_bpermute_b32 v88, v78, v84
	s_waitcnt lgkmcnt(0)
; __device__ __forceinline__ void unitA(unsigned char* lds, const MixCtx& c, int b, int h, int qb, bool ltab) {
;     ...
;     for (int r = 0; r < 16; ++r) {
; #pragma unroll
;         for (int o = 1; o < 32; o <<= 1) ss[r] += __shfl_xor(ss[r], o);
;         ss[r] = (1.0f - lam_init) / sqrtf(ss[r] * (1.f / 128.f) + EPSN); }
; #pragma unroll
;     for (int dt = 0; dt < 4; ++dt) { const float g = subln[dt * 32 + r32];
; #pragma unroll
;         for (int r = 0; r < 16; ++r) oa[dt][r] = oa[dt][r] * ss[r] * g; }
	v_add_f32_e32 v84, v84, v88
	ds_bpermute_b32 v88, v79, v84
	s_waitcnt lgkmcnt(0)
	v_add_f32_e32 v84, v84, v88
	ds_bpermute_b32 v88, v80, v84
	s_waitcnt lgkmcnt(0)
	v_add_f32_e32 v84, v84, v88
	v_fmamk_f32 v84, v84, 0x3c000000, v230
	v_rsq_f32_e32 v84, v84
	s_nop 0
	v_mul_f32_e32 v84, v73, v84
	ds_bpermute_b32 v88, v75, v86
	v_mul_f32_e32 v45, v45, v84
	v_mul_f32_e32 v28, v28, v84
	s_waitcnt lgkmcnt(0)
	v_add_f32_e32 v86, v86, v88
	ds_bpermute_b32 v88, v77, v86
	s_waitcnt lgkmcnt(0)
	v_add_f32_e32 v86, v86, v88
	ds_bpermute_b32 v88, v78, v86
	s_waitcnt lgkmcnt(0)
	v_add_f32_e32 v86, v86, v88
	ds_bpermute_b32 v88, v79, v86
	s_waitcnt lgkmcnt(0)
	v_add_f32_e32 v86, v86, v88
	ds_bpermute_b32 v88, v80, v86
	s_waitcnt lgkmcnt(0)
	v_add_f32_e32 v86, v86, v88
	v_fmamk_f32 v86, v86, 0x3c000000, v230
	v_rsq_f32_e32 v86, v86
	s_nop 0
	v_mul_f32_e32 v86, v73, v86
	ds_bpermute_b32 v88, v75, v87
	v_mul_f32_e32 v46, v46, v86
	v_mul_f32_e32 v29, v29, v86
	s_waitcnt lgkmcnt(0)
	v_add_f32_e32 v87, v87, v88
	ds_bpermute_b32 v88, v77, v87
	s_waitcnt lgkmcnt(0)
	v_add_f32_e32 v87, v87, v88
	ds_bpermute_b32 v88, v78, v87
	s_waitcnt lgkmcnt(0)
	v_add_f32_e32 v87, v87, v88
	ds_bpermute_b32 v88, v79, v87
	s_waitcnt lgkmcnt(0)
	v_add_f32_e32 v87, v87, v88
	ds_bpermute_b32 v88, v80, v87
	s_waitcnt lgkmcnt(0)
	v_add_f32_e32 v87, v87, v88
	v_fmamk_f32 v87, v87, 0x3c000000, v230
	v_rsq_f32_e32 v87, v87
	s_nop 0
	v_mul_f32_e32 v87, v73, v87
	ds_bpermute_b32 v88, v75, v85
	v_mul_f32_e32 v47, v47, v87
	v_mul_f32_e32 v30, v30, v87
	s_waitcnt lgkmcnt(0)
	v_add_f32_e32 v85, v85, v88
	ds_bpermute_b32 v88, v77, v85
	s_waitcnt lgkmcnt(0)
	v_add_f32_e32 v85, v85, v88
	ds_bpermute_b32 v88, v78, v85
	s_waitcnt lgkmcnt(0)
	v_add_f32_e32 v85, v85, v88
	ds_bpermute_b32 v88, v79, v85
	s_waitcnt lgkmcnt(0)
	v_add_f32_e32 v85, v85, v88
	ds_bpermute_b32 v88, v80, v85
	s_waitcnt lgkmcnt(0)
	v_add_f32_e32 v85, v85, v88
	v_fmamk_f32 v85, v85, 0x3c000000, v230
	v_rsq_f32_e32 v85, v85
	s_nop 0
	v_mul_f32_e32 v85, v73, v85
	ds_bpermute_b32 v88, v75, v83
	v_mul_f32_e32 v48, v48, v85
	v_mul_f32_e32 v31, v31, v85
	s_waitcnt lgkmcnt(0)
	v_add_f32_e32 v83, v83, v88
	ds_bpermute_b32 v88, v77, v83
	s_waitcnt lgkmcnt(0)
	v_add_f32_e32 v83, v83, v88
	ds_bpermute_b32 v88, v78, v83
	s_waitcnt lgkmcnt(0)
	v_add_f32_e32 v83, v83, v88
	ds_bpermute_b32 v88, v79, v83
	s_waitcnt lgkmcnt(0)
	v_add_f32_e32 v83, v83, v88
	ds_bpermute_b32 v88, v80, v83
	s_waitcnt lgkmcnt(0)
	v_add_f32_e32 v83, v83, v88
	v_fmamk_f32 v83, v83, 0x3c000000, v230
	v_rsq_f32_e32 v83, v83
	s_nop 0
	v_mul_f32_e32 v83, v73, v83
	ds_bpermute_b32 v88, v75, v81
	v_mul_f32_e32 v49, v49, v83
	v_mul_f32_e32 v32, v32, v83
	s_waitcnt lgkmcnt(0)
	v_add_f32_e32 v81, v81, v88
	ds_bpermute_b32 v88, v77, v81
	s_waitcnt lgkmcnt(0)
	v_add_f32_e32 v81, v81, v88
	ds_bpermute_b32 v88, v78, v81
	s_waitcnt lgkmcnt(0)
	v_add_f32_e32 v81, v81, v88
	ds_bpermute_b32 v88, v79, v81
	s_waitcnt lgkmcnt(0)
	v_add_f32_e32 v81, v81, v88
	ds_bpermute_b32 v88, v80, v81
	s_waitcnt lgkmcnt(0)
	v_add_f32_e32 v81, v81, v88
	v_fmamk_f32 v81, v81, 0x3c000000, v230
	v_rsq_f32_e32 v81, v81
	s_nop 0
	v_mul_f32_e32 v81, v73, v81
	ds_bpermute_b32 v88, v75, v74
	ds_bpermute_b32 v75, v75, v72
	v_mul_f32_e32 v50, v50, v81
	v_mul_f32_e32 v33, v33, v81
	s_waitcnt lgkmcnt(1)
	v_add_f32_e32 v74, v74, v88
	ds_bpermute_b32 v88, v77, v74
	s_waitcnt lgkmcnt(1)
	v_add_f32_e32 v72, v72, v75
	ds_bpermute_b32 v75, v77, v72
	s_waitcnt lgkmcnt(1)
	v_add_f32_e32 v74, v74, v88
	ds_bpermute_b32 v88, v78, v74
	s_waitcnt lgkmcnt(1)
	v_add_f32_e32 v72, v72, v75
	ds_bpermute_b32 v75, v78, v72
	s_waitcnt lgkmcnt(1)
	v_add_f32_e32 v74, v74, v88
	ds_bpermute_b32 v88, v79, v74
	s_waitcnt lgkmcnt(1)
	v_add_f32_e32 v72, v72, v75
	ds_bpermute_b32 v75, v79, v72
	s_waitcnt lgkmcnt(1)
	v_add_f32_e32 v74, v74, v88
	ds_bpermute_b32 v88, v80, v74
	s_waitcnt lgkmcnt(1)
	v_add_f32_e32 v72, v72, v75
	ds_bpermute_b32 v75, v80, v72
	s_waitcnt lgkmcnt(1)
	v_add_f32_e32 v74, v74, v88
	v_fmamk_f32 v74, v74, 0x3c000000, v230
	s_waitcnt lgkmcnt(0)
	v_add_f32_e32 v72, v72, v75
	v_fmamk_f32 v72, v72, 0x3c000000, v230
	v_lshlrev_b32_e32 v89, 2, v2
	global_load_dword v2, v89, s[4:5]
	v_rsq_f32_e32 v74, v74
	s_nop 0
	v_mul_f32_e32 v74, v73, v74
	v_mul_f32_e32 v51, v51, v74
	v_mul_f32_e32 v34, v34, v74
	s_waitcnt vmcnt(0)
	v_mul_f32_e32 v88, v54, v2
	v_mul_f32_e32 v54, v55, v26
	s_lshl_b64 s[0:1], s[54:55], 11
	s_add_u32 s0, s2, s0
	s_addc_u32 s1, s3, s1
	v_mul_f32_e32 v80, v54, v2
	v_mul_f32_e32 v54, v56, v37
	v_mul_f32_e32 v79, v54, v2
	v_mul_f32_e32 v54, v57, v53
	v_mul_f32_e32 v78, v54, v2
	v_mul_f32_e32 v54, v58, v70
	v_mul_f32_e32 v77, v54, v2
	v_mul_f32_e32 v54, v59, v71
	v_rsq_f32_e32 v72, v72
	s_nop 0
	v_mul_f32_e32 v72, v73, v72
	v_mul_f32_e32 v75, v54, v2
	v_mul_f32_e32 v54, v60, v76
	v_mul_f32_e32 v73, v54, v2
	v_mul_f32_e32 v54, v61, v82
	v_mul_f32_e32 v61, v54, v2
	v_mul_f32_e32 v54, v62, v84
	v_mul_f32_e32 v60, v54, v2
	v_mul_f32_e32 v54, v63, v86
	v_mul_f32_e32 v59, v54, v2
	v_mul_f32_e32 v54, v64, v87
	v_mul_f32_e32 v58, v54, v2
	v_mul_f32_e32 v54, v65, v85
	v_mul_f32_e32 v57, v54, v2
	v_mul_f32_e32 v54, v66, v83
	v_mul_f32_e32 v56, v54, v2
	v_mul_f32_e32 v54, v67, v81
	v_mul_f32_e32 v55, v54, v2
	v_mul_f32_e32 v54, v68, v74
	v_mul_f32_e32 v62, v69, v72
	v_mul_f32_e32 v54, v2, v54
	v_mul_f32_e32 v2, v2, v62
	global_load_dword v62, v89, s[4:5] offset:128
	v_mul_f32_e32 v52, v52, v72
	v_mul_f32_e32 v35, v35, v72
	s_waitcnt vmcnt(0)
; __device__ __forceinline__ unsigned cvtpk(float lo, float hi) { f32x2_t v = {lo, hi}; bf16x2_t b = __builtin_convertvector(v, bf16x2_t); return __builtin_bit_cast(unsigned, b); }
; __device__ __forceinline__ int crowc(int r) { return (r & 3) + 8 * (r >> 2); }
; template <int DV>
; __device__ __forceinline__ void attn_store(const f32x16 (&o)[DV / 32], bf16_t* Op, int ldo) {
;     int tid_o = threadIdx.x; asm volatile("" : "+v"(tid_o));
;     const int lane = tid_o & 63, wid = tid_o >> 6, r32 = lane & 31, hi = lane >> 5;
; #pragma unroll
;     for (int dt = 0; dt < DV / 32; ++dt)
; #pragma unroll
;         for (int r = 0; r < 16; ++r) { const int row = 32 * wid + crowc(r) + 4 * hi; Op[(size_t)row * ldo + dt * 32 + r32] = (bf16_t)(cvtpk(o[dt][r], 0.f) & 0xffffu); }
; __device__ __forceinline__ void unitA(unsigned char* lds, const MixCtx& c, int b, int h, int qb, bool ltab) {
;     ...
;     for (int dt = 0; dt < 4; ++dt) { const float g = subln[dt * 32 + r32];
; #pragma unroll
;         for (int r = 0; r < 16; ++r) oa[dt][r] = oa[dt][r] * ss[r] * g; }
;     attn_store<128>(oa, c.MIX + (tokb + q0) * DM + h * 128, DM);
	v_mul_f32_e32 v36, v36, v62
	v_mul_f32_e32 v38, v38, v62
	v_mul_f32_e32 v39, v39, v62
	v_mul_f32_e32 v40, v40, v62
	v_mul_f32_e32 v41, v41, v62
	v_mul_f32_e32 v42, v42, v62
	v_mul_f32_e32 v43, v43, v62
	v_mul_f32_e32 v44, v44, v62
	v_mul_f32_e32 v45, v45, v62
	v_mul_f32_e32 v46, v46, v62
	v_mul_f32_e32 v47, v47, v62
	v_mul_f32_e32 v48, v48, v62
	v_mul_f32_e32 v49, v49, v62
	v_mul_f32_e32 v50, v50, v62
	v_mul_f32_e32 v51, v62, v51
	v_mul_f32_e32 v52, v62, v52
	global_load_dword v62, v89, s[4:5] offset:256
	s_waitcnt vmcnt(0)
	v_mul_f32_e32 v19, v19, v62
	v_mul_f32_e32 v20, v20, v62
	v_mul_f32_e32 v21, v21, v62
	v_mul_f32_e32 v22, v22, v62
	v_mul_f32_e32 v23, v23, v62
	v_mul_f32_e32 v24, v24, v62
	v_mul_f32_e32 v25, v25, v62
	v_mul_f32_e32 v27, v27, v62
	v_mul_f32_e32 v28, v28, v62
	v_mul_f32_e32 v29, v29, v62
	v_mul_f32_e32 v30, v30, v62
	v_mul_f32_e32 v31, v31, v62
	v_mul_f32_e32 v32, v32, v62
	v_mul_f32_e32 v33, v33, v62
	v_mul_f32_e32 v34, v34, v62
	v_mul_f32_e32 v35, v62, v35
	global_load_dword v62, v89, s[4:5] offset:384
	s_lshl_b32 s4, s72, 1
	s_add_u32 s0, s0, s4
	s_addc_u32 s1, s1, 0
	s_add_i32 s78, s78, s34
	s_add_i32 s76, s76, s34
	s_cmpk_lt_i32 s78, 0x400
	s_waitcnt vmcnt(0)
	v_mul_f32_e32 v18, v0, v62
	v_mul_f32_e32 v0, v3, v26
	v_mul_f32_e32 v26, v0, v62
	v_mul_f32_e32 v0, v4, v37
	v_mul_f32_e32 v37, v0, v62
	v_mul_f32_e32 v0, v5, v53
	v_mul_f32_e32 v53, v0, v62
	v_mul_f32_e32 v0, v6, v70
	v_mul_f32_e32 v89, v0, v62
	v_mul_f32_e32 v0, v7, v71
	v_mul_f32_e32 v90, v0, v62
	v_mul_f32_e32 v0, v8, v76
	v_mul_f32_e32 v76, v0, v62
	v_mul_f32_e32 v0, v9, v82
	v_mul_f32_e32 v82, v0, v62
	v_mul_f32_e32 v0, v10, v84
	v_mul_f32_e32 v84, v0, v62
	v_mul_f32_e32 v0, v11, v86
	v_mul_f32_e32 v86, v0, v62
	v_mul_f32_e32 v0, v12, v87
	v_mul_f32_e32 v87, v0, v62
	v_mul_f32_e32 v0, v13, v85
	v_mul_f32_e32 v85, v0, v62
	v_mul_f32_e32 v0, v14, v83
	v_mul_f32_e32 v83, v0, v62
	v_mul_f32_e32 v0, v15, v81
	v_mul_f32_e32 v81, v0, v62
	v_mul_f32_e32 v0, v16, v74
	v_mul_f32_e32 v91, v0, v62
	v_mul_f32_e32 v0, v17, v72
	v_mul_f32_e32 v92, v62, v0
	v_mov_b32_e32 v0, v228
	s_nop 0
	v_ashrrev_i32_e32 v4, 1, v0
	v_and_b32_e32 v3, 31, v0
	v_and_b32_e32 v4, 0xffffffe0, v4
	v_lshrrev_b32_e32 v0, 3, v0
	v_and_or_b32 v4, v0, 4, v4
	v_lshlrev_b32_e32 v0, 1, v3
	v_ashrrev_i32_e32 v5, 31, v4
	v_or_b32_e32 v10, 1, v4
	v_lshl_add_u64 v[6:7], s[0:1], 0, v[0:1]
	v_lshlrev_b64 v[8:9], 11, v[4:5]
	v_ashrrev_i32_e32 v11, 31, v10
	v_or_b32_e32 v12, 2, v4
	v_cvt_pk_bf16_f32 v0, v88, s0
	v_lshl_add_u64 v[8:9], v[6:7], 0, v[8:9]
	v_lshlrev_b64 v[10:11], 11, v[10:11]
	v_ashrrev_i32_e32 v13, 31, v12
	v_or_b32_e32 v14, 3, v4
	global_store_short v[8:9], v0, off
	v_cvt_pk_bf16_f32 v0, v80, s0
	v_lshl_add_u64 v[10:11], v[6:7], 0, v[10:11]
	v_lshlrev_b64 v[12:13], 11, v[12:13]
	v_ashrrev_i32_e32 v15, 31, v14
	v_or_b32_e32 v16, 8, v4
	global_store_short v[10:11], v0, off
	v_cvt_pk_bf16_f32 v0, v79, s0
	v_lshl_add_u64 v[12:13], v[6:7], 0, v[12:13]
	v_lshlrev_b64 v[14:15], 11, v[14:15]
	v_ashrrev_i32_e32 v17, 31, v16
	v_or_b32_e32 v62, 9, v4
	global_store_short v[12:13], v0, off
	v_cvt_pk_bf16_f32 v0, v78, s0
	v_lshl_add_u64 v[14:15], v[6:7], 0, v[14:15]
	v_lshlrev_b64 v[16:17], 11, v[16:17]
	v_ashrrev_i32_e32 v63, 31, v62
	v_or_b32_e32 v64, 10, v4
	global_store_short v[14:15], v0, off
	v_cvt_pk_bf16_f32 v0, v77, s0
	v_lshl_add_u64 v[16:17], v[6:7], 0, v[16:17]
	v_lshlrev_b64 v[62:63], 11, v[62:63]
	v_ashrrev_i32_e32 v65, 31, v64
	v_or_b32_e32 v66, 11, v4
	global_store_short v[16:17], v0, off
	v_cvt_pk_bf16_f32 v0, v75, s0
	v_lshl_add_u64 v[62:63], v[6:7], 0, v[62:63]
	v_lshlrev_b64 v[64:65], 11, v[64:65]
	v_ashrrev_i32_e32 v67, 31, v66
	global_store_short v[62:63], v0, off
	v_cvt_pk_bf16_f32 v0, v73, s0
	v_lshl_add_u64 v[64:65], v[6:7], 0, v[64:65]
	v_lshlrev_b64 v[66:67], 11, v[66:67]
	v_or_b32_e32 v68, 16, v4
	global_store_short v[64:65], v0, off
	v_cvt_pk_bf16_f32 v0, v61, s0
	v_lshl_add_u64 v[66:67], v[6:7], 0, v[66:67]
	v_ashrrev_i32_e32 v69, 31, v68
	global_store_short v[66:67], v0, off
	v_cvt_pk_bf16_f32 v0, v60, s0
	v_lshlrev_b64 v[60:61], 11, v[68:69]
	v_or_b32_e32 v68, 17, v4
	v_ashrrev_i32_e32 v69, 31, v68
	v_lshl_add_u64 v[60:61], v[6:7], 0, v[60:61]
	v_lshlrev_b64 v[68:69], 11, v[68:69]
	v_or_b32_e32 v70, 18, v4
	global_store_short v[60:61], v0, off
	v_cvt_pk_bf16_f32 v0, v59, s0
	v_lshl_add_u64 v[68:69], v[6:7], 0, v[68:69]
	v_ashrrev_i32_e32 v71, 31, v70
	global_store_short v[68:69], v0, off
	v_cvt_pk_bf16_f32 v0, v58, s0
	v_lshlrev_b64 v[58:59], 11, v[70:71]
	v_or_b32_e32 v70, 19, v4
	v_ashrrev_i32_e32 v71, 31, v70
	v_lshl_add_u64 v[58:59], v[6:7], 0, v[58:59]
	v_lshlrev_b64 v[70:71], 11, v[70:71]
	v_or_b32_e32 v72, 24, v4
	global_store_short v[58:59], v0, off
	v_cvt_pk_bf16_f32 v0, v57, s0
; __device__ __forceinline__ unsigned cvtpk(float lo, float hi) { f32x2_t v = {lo, hi}; bf16x2_t b = __builtin_convertvector(v, bf16x2_t); return __builtin_bit_cast(unsigned, b); }
; __device__ __forceinline__ int crowc(int r) { return (r & 3) + 8 * (r >> 2); }
; template <int DV>
; __device__ __forceinline__ void attn_store(const f32x16 (&o)[DV / 32], bf16_t* Op, int ldo) {
;     int tid_o = threadIdx.x; asm volatile("" : "+v"(tid_o));
;     const int lane = tid_o & 63, wid = tid_o >> 6, r32 = lane & 31, hi = lane >> 5;
; #pragma unroll
;     for (int dt = 0; dt < DV / 32; ++dt)
; #pragma unroll
;         for (int r = 0; r < 16; ++r) { const int row = 32 * wid + crowc(r) + 4 * hi; Op[(size_t)row * ldo + dt * 32 + r32] = (bf16_t)(cvtpk(o[dt][r], 0.f) & 0xffffu); }
; __global__ void __launch_bounds__(512, 2) fwd_kernel(Args a) {
;     ...
;         { int ph = -1; for (int it = cb_; it < 1024; it += G) { int b, h, qb; deal_unit(it, b, h, qb); unitA(lds, mc, b, h, qb, h != ph); ph = h; } }
	v_lshl_add_u64 v[70:71], v[6:7], 0, v[70:71]
	v_ashrrev_i32_e32 v73, 31, v72
	global_store_short v[70:71], v0, off
	v_cvt_pk_bf16_f32 v0, v56, s0
	v_lshlrev_b64 v[56:57], 11, v[72:73]
	v_or_b32_e32 v72, 25, v4
	v_ashrrev_i32_e32 v73, 31, v72
	v_lshl_add_u64 v[56:57], v[6:7], 0, v[56:57]
	v_lshlrev_b64 v[72:73], 11, v[72:73]
	v_or_b32_e32 v74, 26, v4
	global_store_short v[56:57], v0, off
	v_cvt_pk_bf16_f32 v0, v55, s0
	v_lshl_add_u64 v[72:73], v[6:7], 0, v[72:73]
	v_ashrrev_i32_e32 v75, 31, v74
	global_store_short v[72:73], v0, off
	v_cvt_pk_bf16_f32 v0, v54, s0
	v_lshlrev_b64 v[54:55], 11, v[74:75]
	v_or_b32_e32 v4, 27, v4
	v_lshl_add_u64 v[54:55], v[6:7], 0, v[54:55]
	v_ashrrev_i32_e32 v5, 31, v4
	global_store_short v[54:55], v0, off
	v_cvt_pk_bf16_f32 v0, v2, s0
	v_lshlrev_b64 v[2:3], 11, v[4:5]
	v_lshl_add_u64 v[2:3], v[6:7], 0, v[2:3]
	global_store_short v[2:3], v0, off
	v_cvt_pk_bf16_f32 v0, v36, s0
	global_store_short v[8:9], v0, off offset:64
	v_cvt_pk_bf16_f32 v0, v38, s0
	global_store_short v[10:11], v0, off offset:64
	v_cvt_pk_bf16_f32 v0, v39, s0
	global_store_short v[12:13], v0, off offset:64
	v_cvt_pk_bf16_f32 v0, v40, s0
	global_store_short v[14:15], v0, off offset:64
	v_cvt_pk_bf16_f32 v0, v41, s0
	global_store_short v[16:17], v0, off offset:64
	v_cvt_pk_bf16_f32 v0, v42, s0
	global_store_short v[62:63], v0, off offset:64
	v_cvt_pk_bf16_f32 v0, v43, s0
	global_store_short v[64:65], v0, off offset:64
	v_cvt_pk_bf16_f32 v0, v44, s0
	global_store_short v[66:67], v0, off offset:64
	v_cvt_pk_bf16_f32 v0, v45, s0
	global_store_short v[60:61], v0, off offset:64
	v_cvt_pk_bf16_f32 v0, v46, s0
	global_store_short v[68:69], v0, off offset:64
	v_cvt_pk_bf16_f32 v0, v47, s0
	global_store_short v[58:59], v0, off offset:64
	v_cvt_pk_bf16_f32 v0, v48, s0
	global_store_short v[70:71], v0, off offset:64
	v_cvt_pk_bf16_f32 v0, v49, s0
	global_store_short v[56:57], v0, off offset:64
	v_cvt_pk_bf16_f32 v0, v50, s0
	global_store_short v[72:73], v0, off offset:64
	v_cvt_pk_bf16_f32 v0, v51, s0
	global_store_short v[54:55], v0, off offset:64
	v_cvt_pk_bf16_f32 v0, v52, s0
	global_store_short v[2:3], v0, off offset:64
	v_cvt_pk_bf16_f32 v0, v19, s0
	global_store_short v[8:9], v0, off offset:128
	v_cvt_pk_bf16_f32 v0, v20, s0
	global_store_short v[10:11], v0, off offset:128
	v_cvt_pk_bf16_f32 v0, v21, s0
	global_store_short v[12:13], v0, off offset:128
	v_cvt_pk_bf16_f32 v0, v22, s0
	global_store_short v[14:15], v0, off offset:128
	v_cvt_pk_bf16_f32 v0, v23, s0
	global_store_short v[16:17], v0, off offset:128
	v_cvt_pk_bf16_f32 v0, v24, s0
	global_store_short v[62:63], v0, off offset:128
	v_cvt_pk_bf16_f32 v0, v25, s0
	global_store_short v[64:65], v0, off offset:128
	v_cvt_pk_bf16_f32 v0, v27, s0
	global_store_short v[66:67], v0, off offset:128
	v_cvt_pk_bf16_f32 v0, v28, s0
	global_store_short v[60:61], v0, off offset:128
	v_cvt_pk_bf16_f32 v0, v29, s0
	global_store_short v[68:69], v0, off offset:128
	v_cvt_pk_bf16_f32 v0, v30, s0
	global_store_short v[58:59], v0, off offset:128
	v_cvt_pk_bf16_f32 v0, v31, s0
	global_store_short v[70:71], v0, off offset:128
	v_cvt_pk_bf16_f32 v0, v32, s0
	global_store_short v[56:57], v0, off offset:128
	v_cvt_pk_bf16_f32 v0, v33, s0
	global_store_short v[72:73], v0, off offset:128
	v_cvt_pk_bf16_f32 v0, v34, s0
	global_store_short v[54:55], v0, off offset:128
	v_cvt_pk_bf16_f32 v0, v35, s0
	global_store_short v[2:3], v0, off offset:128
	v_cvt_pk_bf16_f32 v0, v18, s0
	global_store_short v[8:9], v0, off offset:192
	v_cvt_pk_bf16_f32 v0, v26, s0
	global_store_short v[10:11], v0, off offset:192
	v_cvt_pk_bf16_f32 v0, v37, s0
	global_store_short v[12:13], v0, off offset:192
	v_cvt_pk_bf16_f32 v0, v53, s0
	global_store_short v[14:15], v0, off offset:192
	v_cvt_pk_bf16_f32 v0, v89, s0
	global_store_short v[16:17], v0, off offset:192
	v_cvt_pk_bf16_f32 v0, v90, s0
	global_store_short v[62:63], v0, off offset:192
	v_cvt_pk_bf16_f32 v0, v76, s0
	global_store_short v[64:65], v0, off offset:192
	v_cvt_pk_bf16_f32 v0, v82, s0
	global_store_short v[66:67], v0, off offset:192
	v_cvt_pk_bf16_f32 v0, v84, s0
	global_store_short v[60:61], v0, off offset:192
	v_cvt_pk_bf16_f32 v0, v86, s0
	global_store_short v[68:69], v0, off offset:192
	v_cvt_pk_bf16_f32 v0, v87, s0
	global_store_short v[58:59], v0, off offset:192
	v_cvt_pk_bf16_f32 v0, v85, s0
	global_store_short v[70:71], v0, off offset:192
	v_cvt_pk_bf16_f32 v0, v83, s0
	global_store_short v[56:57], v0, off offset:192
	v_cvt_pk_bf16_f32 v0, v81, s0
	global_store_short v[72:73], v0, off offset:192
	v_cvt_pk_bf16_f32 v0, v91, s0
	global_store_short v[54:55], v0, off offset:192
	v_cvt_pk_bf16_f32 v0, v92, s0
	global_store_short v[2:3], v0, off offset:192
	s_cbranch_scc0 .LBB0_863

; __device__ __forceinline__ unsigned cvt_pk_bf16(float lo, float hi) { unsigned r; asm volatile("v_cvt_pk_bf16_f32 %0, %1, %2" : "=v"(r) : "v"(lo), "v"(hi)); return r; }
; __device__ __forceinline__ void load_row_scales(const float* ssp, int row0, int fq, float (&rs)[2][4]) {
;     f32x4 part[2][4];
;     const float* sp = ssp + (size_t)row0 * 16 + 4 * fq;
; #pragma unroll
;     for (int ai = 0; ai < 2; ++ai)
; #pragma unroll
;         for (int m = 0; m < 4; ++m) part[ai][m] = *(const f32x4*)(sp + (size_t)(ai * HALF + m * 16) * 16);
; #pragma unroll
;     for (int ai = 0; ai < 2; ++ai)
; #pragma unroll
;         for (int m = 0; m < 4; ++m) { float t = (part[ai][m][0] + part[ai][m][1]) + (part[ai][m][2] + part[ai][m][3]);
;             t += __shfl_xor(t, 16); t += __shfl_xor(t, 32);
;             rs[ai][m] = 1.0f / sqrtf(t * (1.0f / 1024.0f) + 1e-6f); }
; }
;     __device__ __forceinline__ void operator()(f32x4 (&acc)[2][2][4][2], const Unit& u, int wr, int wc, int fr, int fq) const {
;     ...
;             bf16_t* rowp = R + (size_t)row0 * ldr + (colt - r_col0);
;             float rsa[2][4];
;             if (ssp) load_row_scales(ssp, row0, fq, rsa);
;             else {
; #pragma unroll
;                 for (int ai = 0; ai < 2; ++ai)
; #pragma unroll
;                     for (int m = 0; m < 4; ++m) rsa[ai][m] = 1.0f; }
; #pragma unroll
;             for (int ai = 0; ai < 2; ++ai) {
; #pragma unroll
;                 for (int m = 0; m < 4; ++m) { const float rs = rsa[ai][m];
; #pragma unroll
;                     for (int bj = 0; bj < 2; ++bj) { const f32x4 v0 = acc[ai][bj][m][0] * rs, v1 = acc[ai][bj][m][1] * rs;
;                         u32x4 w; w.x = cvt_pk_bf16(v0[0], v0[1]); w.y = cvt_pk_bf16(v0[2], v0[3]); w.z = cvt_pk_bf16(v1[0], v1[1]); w.w = cvt_pk_bf16(v1[2], v1[3]);
;                         *(u32x4*)(rowp + bj * HALF) = w; }
;                     rowp += (size_t)16 * ldr; asm volatile("" : "+v"(rowp) :: "memory"); }
;                 rowp += (size_t)64 * ldr; asm volatile("" : "+v"(rowp)); }
.LBB0_1127:
	v_lshl_add_u32 v130, s13, 8, v173
	v_ashrrev_i32_e32 v131, 31, v130
	v_lshlrev_b64 v[134:135], 11, v[130:131]
	v_lshlrev_b64 v[130:131], 6, v[130:131]
	v_lshl_add_u64 v[130:131], v[164:165], 0, v[130:131]
	global_load_dwordx4 v[180:183], v[130:131], off
	global_load_dwordx4 v[154:157], v[130:131], off offset:1024
	global_load_dwordx4 v[150:153], v[130:131], off offset:2048
	global_load_dwordx4 v[146:149], v[130:131], off offset:3072
	s_movk_i32 s0, 0x2000
	v_add_co_u32_e32 v130, vcc, s0, v130
	v_and_b32_e32 v177, 64, v229
	s_nop 0
	v_addc_co_u32_e32 v131, vcc, 0, v131, vcc
	v_xor_b32_e32 v172, 16, v229
	v_add_u32_e32 v178, 64, v177
	v_cmp_lt_i32_e32 vcc, v172, v178
	v_lshl_or_b32 v132, s12, 8, v175
	v_lshl_add_u64 v[134:135], s[46:47], 0, v[134:135]
	v_cndmask_b32_e32 v172, v229, v172, vcc
	v_lshlrev_b32_e32 v177, 2, v172
	v_xor_b32_e32 v172, 32, v229
	v_cmp_lt_i32_e32 vcc, v172, v178
	v_ashrrev_i32_e32 v133, 31, v132
	v_lshl_add_u64 v[170:171], v[132:133], 1, v[134:135]
	v_cndmask_b32_e32 v172, v229, v172, vcc
	v_lshlrev_b32_e32 v178, 2, v172
	global_load_dwordx4 v[142:145], v[130:131], off
	global_load_dwordx4 v[138:141], v[130:131], off offset:1024
	global_load_dwordx4 v[134:137], v[130:131], off offset:2048
	s_nop 0
	global_load_dwordx4 v[130:133], v[130:131], off offset:3072
	s_mov_b64 s[12:13], 0x8000
	s_waitcnt vmcnt(0)
	v_mov_b32_e32 v184, v181
	v_mov_b32_e32 v185, v182
	v_mov_b32_e32 v181, v183
	v_pk_add_f32 v[180:181], v[184:185], v[180:181]
	s_nop 0
	v_add_f32_e32 v172, v180, v181
	ds_bpermute_b32 v179, v177, v172
	s_waitcnt lgkmcnt(0)
	v_add_f32_e32 v172, v172, v179
	ds_bpermute_b32 v179, v178, v172
	s_waitcnt lgkmcnt(0)
	v_add_f32_e32 v172, v172, v179
	v_fmamk_f32 v172, v172, 0x3a800000, v230
	v_mov_b32_e32 v180, v155
	v_mov_b32_e32 v181, v156
	v_mov_b32_e32 v155, v157
	v_pk_add_f32 v[154:155], v[180:181], v[154:155]
	v_rsq_f32_e32 v172, v172
	s_nop 0
	v_add_f32_e32 v154, v154, v155
	ds_bpermute_b32 v155, v177, v154
	v_pk_mul_f32 v[128:129], v[128:129], v[172:173] op_sel_hi:[1,0]
	v_pk_mul_f32 v[126:127], v[126:127], v[172:173] op_sel_hi:[1,0]
	v_pk_mul_f32 v[120:121], v[120:121], v[172:173] op_sel_hi:[1,0]
	v_pk_mul_f32 v[118:119], v[118:119], v[172:173] op_sel_hi:[1,0]
	s_waitcnt lgkmcnt(0)
	v_add_f32_e32 v154, v154, v155
	ds_bpermute_b32 v155, v178, v154
	s_waitcnt lgkmcnt(0)
	v_add_f32_e32 v154, v154, v155
	v_fmamk_f32 v154, v154, 0x3a800000, v230
	v_mov_b32_e32 v156, v151
	v_mov_b32_e32 v157, v152
	v_mov_b32_e32 v151, v153
	v_pk_add_f32 v[150:151], v[156:157], v[150:151]
	v_rsq_f32_e32 v154, v154
	s_nop 0
	v_add_f32_e32 v150, v150, v151
	ds_bpermute_b32 v151, v177, v150
	s_waitcnt lgkmcnt(0)
	v_add_f32_e32 v150, v150, v151
	ds_bpermute_b32 v151, v178, v150
	s_waitcnt lgkmcnt(0)
	v_add_f32_e32 v150, v150, v151
	v_fmamk_f32 v150, v150, 0x3a800000, v230
	v_mov_b32_e32 v152, v147
	v_mov_b32_e32 v153, v148
	v_mov_b32_e32 v147, v149
	v_pk_add_f32 v[146:147], v[152:153], v[146:147]
	v_rsq_f32_e32 v150, v150
	s_nop 0
	v_add_f32_e32 v146, v146, v147
	ds_bpermute_b32 v147, v177, v146
	v_pk_mul_f32 v[114:115], v[114:115], v[154:155] op_sel_hi:[1,0]
	v_pk_mul_f32 v[104:105], v[104:105], v[154:155] op_sel_hi:[1,0]
	v_pk_mul_f32 v[102:103], v[102:103], v[154:155] op_sel_hi:[1,0]
	s_waitcnt lgkmcnt(0)
	v_add_f32_e32 v146, v146, v147
	ds_bpermute_b32 v147, v178, v146
	s_waitcnt lgkmcnt(0)
	v_add_f32_e32 v146, v146, v147
	v_fmamk_f32 v146, v146, 0x3a800000, v230
	v_mov_b32_e32 v148, v143
	v_mov_b32_e32 v149, v144
	v_mov_b32_e32 v143, v145
	v_pk_add_f32 v[142:143], v[148:149], v[142:143]
	v_rsq_f32_e32 v146, v146
	s_nop 0
	v_add_f32_e32 v142, v142, v143
	ds_bpermute_b32 v143, v177, v142
	v_pk_mul_f32 v[98:99], v[98:99], v[150:151] op_sel_hi:[1,0]
	v_pk_mul_f32 v[88:89], v[88:89], v[150:151] op_sel_hi:[1,0]
	v_pk_mul_f32 v[86:87], v[86:87], v[150:151] op_sel_hi:[1,0]
	s_waitcnt lgkmcnt(0)
	v_add_f32_e32 v142, v142, v143
	ds_bpermute_b32 v143, v178, v142
	s_waitcnt lgkmcnt(0)
	v_add_f32_e32 v142, v142, v143
	v_fmamk_f32 v142, v142, 0x3a800000, v230
	v_mov_b32_e32 v144, v139
	v_mov_b32_e32 v145, v140
	v_mov_b32_e32 v139, v141
	v_pk_add_f32 v[138:139], v[144:145], v[138:139]
	v_rsq_f32_e32 v142, v142
	s_nop 0
	v_add_f32_e32 v138, v138, v139
	ds_bpermute_b32 v139, v177, v138
	v_pk_mul_f32 v[82:83], v[82:83], v[146:147] op_sel_hi:[1,0]
	v_pk_mul_f32 v[72:73], v[72:73], v[146:147] op_sel_hi:[1,0]
	v_pk_mul_f32 v[70:71], v[70:71], v[146:147] op_sel_hi:[1,0]
	s_waitcnt lgkmcnt(0)
	v_add_f32_e32 v138, v138, v139
	ds_bpermute_b32 v139, v178, v138
	s_waitcnt lgkmcnt(0)
	v_add_f32_e32 v138, v138, v139
	v_fmamk_f32 v138, v138, 0x3a800000, v230
	v_mov_b32_e32 v140, v135
	v_mov_b32_e32 v141, v136
	v_mov_b32_e32 v135, v137
	v_pk_add_f32 v[134:135], v[140:141], v[134:135]
	v_rsq_f32_e32 v138, v138
	s_nop 0
	v_add_f32_e32 v134, v134, v135
	ds_bpermute_b32 v135, v177, v134
	v_pk_mul_f32 v[64:65], v[64:65], v[142:143] op_sel_hi:[1,0]
	v_pk_mul_f32 v[62:63], v[62:63], v[142:143] op_sel_hi:[1,0]
	v_pk_mul_f32 v[56:57], v[56:57], v[142:143] op_sel_hi:[1,0]
	v_pk_mul_f32 v[54:55], v[54:55], v[142:143] op_sel_hi:[1,0]
	s_waitcnt lgkmcnt(0)
	v_add_f32_e32 v134, v134, v135
	ds_bpermute_b32 v135, v178, v134
	s_waitcnt lgkmcnt(0)
	v_add_f32_e32 v134, v134, v135
	v_fmamk_f32 v134, v134, 0x3a800000, v230
	v_mov_b32_e32 v136, v131
	v_mov_b32_e32 v137, v132
	v_mov_b32_e32 v131, v133
	v_pk_add_f32 v[130:131], v[136:137], v[130:131]
	v_rsq_f32_e32 v134, v134
	s_nop 0
	v_add_f32_e32 v130, v130, v131
	ds_bpermute_b32 v131, v177, v130
	v_pk_mul_f32 v[50:51], v[50:51], v[138:139] op_sel_hi:[1,0]
	v_pk_mul_f32 v[40:41], v[40:41], v[138:139] op_sel_hi:[1,0]
	v_pk_mul_f32 v[38:39], v[38:39], v[138:139] op_sel_hi:[1,0]
	s_waitcnt lgkmcnt(0)
; __device__ __forceinline__ unsigned cvt_pk_bf16(float lo, float hi) { unsigned r; asm volatile("v_cvt_pk_bf16_f32 %0, %1, %2" : "=v"(r) : "v"(lo), "v"(hi)); return r; }
;     __device__ __forceinline__ void operator()(f32x4 (&acc)[2][2][4][2], const Unit& u, int wr, int wc, int fr, int fq) const {
;     ...
; #pragma unroll
;             for (int ai = 0; ai < 2; ++ai) {
; #pragma unroll
;                 for (int m = 0; m < 4; ++m) { const float rs = rsa[ai][m];
; #pragma unroll
;                     for (int bj = 0; bj < 2; ++bj) { const f32x4 v0 = acc[ai][bj][m][0] * rs, v1 = acc[ai][bj][m][1] * rs;
;                         u32x4 w; w.x = cvt_pk_bf16(v0[0], v0[1]); w.y = cvt_pk_bf16(v0[2], v0[3]); w.z = cvt_pk_bf16(v1[0], v1[1]); w.w = cvt_pk_bf16(v1[2], v1[3]);
;                         *(u32x4*)(rowp + bj * HALF) = w; }
;                     rowp += (size_t)16 * ldr; asm volatile("" : "+v"(rowp) :: "memory"); }
;                 rowp += (size_t)64 * ldr; asm volatile("" : "+v"(rowp)); }
	v_add_f32_e32 v130, v130, v131
	ds_bpermute_b32 v131, v178, v130
	s_waitcnt lgkmcnt(0)
	v_add_f32_e32 v130, v130, v131
	v_fmamk_f32 v130, v130, 0x3a800000, v230
	s_mov_b64 s[0:1], 0x20000
	v_pk_mul_f32 v[132:133], v[124:125], v[172:173] op_sel_hi:[1,0]
	v_pk_mul_f32 v[124:125], v[122:123], v[172:173] op_sel_hi:[1,0]
	v_cvt_pk_bf16_f32 v122, v126, v127
	v_cvt_pk_bf16_f32 v123, v128, v129
	v_pk_mul_f32 v[34:35], v[34:35], v[134:135] op_sel_hi:[1,0]
	v_cvt_pk_bf16_f32 v124, v124, v125
	v_cvt_pk_bf16_f32 v125, v132, v133
	global_store_dwordx4 v[170:171], v[122:125], off
	v_pk_mul_f32 v[24:25], v[24:25], v[134:135] op_sel_hi:[1,0]
	v_pk_mul_f32 v[22:23], v[22:23], v[134:135] op_sel_hi:[1,0]
	v_pk_mul_f32 v[122:123], v[112:113], v[172:173] op_sel_hi:[1,0]
	v_pk_mul_f32 v[112:113], v[110:111], v[172:173] op_sel_hi:[1,0]
	v_cvt_pk_bf16_f32 v110, v118, v119
	v_cvt_pk_bf16_f32 v111, v120, v121
	v_rsq_f32_e32 v130, v130
	s_nop 0
	v_cvt_pk_bf16_f32 v112, v112, v113
	v_cvt_pk_bf16_f32 v113, v122, v123
	global_store_dwordx4 v[170:171], v[110:113], off offset:256
	v_pk_mul_f32 v[18:19], v[18:19], v[130:131] op_sel_hi:[1,0]
	v_pk_mul_f32 v[8:9], v[8:9], v[130:131] op_sel_hi:[1,0]
	v_lshl_add_u64 v[110:111], v[170:171], 0, s[12:13]
	v_pk_mul_f32 v[112:113], v[116:117], v[154:155] op_sel_hi:[1,0]
	v_pk_mul_f32 v[116:117], v[108:109], v[154:155] op_sel_hi:[1,0]
	v_pk_mul_f32 v[108:109], v[106:107], v[154:155] op_sel_hi:[1,0]
	v_cvt_pk_bf16_f32 v106, v114, v115
	v_cvt_pk_bf16_f32 v107, v112, v113
	v_pk_mul_f32 v[6:7], v[6:7], v[130:131] op_sel_hi:[1,0]
	v_cvt_pk_bf16_f32 v108, v108, v109
	v_cvt_pk_bf16_f32 v109, v116, v117
	flat_store_dwordx4 v[110:111], v[106:109]
	s_andn2_b64 vcc, exec, s[6:7]
	s_nop 0
	v_pk_mul_f32 v[106:107], v[96:97], v[154:155] op_sel_hi:[1,0]
	v_pk_mul_f32 v[96:97], v[94:95], v[154:155] op_sel_hi:[1,0]
	v_cvt_pk_bf16_f32 v94, v102, v103
	v_cvt_pk_bf16_f32 v95, v104, v105
	s_nop 0
	v_cvt_pk_bf16_f32 v96, v96, v97
	v_cvt_pk_bf16_f32 v97, v106, v107
	flat_store_dwordx4 v[110:111], v[94:97] offset:256
	s_nop 1
	v_lshl_add_u64 v[94:95], v[110:111], 0, s[12:13]
	v_pk_mul_f32 v[96:97], v[100:101], v[150:151] op_sel_hi:[1,0]
	v_pk_mul_f32 v[100:101], v[92:93], v[150:151] op_sel_hi:[1,0]
	v_pk_mul_f32 v[92:93], v[90:91], v[150:151] op_sel_hi:[1,0]
	v_cvt_pk_bf16_f32 v90, v98, v99
	v_cvt_pk_bf16_f32 v91, v96, v97
	s_nop 0
	v_cvt_pk_bf16_f32 v92, v92, v93
	v_cvt_pk_bf16_f32 v93, v100, v101
	flat_store_dwordx4 v[94:95], v[90:93]
	s_nop 1
	v_pk_mul_f32 v[90:91], v[80:81], v[150:151] op_sel_hi:[1,0]
	v_pk_mul_f32 v[80:81], v[78:79], v[150:151] op_sel_hi:[1,0]
	v_cvt_pk_bf16_f32 v78, v86, v87
	v_cvt_pk_bf16_f32 v79, v88, v89
	s_nop 0
	v_cvt_pk_bf16_f32 v80, v80, v81
	v_cvt_pk_bf16_f32 v81, v90, v91
	flat_store_dwordx4 v[94:95], v[78:81] offset:256
	s_nop 1
	v_lshl_add_u64 v[78:79], v[94:95], 0, s[12:13]
	v_pk_mul_f32 v[80:81], v[84:85], v[146:147] op_sel_hi:[1,0]
	v_pk_mul_f32 v[84:85], v[76:77], v[146:147] op_sel_hi:[1,0]
	v_pk_mul_f32 v[76:77], v[74:75], v[146:147] op_sel_hi:[1,0]
	v_cvt_pk_bf16_f32 v74, v82, v83
	v_cvt_pk_bf16_f32 v75, v80, v81
	s_nop 0
	v_cvt_pk_bf16_f32 v76, v76, v77
	v_cvt_pk_bf16_f32 v77, v84, v85
	flat_store_dwordx4 v[78:79], v[74:77]
	s_nop 1
	v_pk_mul_f32 v[74:75], v[68:69], v[146:147] op_sel_hi:[1,0]
	v_pk_mul_f32 v[68:69], v[66:67], v[146:147] op_sel_hi:[1,0]
	v_cvt_pk_bf16_f32 v66, v70, v71
	v_cvt_pk_bf16_f32 v67, v72, v73
	s_nop 0
	v_cvt_pk_bf16_f32 v68, v68, v69
	v_cvt_pk_bf16_f32 v69, v74, v75
	flat_store_dwordx4 v[78:79], v[66:69] offset:256
	s_nop 1
	v_lshl_add_u64 v[66:67], v[78:79], 0, s[12:13]
	v_pk_mul_f32 v[68:69], v[60:61], v[142:143] op_sel_hi:[1,0]
	v_lshl_add_u64 v[66:67], v[66:67], 0, s[0:1]
	v_pk_mul_f32 v[60:61], v[58:59], v[142:143] op_sel_hi:[1,0]
	v_cvt_pk_bf16_f32 v58, v62, v63
	v_cvt_pk_bf16_f32 v59, v64, v65
	s_nop 0
	v_cvt_pk_bf16_f32 v60, v60, v61
	v_cvt_pk_bf16_f32 v61, v68, v69
	flat_store_dwordx4 v[66:67], v[58:61]
	s_nop 1
	v_pk_mul_f32 v[58:59], v[48:49], v[142:143] op_sel_hi:[1,0]
	v_pk_mul_f32 v[48:49], v[46:47], v[142:143] op_sel_hi:[1,0]
	v_cvt_pk_bf16_f32 v46, v54, v55
	v_cvt_pk_bf16_f32 v47, v56, v57
	s_nop 0
	v_cvt_pk_bf16_f32 v48, v48, v49
	v_cvt_pk_bf16_f32 v49, v58, v59
	flat_store_dwordx4 v[66:67], v[46:49] offset:256
	s_nop 1
	v_lshl_add_u64 v[46:47], v[66:67], 0, s[12:13]
	v_pk_mul_f32 v[48:49], v[52:53], v[138:139] op_sel_hi:[1,0]
	v_pk_mul_f32 v[52:53], v[44:45], v[138:139] op_sel_hi:[1,0]
	v_pk_mul_f32 v[44:45], v[42:43], v[138:139] op_sel_hi:[1,0]
	v_cvt_pk_bf16_f32 v42, v50, v51
	v_cvt_pk_bf16_f32 v43, v48, v49
	s_nop 0
	v_cvt_pk_bf16_f32 v44, v44, v45
	v_cvt_pk_bf16_f32 v45, v52, v53
	flat_store_dwordx4 v[46:47], v[42:45]
	s_nop 1
	v_pk_mul_f32 v[42:43], v[32:33], v[138:139] op_sel_hi:[1,0]
	v_pk_mul_f32 v[32:33], v[30:31], v[138:139] op_sel_hi:[1,0]
	v_cvt_pk_bf16_f32 v30, v38, v39
	v_cvt_pk_bf16_f32 v31, v40, v41
	s_nop 0
	v_cvt_pk_bf16_f32 v32, v32, v33
	v_cvt_pk_bf16_f32 v33, v42, v43
	flat_store_dwordx4 v[46:47], v[30:33] offset:256
	s_nop 1
	v_lshl_add_u64 v[30:31], v[46:47], 0, s[12:13]
	v_pk_mul_f32 v[32:33], v[36:37], v[134:135] op_sel_hi:[1,0]
	v_pk_mul_f32 v[36:37], v[28:29], v[134:135] op_sel_hi:[1,0]
	v_pk_mul_f32 v[28:29], v[26:27], v[134:135] op_sel_hi:[1,0]
	v_cvt_pk_bf16_f32 v26, v34, v35
	v_cvt_pk_bf16_f32 v27, v32, v33
	s_nop 0
	v_cvt_pk_bf16_f32 v28, v28, v29
	v_cvt_pk_bf16_f32 v29, v36, v37
	flat_store_dwordx4 v[30:31], v[26:29]
	s_nop 1
	v_pk_mul_f32 v[26:27], v[16:17], v[134:135] op_sel_hi:[1,0]
	v_pk_mul_f32 v[16:17], v[14:15], v[134:135] op_sel_hi:[1,0]
	v_cvt_pk_bf16_f32 v14, v22, v23
	v_cvt_pk_bf16_f32 v15, v24, v25
	s_nop 0
	v_cvt_pk_bf16_f32 v16, v16, v17
	v_cvt_pk_bf16_f32 v17, v26, v27
	flat_store_dwordx4 v[30:31], v[14:17] offset:256
	s_nop 1
	v_lshl_add_u64 v[14:15], v[30:31], 0, s[12:13]
	v_pk_mul_f32 v[16:17], v[20:21], v[130:131] op_sel_hi:[1,0]
	v_pk_mul_f32 v[20:21], v[12:13], v[130:131] op_sel_hi:[1,0]
	v_pk_mul_f32 v[12:13], v[10:11], v[130:131] op_sel_hi:[1,0]
	v_cvt_pk_bf16_f32 v10, v18, v19
	v_cvt_pk_bf16_f32 v11, v16, v17
	s_nop 0
	v_cvt_pk_bf16_f32 v12, v12, v13
	v_cvt_pk_bf16_f32 v13, v20, v21
	flat_store_dwordx4 v[14:15], v[10:13]
	s_nop 1
	v_pk_mul_f32 v[10:11], v[4:5], v[130:131] op_sel_hi:[1,0]
	v_pk_mul_f32 v[4:5], v[2:3], v[130:131] op_sel_hi:[1,0]
	v_cvt_pk_bf16_f32 v2, v6, v7
	v_cvt_pk_bf16_f32 v3, v8, v9
	s_nop 0
	v_cvt_pk_bf16_f32 v4, v4, v5
	v_cvt_pk_bf16_f32 v5, v10, v11
	flat_store_dwordx4 v[14:15], v[2:5] offset:256
	s_nop 1
	v_lshl_add_u64 v[2:3], v[14:15], 0, s[12:13]
	s_nop 0
	v_lshl_add_u64 v[2:3], v[2:3], 0, s[0:1]
	s_mov_b64 s[0:1], -1
	s_cbranch_vccnz .LBB0_1116
	s_andn2_b64 vcc, exec, s[4:5]
	s_cbranch_vccnz .LBB0_1115
	s_barrier
	s_branch .LBB0_1115

; __device__ __forceinline__ void load_row_scales(const float* ssp, int row0, int fq, float (&rs)[2][4]) {
;     f32x4 part[2][4];
;     const float* sp = ssp + (size_t)row0 * 16 + 4 * fq;
; #pragma unroll
;     for (int ai = 0; ai < 2; ++ai)
; #pragma unroll
;         for (int m = 0; m < 4; ++m) part[ai][m] = *(const f32x4*)(sp + (size_t)(ai * HALF + m * 16) * 16);
; #pragma unroll
;     for (int ai = 0; ai < 2; ++ai)
; #pragma unroll
;         for (int m = 0; m < 4; ++m) { float t = (part[ai][m][0] + part[ai][m][1]) + (part[ai][m][2] + part[ai][m][3]);
;             t += __shfl_xor(t, 16); t += __shfl_xor(t, 32);
;             rs[ai][m] = 1.0f / sqrtf(t * (1.0f / 1024.0f) + 1e-6f); }
;     __device__ __forceinline__ void operator()(f32x4 (&acc)[2][2][4][2], const Unit& u, int wr, int wc, int fr, int fq) const {
;     ...
;         const int row0 = u.pm * BM + wr * 64 + fr;
;         { float rs[2][4]; load_row_scales(ssp, row0, fq, rs);
.LBB0_1350:
	s_lshl_b32 s13, s13, 8
	s_add_i32 s13, s13, s24
	v_or_b32_e32 v176, s13, v161
	v_ashrrev_i32_e32 v177, 31, v176
	v_lshlrev_b64 v[130:131], 6, v[176:177]
	v_lshl_add_u64 v[146:147], v[162:163], 0, v[130:131]
	global_load_dwordx4 v[130:133], v[146:147], off
	global_load_dwordx4 v[134:137], v[146:147], off offset:1024
	global_load_dwordx4 v[138:141], v[146:147], off offset:2048
	global_load_dwordx4 v[142:145], v[146:147], off offset:3072
	v_add_co_u32_e32 v168, vcc, 0x2000, v146
	v_mov_b32_e32 v177, v1
	s_nop 0
	v_addc_co_u32_e32 v169, vcc, 0, v147, vcc
	global_load_dwordx4 v[146:149], v[168:169], off
	global_load_dwordx4 v[150:153], v[168:169], off offset:1024
	global_load_dwordx4 v[170:173], v[168:169], off offset:2048
	global_load_dwordx4 v[178:181], v[168:169], off offset:3072
	v_and_b32_e32 v169, 64, v229
	v_xor_b32_e32 v168, 16, v229
	v_add_u32_e32 v169, 64, v169
	v_cmp_lt_i32_e32 vcc, v168, v169
	v_mov_b32_dpp v177, v177 row_ror:1 row_mask:0xf bank_mask:0xf
	v_mov_b32_e32 v189, v177
	v_cndmask_b32_e32 v168, v229, v168, vcc
	v_lshlrev_b32_e32 v174, 2, v168
	v_xor_b32_e32 v168, 32, v229
	v_cmp_lt_i32_e32 vcc, v168, v169
	s_waitcnt vmcnt(0)
	v_mov_b32_e32 v169, v132
	v_cndmask_b32_e32 v168, v229, v168, vcc
	v_lshlrev_b32_e32 v175, 2, v168
	v_mov_b32_e32 v168, v131
	v_mov_b32_e32 v131, v133
	v_pk_add_f32 v[130:131], v[168:169], v[130:131]
	s_nop 0
	v_add_f32_e32 v130, v130, v131
	ds_bpermute_b32 v131, v174, v130
	s_waitcnt lgkmcnt(0)
	v_add_f32_e32 v130, v130, v131
	ds_bpermute_b32 v131, v175, v130
	s_waitcnt lgkmcnt(0)
	v_add_f32_e32 v130, v130, v131
	v_fmamk_f32 v130, v130, 0x3a800000, v230
	s_ashr_i32 s0, s13, 5
	v_rsq_f32_e32 v168, v130
	s_nop 0
	v_mov_b32_e32 v130, v135
	v_mov_b32_e32 v131, v136
	v_mov_b32_e32 v135, v137
	v_pk_add_f32 v[130:131], v[130:131], v[134:135]
	s_nop 0
	v_add_f32_e32 v130, v130, v131
	ds_bpermute_b32 v131, v174, v130
	s_waitcnt lgkmcnt(0)
	v_add_f32_e32 v205, v130, v131
	v_mov_b32_e32 v130, v139
	v_mov_b32_e32 v131, v140
	v_mov_b32_e32 v139, v141
	v_pk_add_f32 v[130:131], v[130:131], v[138:139]
	ds_bpermute_b32 v206, v175, v205
	v_add_f32_e32 v130, v130, v131
	ds_bpermute_b32 v131, v174, v130
	s_waitcnt lgkmcnt(0)
	v_add_f32_e32 v203, v130, v131
	v_mov_b32_e32 v130, v143
	v_mov_b32_e32 v131, v144
	v_mov_b32_e32 v143, v145
	v_pk_add_f32 v[130:131], v[130:131], v[142:143]
	ds_bpermute_b32 v204, v175, v203
	v_add_f32_e32 v130, v130, v131
	ds_bpermute_b32 v131, v174, v130
	s_waitcnt lgkmcnt(0)
	v_add_f32_e32 v182, v130, v131
	v_mov_b32_e32 v130, v147
	v_mov_b32_e32 v131, v148
	v_mov_b32_e32 v147, v149
	v_pk_add_f32 v[130:131], v[130:131], v[146:147]
	ds_bpermute_b32 v202, v175, v182
	v_add_f32_e32 v130, v130, v131
	ds_bpermute_b32 v131, v174, v130
	s_waitcnt lgkmcnt(0)
	v_add_f32_e32 v244, v130, v131
	v_mov_b32_e32 v130, v151
	v_mov_b32_e32 v131, v152
	v_mov_b32_e32 v151, v153
	v_pk_add_f32 v[130:131], v[130:131], v[150:151]
	ds_bpermute_b32 v245, v175, v244
	v_add_f32_e32 v130, v130, v131
	ds_bpermute_b32 v131, v174, v130
	s_waitcnt lgkmcnt(0)
	v_add_f32_e32 v242, v130, v131
	v_mov_b32_e32 v130, v171
	v_mov_b32_e32 v131, v172
	v_mov_b32_e32 v171, v173
	v_pk_add_f32 v[130:131], v[130:131], v[170:171]
	v_lshl_or_b32 v170, s12, 7, v238
	v_add_f32_e32 v130, v130, v131
	ds_bpermute_b32 v131, v174, v130
	v_ashrrev_i32_e32 v171, 31, v170
	v_lshlrev_b64 v[150:151], 2, v[170:171]
	v_lshl_add_u64 v[172:173], s[70:71], 0, v[150:151]
	ds_bpermute_b32 v243, v175, v242
	s_waitcnt lgkmcnt(1)
	v_add_f32_e32 v240, v130, v131
	v_mov_b32_e32 v130, v179
	v_mov_b32_e32 v131, v180
	v_mov_b32_e32 v179, v181
	v_pk_add_f32 v[130:131], v[130:131], v[178:179]
	ds_bpermute_b32 v241, v175, v240
	v_add_f32_e32 v130, v130, v131
	ds_bpermute_b32 v131, v174, v130
	v_lshlrev_b64 v[178:179], 1, v[170:171]
	s_waitcnt lgkmcnt(0)
;     __device__ __forceinline__ void operator()(f32x4 (&acc)[2][2][4][2], const Unit& u, int wr, int wc, int fr, int fq) const {
;     ...
;         for (int n = 0; n < 2; ++n) {
;             const int gc0 = u.pn * 128 + wc * 32 + 8 * fq + 4 * n;
;             const float* cwp = cw + gc0; asm volatile("" : "+v"(cwp));
;             const f32x4 wg0 = *(const f32x4*)(cwp), wg1 = *(const f32x4*)(cwp + FF2c), wg2 = *(const f32x4*)(cwp + 2 * FF2c);
;             const f32x4 wv0 = *(const f32x4*)(cwp + FFc), wv1 = *(const f32x4*)(cwp + FF2c + FFc), wv2 = *(const f32x4*)(cwp + 2 * FF2c + FFc);
;             const f32x4 bg = *(const f32x4*)(cb + gc0), bv = *(const f32x4*)(cb + FFc + gc0);
;             bf16_t* gp = G + (size_t)row0 * FFc + gc0;
;             bf16_t* sb = Fb + ((size_t)(row0 >> 6) * 2 + (fr & 1)) * FF2c + gc0;
;             bf16_t* hb = Hb + ((size_t)(row0 >> 6) * 2 + (fr & 1)) * FF2c + gc0;
; #pragma unroll
;             for (int ai = 0; ai < 2; ++ai) {
; #pragma unroll
;                 for (int m = 0; m < 4; ++m) {
;                     float og[4];
; #pragma unroll
;                     for (int j = 0; j < 4; ++j) {
;                         const float vg = acc[ai][0][m][n][j], vv = acc[ai][1][m][n][j];
;                         const float pg = (m > 0) ? acc[ai][0][m - 1][n][j] : 0.f, pv = (m > 0) ? acc[ai][1][m - 1][n][j] : 0.f;
;                         const float g1 = dppf(dppf(0.f, pg, 2), vg, 0), g2 = dppf(dppf(0.f, pg, 3), vg, 1);
;                         const float v1 = dppf(dppf(0.f, pv, 2), vv, 0), v2 = dppf(dppf(0.f, pv, 3), vv, 1);
;                         const float cgate = bg[j] + wg0[j] * g2 + wg1[j] * g1 + wg2[j] * vg;
;                         const float cval = bv[j] + wv0[j] * v2 + wv1[j] * v1 + wv2[j] * vv;
;                         og[j] = cgate * __builtin_amdgcn_rcpf(1.0f + __builtin_amdgcn_exp2f(-1.4426950408889634f * cgate)) * cval; }
;                     const unsigned long long w = (unsigned long long)cvt_pk_bf16(og[0], og[1]) | ((unsigned long long)cvt_pk_bf16(og[2], og[3]) << 32);
;                     if (m == 0) {
;                         if (fr >= 2) *(unsigned long long*)gp = w;
;                         else { *(unsigned long long*)sb = (unsigned long long)cvt_pk_bf16(acc[ai][0][0][n][0], acc[ai][0][0][n][1]) | ((unsigned long long)cvt_pk_bf16(acc[ai][0][0][n][2], acc[ai][0][0][n][3]) << 32);
	v_add_f32_e32 v169, v130, v131
	v_pk_mul_f32 v[196:197], v[98:99], v[168:169] op_sel_hi:[1,0]
	v_or_b32_e32 v98, s0, v160
	v_mad_i64_i32 v[200:201], s[0:1], v98, s37, 0
	v_pk_mul_f32 v[198:199], v[102:103], v[168:169] op_sel_hi:[1,0]
	v_mov_b64_e32 v[102:103], v[172:173]
	s_movk_i32 s0, 0x5000
	ds_bpermute_b32 v183, v175, v169
	v_add_co_u32_e32 v98, vcc, s0, v102
	s_mov_b32 s0, 0xb000
	s_nop 0
	v_addc_co_u32_e32 v99, vcc, 0, v103, vcc
	flat_load_dwordx4 v[142:145], v[98:99] offset:2048
	v_add_co_u32_e32 v98, vcc, s0, v102
	s_movk_i32 s0, 0x2000
	s_nop 0
	v_addc_co_u32_e32 v99, vcc, 0, v103, vcc
	v_pk_mul_f32 v[194:195], v[104:105], v[168:169] op_sel_hi:[1,0]
	v_add_co_u32_e32 v104, vcc, s0, v102
	v_lshl_add_u64 v[174:175], s[72:73], 0, v[150:151]
	flat_load_dwordx4 v[138:141], v[102:103]
	v_addc_co_u32_e32 v105, vcc, 0, v103, vcc
	s_mov_b32 s0, 0x8000
	global_load_dwordx4 v[146:149], v[174:175], off
	flat_load_dwordx4 v[130:133], v[104:105] offset:3072
	v_add_co_u32_e32 v104, vcc, s0, v102
	v_lshl_add_u64 v[150:151], s[76:77], 0, v[150:151]
	v_pk_mul_f32 v[192:193], v[100:101], v[168:169] op_sel_hi:[1,0]
	flat_load_dwordx4 v[98:101], v[98:99]
	v_addc_co_u32_e32 v105, vcc, 0, v103, vcc
	global_load_dwordx4 v[150:153], v[150:151], off
	s_mov_b32 s0, 0xd000
	flat_load_dwordx4 v[134:137], v[104:105] offset:1024
	v_add_co_u32_e32 v102, vcc, s0, v102
	v_readlane_b32 s0, v253, 44
	s_nop 0
	v_addc_co_u32_e32 v103, vcc, 0, v103, vcc
	flat_load_dwordx4 v[102:105], v[102:103] offset:3072
	v_readlane_b32 s1, v253, 45
	v_mov_b32_dpp v189, v196 row_shr:1 row_mask:0xf bank_mask:0xf
	s_nop 0
	v_lshl_add_u64 v[180:181], v[200:201], 1, s[0:1]
	v_lshl_add_u64 v[184:185], v[180:181], 0, v[178:179]
	v_mov_b32_e32 v181, v1
	v_mov_b32_e32 v180, v177
	s_nop 0
	v_mov_b32_dpp v181, v181 row_ror:2 row_mask:0xf bank_mask:0xf
	v_mov_b32_e32 v188, v181
	v_mov_b32_dpp v180, v198 row_shr:1 row_mask:0xf bank_mask:0xf
	v_mov_b32_e32 v190, v181
	v_mov_b32_dpp v188, v198 row_shr:2 row_mask:0xf bank_mask:0xf
	v_mov_b32_e32 v191, v181
	v_mov_b32_dpp v190, v196 row_shr:2 row_mask:0xf bank_mask:0xf
	v_mov_b32_e32 v207, v181
	v_mov_b32_dpp v191, v197 row_shr:2 row_mask:0xf bank_mask:0xf
	s_waitcnt vmcnt(0) lgkmcnt(0)
	v_fma_f32 v188, v138, v188, v146
	v_fmac_f32_e32 v188, v142, v180
	v_mov_b32_dpp v207, v192 row_shr:2 row_mask:0xf bank_mask:0xf
	v_fmac_f32_e32 v188, v198, v98
	v_fma_f32 v180, v130, v190, v150
	v_mov_b32_e32 v190, v177
	v_fmac_f32_e32 v180, v134, v189
	v_mul_f32_e32 v189, 0xbfb8aa3b, v188
	v_exp_f32_e32 v189, v189
	v_mov_b32_dpp v190, v197 row_shr:1 row_mask:0xf bank_mask:0xf
	v_add_f32_e32 v189, 1.0, v189
	v_rcp_f32_e32 v189, v189
	v_fmac_f32_e32 v180, v196, v102
	v_mul_f32_e32 v188, v188, v189
	v_mov_b32_e32 v189, v181
	v_mul_f32_e32 v180, v180, v188
	v_mov_b32_e32 v188, v177
	v_mov_b32_dpp v189, v199 row_shr:2 row_mask:0xf bank_mask:0xf
	v_fma_f32 v189, v139, v189, v147
	v_mov_b32_dpp v188, v199 row_shr:1 row_mask:0xf bank_mask:0xf
	v_fmac_f32_e32 v189, v143, v188
	v_fmac_f32_e32 v189, v199, v99
	v_fma_f32 v188, v131, v191, v151
	v_fmac_f32_e32 v188, v135, v190
	v_mul_f32_e32 v190, 0xbfb8aa3b, v189
	v_exp_f32_e32 v190, v190
	v_fmac_f32_e32 v188, v197, v103
	v_mov_b32_e32 v191, v177
	v_add_f32_e32 v190, 1.0, v190
	v_rcp_f32_e32 v190, v190
	v_mov_b32_dpp v191, v192 row_shr:1 row_mask:0xf bank_mask:0xf
	v_mul_f32_e32 v189, v189, v190
	v_mov_b32_e32 v190, v181
	v_mul_f32_e32 v188, v188, v189
	v_mov_b32_e32 v189, v177
	v_mov_b32_dpp v190, v194 row_shr:2 row_mask:0xf bank_mask:0xf
	v_fma_f32 v190, v140, v190, v148
	v_mov_b32_dpp v189, v194 row_shr:1 row_mask:0xf bank_mask:0xf
	v_fmac_f32_e32 v190, v144, v189
	v_fmac_f32_e32 v190, v194, v100
	v_fma_f32 v189, v132, v207, v152
	v_fmac_f32_e32 v189, v136, v191
	v_mul_f32_e32 v191, 0xbfb8aa3b, v190
	v_exp_f32_e32 v191, v191
	v_fmac_f32_e32 v189, v192, v104
	v_cvt_pk_bf16_f32 v180, v180, v188
	v_add_f32_e32 v191, 1.0, v191
	v_rcp_f32_e32 v191, v191
	s_nop 0
	v_mul_f32_e32 v190, v190, v191
	v_mov_b32_e32 v191, v181
	v_mul_f32_e32 v189, v189, v190
	v_mov_b32_e32 v190, v177
	v_mov_b32_dpp v191, v195 row_shr:2 row_mask:0xf bank_mask:0xf
	v_fma_f32 v191, v141, v191, v149
	v_mov_b32_dpp v190, v195 row_shr:1 row_mask:0xf bank_mask:0xf
	v_mov_b32_dpp v181, v193 row_shr:2 row_mask:0xf bank_mask:0xf
	v_fmac_f32_e32 v191, v145, v190
	v_mov_b32_dpp v177, v193 row_shr:1 row_mask:0xf bank_mask:0xf
	v_fmac_f32_e32 v191, v195, v101
	v_fma_f32 v181, v133, v181, v153
	v_fmac_f32_e32 v181, v137, v177
	v_mul_f32_e32 v177, 0xbfb8aa3b, v191
	v_exp_f32_e32 v177, v177
	v_fmac_f32_e32 v181, v193, v105
	v_add_f32_e32 v177, 1.0, v177
	v_rcp_f32_e32 v177, v177
	s_nop 0
	v_mul_f32_e32 v177, v191, v177
	v_mul_f32_e32 v177, v181, v177
	v_cvt_pk_bf16_f32 v181, v189, v177
	s_and_saveexec_b64 s[0:1], s[6:7]
	s_xor_b64 s[0:1], exec, s[0:1]
	s_mov_b64 s[50:51], 0x16000
	s_mov_b64 s[52:53], 0x58000
	s_mov_b64 s[54:55], 0xb000
	s_cbranch_execz .LBB0_1352
	v_cvt_pk_bf16_f32 v180, v198, v199
	v_cvt_pk_bf16_f32 v181, v194, v195
	v_add_co_u32_e32 v188, vcc, 0x1000, v184
	global_store_dwordx2 v[184:185], v[180:181], off
	v_cvt_pk_bf16_f32 v180, v196, v197
	v_cvt_pk_bf16_f32 v181, v192, v193
	s_nop 0
	v_addc_co_u32_e32 v189, vcc, 0, v185, vcc
	global_store_dwordx2 v[188:189], v[180:181], off offset:1536

; __device__ __forceinline__ void load_row_scales(const float* ssp, int row0, int fq, float (&rs)[2][4]) {
;     ...
;             rs[ai][m] = 1.0f / sqrtf(t * (1.0f / 1024.0f) + 1e-6f); }
;     __device__ __forceinline__ void operator()(f32x4 (&acc)[2][2][4][2], const Unit& u, int wr, int wc, int fr, int fq) const {
;     ...
;                       for (int n = 0; n < 2; ++n) acc[ai][bj][m][n] = acc[ai][bj][m][n] * rs[ai][m]; }
;     ...
;                 for (int m = 0; m < 4; ++m) {
;                     float og[4];
; #pragma unroll
;                     for (int j = 0; j < 4; ++j) {
;                         const float vg = acc[ai][0][m][n][j], vv = acc[ai][1][m][n][j];
;                         const float pg = (m > 0) ? acc[ai][0][m - 1][n][j] : 0.f, pv = (m > 0) ? acc[ai][1][m - 1][n][j] : 0.f;
;                         const float g1 = dppf(dppf(0.f, pg, 2), vg, 0), g2 = dppf(dppf(0.f, pg, 3), vg, 1);
;                         const float v1 = dppf(dppf(0.f, pv, 2), vv, 0), v2 = dppf(dppf(0.f, pv, 3), vv, 1);
;                         const float cgate = bg[j] + wg0[j] * g2 + wg1[j] * g1 + wg2[j] * vg;
;                         const float cval = bv[j] + wv0[j] * v2 + wv1[j] * v1 + wv2[j] * vv;
;                         og[j] = cgate * __builtin_amdgcn_rcpf(1.0f + __builtin_amdgcn_exp2f(-1.4426950408889634f * cgate)) * cval; }
;                     const unsigned long long w = (unsigned long long)cvt_pk_bf16(og[0], og[1]) | ((unsigned long long)cvt_pk_bf16(og[2], og[3]) << 32);
;                     if (m == 0) {
;                         if (fr >= 2) *(unsigned long long*)gp = w;
;                         else { *(unsigned long long*)sb = (unsigned long long)cvt_pk_bf16(acc[ai][0][0][n][0], acc[ai][0][0][n][1]) | ((unsigned long long)cvt_pk_bf16(acc[ai][0][0][n][2], acc[ai][0][0][n][3]) << 32);
;                                *(unsigned long long*)(sb + FFc) = (unsigned long long)cvt_pk_bf16(acc[ai][1][0][n][0], acc[ai][1][0][n][1]) | ((unsigned long long)cvt_pk_bf16(acc[ai][1][0][n][2], acc[ai][1][0][n][3]) << 32); }
;                     } else *(unsigned long long*)gp = w;
;                     if (m == 3 && fr >= 14) {
;                         *(unsigned long long*)hb = (unsigned long long)cvt_pk_bf16(acc[ai][0][3][n][0], acc[ai][0][3][n][1]) | ((unsigned long long)cvt_pk_bf16(acc[ai][0][3][n][2], acc[ai][0][3][n][3]) << 32);
.LBB0_1354:
	s_or_b64 exec, exec, s[0:1]
	v_add_f32_e32 v178, v205, v206
	v_fmamk_f32 v178, v178, 0x3a800000, v230
	v_mov_b32_e32 v191, v1
	s_nop 1
	v_mov_b32_dpp v191, v194 row_ror:2 row_mask:0xf bank_mask:0xf
	v_lshl_add_u64 v[226:227], v[176:177], 0, s[50:51]
	v_rsq_f32_e32 v178, v178
	s_nop 0
	v_add_f32_e32 v179, v203, v204
	v_fmamk_f32 v179, v179, 0x3a800000, v230
	v_mov_b32_e32 v203, v101
	v_rsq_f32_e32 v180, v179
	s_nop 0
	v_add_f32_e32 v179, v182, v202
	v_fmamk_f32 v179, v179, 0x3a800000, v230
	v_mov_b32_e32 v202, v105
	v_pk_mul_f32 v[224:225], v[126:127], v[178:179] op_sel_hi:[1,0]
	v_pk_mul_f32 v[222:223], v[118:119], v[178:179] op_sel_hi:[1,0]
	v_pk_mul_f32 v[218:219], v[120:121], v[178:179] op_sel_hi:[1,0]
	v_rsq_f32_e32 v182, v179
	s_nop 0
	v_pk_mul_f32 v[208:209], v[114:115], v[182:183] op_sel_hi:[1,0]
	v_mov_b32_e32 v115, v1
	v_mov_b32_e32 v114, v1
	v_pk_mul_f32 v[206:207], v[116:117], v[182:183] op_sel_hi:[1,0]
	v_mov_b32_e32 v117, v1
	v_mov_b32_dpp v115, v198 row_ror:2 row_mask:0xf bank_mask:0xf
	v_mov_b32_e32 v116, v1
	v_mov_b32_dpp v114, v196 row_ror:2 row_mask:0xf bank_mask:0xf
	v_pk_mul_f32 v[210:211], v[112:113], v[180:181] op_sel_hi:[1,0]
	v_pk_mul_f32 v[214:215], v[110:111], v[180:181] op_sel_hi:[1,0]
	v_mov_b32_dpp v117, v198 row_ror:1 row_mask:0xf bank_mask:0xf
	v_mov_b32_dpp v115, v224 row_shr:2 row_mask:0xf bank_mask:0xf
	v_mov_b32_dpp v116, v196 row_ror:1 row_mask:0xf bank_mask:0xf
	v_mov_b32_dpp v114, v222 row_shr:2 row_mask:0xf bank_mask:0xf
	v_mov_b32_e32 v110, v130
	v_mov_b32_e32 v111, v138
	v_mov_b32_e32 v112, v150
	v_mov_b32_e32 v113, v146
	v_mov_b32_dpp v117, v224 row_shr:1 row_mask:0xf bank_mask:0xf
	v_mov_b32_dpp v116, v222 row_shr:1 row_mask:0xf bank_mask:0xf
	v_pk_fma_f32 v[118:119], v[110:111], v[114:115], v[112:113]
	v_mov_b32_e32 v114, v134
	v_mov_b32_e32 v115, v142
	v_pk_fma_f32 v[118:119], v[114:115], v[116:117], v[118:119]
	v_mov_b32_e32 v120, v222
	v_mov_b32_e32 v121, v224
	v_mov_b32_e32 v116, v102
	v_mov_b32_e32 v117, v98
	v_pk_fma_f32 v[118:119], v[120:121], v[116:117], v[118:119]
	v_readlane_b32 s0, v253, 46
	v_mul_f32_e32 v120, 0xbfb8aa3b, v119
	v_exp_f32_e32 v120, v120
	v_pk_mul_f32 v[216:217], v[122:123], v[180:181] op_sel_hi:[1,0]
	v_readlane_b32 s1, v253, 47
	v_mov_b32_e32 v123, v1
	v_add_f32_e32 v120, 1.0, v120
	v_rcp_f32_e32 v120, v120
	v_mov_b32_e32 v122, v1
	v_pk_mul_f32 v[212:213], v[124:125], v[180:181] op_sel_hi:[1,0]
	v_pk_mul_f32 v[204:205], v[108:109], v[182:183] op_sel_hi:[1,0]
	v_lshl_add_u64 v[108:109], v[200:201], 1, s[0:1]
	v_mul_f32_e32 v119, v119, v120
	v_mov_b32_e32 v125, v1
	v_mov_b32_dpp v123, v199 row_ror:2 row_mask:0xf bank_mask:0xf
	v_mov_b32_e32 v124, v1
	v_mov_b32_dpp v122, v197 row_ror:2 row_mask:0xf bank_mask:0xf
	v_lshl_add_u64 v[108:109], v[170:171], 1, v[108:109]
	v_mul_f32_e32 v171, v118, v119
	v_mov_b32_dpp v125, v199 row_ror:1 row_mask:0xf bank_mask:0xf
	v_mov_b32_dpp v123, v225 row_shr:2 row_mask:0xf bank_mask:0xf
	v_mov_b32_dpp v124, v197 row_ror:1 row_mask:0xf bank_mask:0xf
	v_mov_b32_dpp v122, v223 row_shr:2 row_mask:0xf bank_mask:0xf
	v_mov_b32_e32 v118, v131
	v_mov_b32_e32 v119, v139
	v_mov_b32_e32 v120, v151
	v_mov_b32_e32 v121, v147
	v_mov_b32_dpp v125, v225 row_shr:1 row_mask:0xf bank_mask:0xf
	v_mov_b32_dpp v124, v223 row_shr:1 row_mask:0xf bank_mask:0xf
	v_pk_fma_f32 v[126:127], v[118:119], v[122:123], v[120:121]
	v_mov_b32_e32 v122, v135
	v_mov_b32_e32 v123, v143
	v_pk_mul_f32 v[220:221], v[128:129], v[178:179] op_sel_hi:[1,0]
	v_pk_fma_f32 v[126:127], v[122:123], v[124:125], v[126:127]
	v_mov_b32_e32 v128, v223
	v_mov_b32_e32 v129, v225
	v_mov_b32_e32 v124, v103
	v_mov_b32_e32 v125, v99
	v_pk_fma_f32 v[126:127], v[128:129], v[124:125], v[126:127]
	v_mov_b32_e32 v190, v1
	v_mul_f32_e32 v128, 0xbfb8aa3b, v127
	v_exp_f32_e32 v128, v128
	v_mov_b32_e32 v189, v1
	v_mov_b32_e32 v188, v1
	v_mov_b32_dpp v190, v192 row_ror:2 row_mask:0xf bank_mask:0xf
	v_add_f32_e32 v128, 1.0, v128
	v_rcp_f32_e32 v128, v128
	v_mov_b32_dpp v189, v194 row_ror:1 row_mask:0xf bank_mask:0xf
	v_mov_b32_dpp v191, v220 row_shr:2 row_mask:0xf bank_mask:0xf
	v_mov_b32_dpp v188, v192 row_ror:1 row_mask:0xf bank_mask:0xf
	v_mul_f32_e32 v127, v127, v128
	v_mul_f32_e32 v179, v126, v127
	v_mov_b32_dpp v190, v218 row_shr:2 row_mask:0xf bank_mask:0xf
	v_mov_b32_e32 v126, v132
	v_mov_b32_e32 v127, v140
	v_mov_b32_e32 v128, v152
	v_mov_b32_e32 v129, v148
	v_mov_b32_dpp v189, v220 row_shr:1 row_mask:0xf bank_mask:0xf
	v_mov_b32_dpp v188, v218 row_shr:1 row_mask:0xf bank_mask:0xf
	v_pk_fma_f32 v[190:191], v[126:127], v[190:191], v[128:129]
	v_mov_b32_e32 v196, v136
	v_mov_b32_e32 v197, v144
	v_pk_fma_f32 v[188:189], v[196:197], v[188:189], v[190:191]
	v_mov_b32_e32 v190, v218
	v_mov_b32_e32 v191, v220
	v_mov_b32_e32 v198, v104
	v_mov_b32_e32 v199, v100
	v_pk_fma_f32 v[188:189], v[190:191], v[198:199], v[188:189]
	v_mov_b32_e32 v191, v1
	v_mul_f32_e32 v181, 0xbfb8aa3b, v189
	v_exp_f32_e32 v181, v181
	v_mov_b32_e32 v190, v1
	v_mov_b32_dpp v191, v195 row_ror:2 row_mask:0xf bank_mask:0xf
	v_mov_b32_e32 v192, v133
	v_add_f32_e32 v181, 1.0, v181
	v_rcp_f32_e32 v181, v181
	v_mov_b32_dpp v190, v193 row_ror:2 row_mask:0xf bank_mask:0xf
	v_mov_b32_dpp v191, v221 row_shr:2 row_mask:0xf bank_mask:0xf
	v_mov_b32_e32 v194, v153
	v_mul_f32_e32 v181, v189, v181
	v_mul_f32_e32 v181, v188, v181
	v_mov_b32_e32 v189, v1
	v_mov_b32_e32 v188, v1
	v_mov_b32_dpp v190, v219 row_shr:2 row_mask:0xf bank_mask:0xf
	v_mov_b32_dpp v189, v195 row_ror:1 row_mask:0xf bank_mask:0xf
	v_mov_b32_dpp v188, v193 row_ror:1 row_mask:0xf bank_mask:0xf
	v_mov_b32_e32 v193, v141
	v_mov_b32_e32 v195, v149
;     __device__ __forceinline__ void operator()(f32x4 (&acc)[2][2][4][2], const Unit& u, int wr, int wc, int fr, int fq) const {
;     ...
;                 for (int m = 0; m < 4; ++m) {
;                     float og[4];
; #pragma unroll
;                     for (int j = 0; j < 4; ++j) {
;                         const float vg = acc[ai][0][m][n][j], vv = acc[ai][1][m][n][j];
;                         const float pg = (m > 0) ? acc[ai][0][m - 1][n][j] : 0.f, pv = (m > 0) ? acc[ai][1][m - 1][n][j] : 0.f;
;                         const float g1 = dppf(dppf(0.f, pg, 2), vg, 0), g2 = dppf(dppf(0.f, pg, 3), vg, 1);
;                         const float v1 = dppf(dppf(0.f, pv, 2), vv, 0), v2 = dppf(dppf(0.f, pv, 3), vv, 1);
;                         const float cgate = bg[j] + wg0[j] * g2 + wg1[j] * g1 + wg2[j] * vg;
;                         const float cval = bv[j] + wv0[j] * v2 + wv1[j] * v1 + wv2[j] * vv;
;                         og[j] = cgate * __builtin_amdgcn_rcpf(1.0f + __builtin_amdgcn_exp2f(-1.4426950408889634f * cgate)) * cval; }
;                     const unsigned long long w = (unsigned long long)cvt_pk_bf16(og[0], og[1]) | ((unsigned long long)cvt_pk_bf16(og[2], og[3]) << 32);
;                     if (m == 0) {
;                         if (fr >= 2) *(unsigned long long*)gp = w;
;                         else { *(unsigned long long*)sb = (unsigned long long)cvt_pk_bf16(acc[ai][0][0][n][0], acc[ai][0][0][n][1]) | ((unsigned long long)cvt_pk_bf16(acc[ai][0][0][n][2], acc[ai][0][0][n][3]) << 32);
;                                *(unsigned long long*)(sb + FFc) = (unsigned long long)cvt_pk_bf16(acc[ai][1][0][n][0], acc[ai][1][0][n][1]) | ((unsigned long long)cvt_pk_bf16(acc[ai][1][0][n][2], acc[ai][1][0][n][3]) << 32); }
;                     } else *(unsigned long long*)gp = w;
;                     if (m == 3 && fr >= 14) {
;                         *(unsigned long long*)hb = (unsigned long long)cvt_pk_bf16(acc[ai][0][3][n][0], acc[ai][0][3][n][1]) | ((unsigned long long)cvt_pk_bf16(acc[ai][0][3][n][2], acc[ai][0][3][n][3]) << 32);
;                         *(unsigned long long*)(hb + FFc) = (unsigned long long)cvt_pk_bf16(acc[ai][1][3][n][0], acc[ai][1][3][n][1]) | ((unsigned long long)cvt_pk_bf16(acc[ai][1][3][n][2], acc[ai][1][3][n][3]) << 32); }
;                     gp += (size_t)16 * FFc; asm volatile("" : "+v"(gp) :: "memory"); }
	v_mov_b32_dpp v189, v221 row_shr:1 row_mask:0xf bank_mask:0xf
	v_mov_b32_dpp v188, v219 row_shr:1 row_mask:0xf bank_mask:0xf
	v_pk_fma_f32 v[190:191], v[192:193], v[190:191], v[194:195]
	v_mov_b32_e32 v200, v137
	v_mov_b32_e32 v201, v145
	v_pk_fma_f32 v[188:189], v[200:201], v[188:189], v[190:191]
	v_mov_b32_e32 v190, v219
	v_mov_b32_e32 v191, v221
	v_pk_fma_f32 v[188:189], v[190:191], v[202:203], v[188:189]
	v_mov_b32_e32 v191, v1
	v_mul_f32_e32 v190, 0xbfb8aa3b, v189
	v_exp_f32_e32 v190, v190
	v_mov_b32_dpp v191, v224 row_ror:1 row_mask:0xf bank_mask:0xf
	v_pk_mul_f32 v[106:107], v[106:107], v[182:183] op_sel_hi:[1,0]
	v_add_f32_e32 v190, 1.0, v190
	v_rcp_f32_e32 v190, v190
	v_mov_b32_dpp v191, v216 row_shr:1 row_mask:0xf bank_mask:0xf
	v_mul_f32_e32 v189, v189, v190
	v_mul_f32_e32 v189, v188, v189
	v_cvt_pk_bf16_f32 v188, v171, v179
	v_cvt_pk_bf16_f32 v189, v181, v189
	flat_store_dwordx2 v[226:227], v[188:189]
	v_lshl_add_u64 v[188:189], v[226:227], 0, s[50:51]
	v_mov_b32_e32 v227, v1
	v_mov_b32_e32 v226, v1
	v_mov_b32_e32 v190, v1
	v_mov_b32_dpp v227, v224 row_ror:2 row_mask:0xf bank_mask:0xf
	v_mov_b32_dpp v226, v222 row_ror:2 row_mask:0xf bank_mask:0xf
	v_mov_b32_dpp v190, v222 row_ror:1 row_mask:0xf bank_mask:0xf
	v_mov_b32_dpp v227, v216 row_shr:2 row_mask:0xf bank_mask:0xf
	v_mov_b32_dpp v226, v214 row_shr:2 row_mask:0xf bank_mask:0xf
	v_mov_b32_dpp v190, v214 row_shr:1 row_mask:0xf bank_mask:0xf
	v_pk_fma_f32 v[226:227], v[110:111], v[226:227], v[112:113]
	s_nop 0
	v_pk_fma_f32 v[190:191], v[114:115], v[190:191], v[226:227]
	v_mov_b32_e32 v226, v214
	v_mov_b32_e32 v227, v216
	v_pk_fma_f32 v[190:191], v[226:227], v[116:117], v[190:191]
	v_mov_b32_e32 v227, v1
	v_mul_f32_e32 v171, 0xbfb8aa3b, v191
	v_exp_f32_e32 v171, v171
	v_mov_b32_e32 v226, v1
	v_mov_b32_dpp v227, v225 row_ror:2 row_mask:0xf bank_mask:0xf
	v_add_f32_e32 v171, 1.0, v171
	v_rcp_f32_e32 v171, v171
	v_mov_b32_dpp v226, v223 row_ror:2 row_mask:0xf bank_mask:0xf
	v_mov_b32_dpp v227, v217 row_shr:2 row_mask:0xf bank_mask:0xf
	v_mul_f32_e32 v171, v191, v171
	v_mul_f32_e32 v171, v190, v171
	v_mov_b32_e32 v191, v1
	v_mov_b32_e32 v190, v1
	v_mov_b32_dpp v226, v215 row_shr:2 row_mask:0xf bank_mask:0xf
	v_mov_b32_dpp v191, v225 row_ror:1 row_mask:0xf bank_mask:0xf
	v_mov_b32_dpp v190, v223 row_ror:1 row_mask:0xf bank_mask:0xf
	v_pk_fma_f32 v[222:223], v[118:119], v[226:227], v[120:121]
	v_mov_b32_dpp v191, v217 row_shr:1 row_mask:0xf bank_mask:0xf
	v_mov_b32_dpp v190, v215 row_shr:1 row_mask:0xf bank_mask:0xf
	v_pk_fma_f32 v[190:191], v[122:123], v[190:191], v[222:223]
	v_mov_b32_e32 v222, v215
	v_mov_b32_e32 v223, v217
	v_pk_fma_f32 v[190:191], v[222:223], v[124:125], v[190:191]
	v_mov_b32_e32 v223, v1
	v_mul_f32_e32 v179, 0xbfb8aa3b, v191
	v_exp_f32_e32 v179, v179
	v_mov_b32_e32 v222, v1
	v_mov_b32_dpp v223, v220 row_ror:2 row_mask:0xf bank_mask:0xf
	v_add_f32_e32 v179, 1.0, v179
	v_rcp_f32_e32 v179, v179
	v_mov_b32_dpp v222, v218 row_ror:2 row_mask:0xf bank_mask:0xf
	v_mov_b32_dpp v223, v212 row_shr:2 row_mask:0xf bank_mask:0xf
	v_mul_f32_e32 v179, v191, v179
	v_mul_f32_e32 v179, v190, v179
	v_mov_b32_e32 v191, v1
	v_mov_b32_e32 v190, v1
	v_mov_b32_dpp v222, v210 row_shr:2 row_mask:0xf bank_mask:0xf
	v_mov_b32_dpp v191, v220 row_ror:1 row_mask:0xf bank_mask:0xf
	v_mov_b32_dpp v190, v218 row_ror:1 row_mask:0xf bank_mask:0xf
	v_pk_fma_f32 v[222:223], v[126:127], v[222:223], v[128:129]
	v_mov_b32_dpp v191, v212 row_shr:1 row_mask:0xf bank_mask:0xf
	v_mov_b32_dpp v190, v210 row_shr:1 row_mask:0xf bank_mask:0xf
	v_pk_fma_f32 v[190:191], v[196:197], v[190:191], v[222:223]
	v_mov_b32_e32 v222, v210
	v_mov_b32_e32 v223, v212
	v_pk_fma_f32 v[190:191], v[222:223], v[198:199], v[190:191]
	v_mov_b32_e32 v223, v1
	v_mul_f32_e32 v181, 0xbfb8aa3b, v191
	v_exp_f32_e32 v181, v181
	v_mov_b32_e32 v222, v1
	v_mov_b32_dpp v223, v221 row_ror:2 row_mask:0xf bank_mask:0xf
	v_add_f32_e32 v181, 1.0, v181
	v_rcp_f32_e32 v181, v181
	v_mov_b32_dpp v222, v219 row_ror:2 row_mask:0xf bank_mask:0xf
	v_mov_b32_dpp v223, v213 row_shr:2 row_mask:0xf bank_mask:0xf
	v_mul_f32_e32 v181, v191, v181
	v_mul_f32_e32 v181, v190, v181
	v_mov_b32_e32 v191, v1
	v_mov_b32_e32 v190, v1
	v_mov_b32_dpp v222, v211 row_shr:2 row_mask:0xf bank_mask:0xf
	v_mov_b32_dpp v191, v221 row_ror:1 row_mask:0xf bank_mask:0xf
	v_mov_b32_dpp v190, v219 row_ror:1 row_mask:0xf bank_mask:0xf
	v_pk_fma_f32 v[218:219], v[192:193], v[222:223], v[194:195]
	v_mov_b32_dpp v191, v213 row_shr:1 row_mask:0xf bank_mask:0xf
	v_mov_b32_dpp v190, v211 row_shr:1 row_mask:0xf bank_mask:0xf
	v_pk_fma_f32 v[190:191], v[200:201], v[190:191], v[218:219]
	v_mov_b32_e32 v218, v211
	v_mov_b32_e32 v219, v213
	v_pk_fma_f32 v[190:191], v[218:219], v[202:203], v[190:191]
	s_nop 0
	v_mul_f32_e32 v218, 0xbfb8aa3b, v191
	v_exp_f32_e32 v218, v218
	s_nop 0
	v_add_f32_e32 v218, 1.0, v218
	v_rcp_f32_e32 v218, v218
	s_nop 0
	v_mul_f32_e32 v191, v191, v218
	v_mul_f32_e32 v191, v190, v191
	v_cvt_pk_bf16_f32 v190, v171, v179
	v_cvt_pk_bf16_f32 v191, v181, v191
	flat_store_dwordx2 v[188:189], v[190:191]
	v_mov_b32_e32 v191, v1
	v_mov_b32_e32 v190, v1
	v_lshl_add_u64 v[218:219], v[188:189], 0, s[50:51]
	v_mov_b32_e32 v189, v1
	v_mov_b32_dpp v191, v216 row_ror:2 row_mask:0xf bank_mask:0xf
	v_mov_b32_e32 v188, v1
	v_mov_b32_dpp v190, v214 row_ror:2 row_mask:0xf bank_mask:0xf
	v_mov_b32_dpp v189, v216 row_ror:1 row_mask:0xf bank_mask:0xf
	v_mov_b32_dpp v191, v208 row_shr:2 row_mask:0xf bank_mask:0xf
	v_mov_b32_dpp v188, v214 row_ror:1 row_mask:0xf bank_mask:0xf
	v_mov_b32_dpp v190, v106 row_shr:2 row_mask:0xf bank_mask:0xf
	v_mov_b32_dpp v189, v208 row_shr:1 row_mask:0xf bank_mask:0xf
;     __device__ __forceinline__ void operator()(f32x4 (&acc)[2][2][4][2], const Unit& u, int wr, int wc, int fr, int fq) const {
;     ...
;                 for (int m = 0; m < 4; ++m) {
;                     float og[4];
; #pragma unroll
;                     for (int j = 0; j < 4; ++j) {
;                         const float vg = acc[ai][0][m][n][j], vv = acc[ai][1][m][n][j];
;                         const float pg = (m > 0) ? acc[ai][0][m - 1][n][j] : 0.f, pv = (m > 0) ? acc[ai][1][m - 1][n][j] : 0.f;
;                         const float g1 = dppf(dppf(0.f, pg, 2), vg, 0), g2 = dppf(dppf(0.f, pg, 3), vg, 1);
;                         const float v1 = dppf(dppf(0.f, pv, 2), vv, 0), v2 = dppf(dppf(0.f, pv, 3), vv, 1);
;                         const float cgate = bg[j] + wg0[j] * g2 + wg1[j] * g1 + wg2[j] * vg;
;                         const float cval = bv[j] + wv0[j] * v2 + wv1[j] * v1 + wv2[j] * vv;
;                         og[j] = cgate * __builtin_amdgcn_rcpf(1.0f + __builtin_amdgcn_exp2f(-1.4426950408889634f * cgate)) * cval; }
;                     const unsigned long long w = (unsigned long long)cvt_pk_bf16(og[0], og[1]) | ((unsigned long long)cvt_pk_bf16(og[2], og[3]) << 32);
;                     if (m == 0) {
;                         if (fr >= 2) *(unsigned long long*)gp = w;
;                         else { *(unsigned long long*)sb = (unsigned long long)cvt_pk_bf16(acc[ai][0][0][n][0], acc[ai][0][0][n][1]) | ((unsigned long long)cvt_pk_bf16(acc[ai][0][0][n][2], acc[ai][0][0][n][3]) << 32);
;                                *(unsigned long long*)(sb + FFc) = (unsigned long long)cvt_pk_bf16(acc[ai][1][0][n][0], acc[ai][1][0][n][1]) | ((unsigned long long)cvt_pk_bf16(acc[ai][1][0][n][2], acc[ai][1][0][n][3]) << 32); }
;                     } else *(unsigned long long*)gp = w;
;                     if (m == 3 && fr >= 14) {
;                         *(unsigned long long*)hb = (unsigned long long)cvt_pk_bf16(acc[ai][0][3][n][0], acc[ai][0][3][n][1]) | ((unsigned long long)cvt_pk_bf16(acc[ai][0][3][n][2], acc[ai][0][3][n][3]) << 32);
;                         *(unsigned long long*)(hb + FFc) = (unsigned long long)cvt_pk_bf16(acc[ai][1][3][n][0], acc[ai][1][3][n][1]) | ((unsigned long long)cvt_pk_bf16(acc[ai][1][3][n][2], acc[ai][1][3][n][3]) << 32); }
	v_mov_b32_dpp v188, v106 row_shr:1 row_mask:0xf bank_mask:0xf
	v_pk_fma_f32 v[190:191], v[110:111], v[190:191], v[112:113]
	s_nop 0
	v_pk_fma_f32 v[188:189], v[114:115], v[188:189], v[190:191]
	v_mov_b32_e32 v190, v106
	v_mov_b32_e32 v191, v208
	v_pk_fma_f32 v[188:189], v[190:191], v[116:117], v[188:189]
	v_mov_b32_e32 v191, v1
	v_mul_f32_e32 v171, 0xbfb8aa3b, v189
	v_exp_f32_e32 v171, v171
	v_mov_b32_e32 v190, v1
	v_mov_b32_dpp v191, v217 row_ror:2 row_mask:0xf bank_mask:0xf
	v_add_f32_e32 v171, 1.0, v171
	v_rcp_f32_e32 v171, v171
	v_mov_b32_dpp v190, v215 row_ror:2 row_mask:0xf bank_mask:0xf
	v_mov_b32_dpp v191, v209 row_shr:2 row_mask:0xf bank_mask:0xf
	v_mul_f32_e32 v171, v189, v171
	v_mul_f32_e32 v171, v188, v171
	v_mov_b32_e32 v189, v1
	v_mov_b32_e32 v188, v1
	v_mov_b32_dpp v190, v107 row_shr:2 row_mask:0xf bank_mask:0xf
	v_mov_b32_dpp v189, v217 row_ror:1 row_mask:0xf bank_mask:0xf
	v_mov_b32_dpp v188, v215 row_ror:1 row_mask:0xf bank_mask:0xf
	v_pk_fma_f32 v[190:191], v[118:119], v[190:191], v[120:121]
	v_mov_b32_dpp v189, v209 row_shr:1 row_mask:0xf bank_mask:0xf
	v_mov_b32_dpp v188, v107 row_shr:1 row_mask:0xf bank_mask:0xf
	v_pk_fma_f32 v[188:189], v[122:123], v[188:189], v[190:191]
	v_mov_b32_e32 v190, v107
	v_mov_b32_e32 v191, v209
	v_pk_fma_f32 v[188:189], v[190:191], v[124:125], v[188:189]
	v_mov_b32_e32 v191, v1
	v_mul_f32_e32 v179, 0xbfb8aa3b, v189
	v_exp_f32_e32 v179, v179
	v_mov_b32_e32 v190, v1
	v_mov_b32_dpp v191, v212 row_ror:2 row_mask:0xf bank_mask:0xf
	v_add_f32_e32 v179, 1.0, v179
	v_rcp_f32_e32 v179, v179
	v_mov_b32_dpp v190, v210 row_ror:2 row_mask:0xf bank_mask:0xf
	v_mov_b32_dpp v191, v206 row_shr:2 row_mask:0xf bank_mask:0xf
	v_mul_f32_e32 v179, v189, v179
	v_mul_f32_e32 v179, v188, v179
	v_mov_b32_e32 v189, v1
	v_mov_b32_e32 v188, v1
	v_mov_b32_dpp v190, v204 row_shr:2 row_mask:0xf bank_mask:0xf
	v_mov_b32_dpp v189, v212 row_ror:1 row_mask:0xf bank_mask:0xf
	v_mov_b32_dpp v188, v210 row_ror:1 row_mask:0xf bank_mask:0xf
	v_pk_fma_f32 v[190:191], v[126:127], v[190:191], v[128:129]
	v_mov_b32_dpp v189, v206 row_shr:1 row_mask:0xf bank_mask:0xf
	v_mov_b32_dpp v188, v204 row_shr:1 row_mask:0xf bank_mask:0xf
	v_pk_fma_f32 v[188:189], v[196:197], v[188:189], v[190:191]
	v_mov_b32_e32 v190, v204
	v_mov_b32_e32 v191, v206
	v_pk_fma_f32 v[188:189], v[190:191], v[198:199], v[188:189]
	v_mov_b32_e32 v191, v1
	v_mul_f32_e32 v181, 0xbfb8aa3b, v189
	v_exp_f32_e32 v181, v181
	v_mov_b32_e32 v190, v1
	v_mov_b32_dpp v191, v213 row_ror:2 row_mask:0xf bank_mask:0xf
	v_add_f32_e32 v181, 1.0, v181
	v_rcp_f32_e32 v181, v181
	v_mov_b32_dpp v190, v211 row_ror:2 row_mask:0xf bank_mask:0xf
	v_mov_b32_dpp v191, v207 row_shr:2 row_mask:0xf bank_mask:0xf
	v_mul_f32_e32 v181, v189, v181
	v_mul_f32_e32 v181, v188, v181
	v_mov_b32_e32 v189, v1
	v_mov_b32_e32 v188, v1
	v_mov_b32_dpp v190, v205 row_shr:2 row_mask:0xf bank_mask:0xf
	v_mov_b32_dpp v189, v213 row_ror:1 row_mask:0xf bank_mask:0xf
	v_mov_b32_dpp v188, v211 row_ror:1 row_mask:0xf bank_mask:0xf
	v_pk_fma_f32 v[190:191], v[192:193], v[190:191], v[194:195]
	v_mov_b32_dpp v189, v207 row_shr:1 row_mask:0xf bank_mask:0xf
	v_mov_b32_dpp v188, v205 row_shr:1 row_mask:0xf bank_mask:0xf
	v_pk_fma_f32 v[188:189], v[200:201], v[188:189], v[190:191]
	v_mov_b32_e32 v190, v205
	v_mov_b32_e32 v191, v207
	v_pk_fma_f32 v[188:189], v[190:191], v[202:203], v[188:189]
	s_nop 0
	v_mul_f32_e32 v190, 0xbfb8aa3b, v189
	v_exp_f32_e32 v190, v190
	s_nop 0
	v_add_f32_e32 v190, 1.0, v190
	v_rcp_f32_e32 v190, v190
	s_nop 0
	v_mul_f32_e32 v189, v189, v190
	v_mul_f32_e32 v189, v188, v189
	v_cvt_pk_bf16_f32 v188, v171, v179
	v_cvt_pk_bf16_f32 v189, v181, v189
	flat_store_dwordx2 v[218:219], v[188:189]
	s_and_saveexec_b64 s[0:1], s[8:9]
	s_mov_b64 s[66:67], s[14:15]
	s_cbranch_execz .LBB0_1356
	v_cvt_pk_bf16_f32 v188, v208, v209
	v_cvt_pk_bf16_f32 v189, v206, v207
	global_store_dwordx2 v[108:109], v[188:189], off
	v_add_co_u32_e32 v188, vcc, 0x1000, v108
	v_cvt_pk_bf16_f32 v106, v106, v107
	v_cvt_pk_bf16_f32 v107, v204, v205
	s_nop 1
	v_addc_co_u32_e32 v189, vcc, 0, v109, vcc
	global_store_dwordx2 v[188:189], v[106:107], off offset:1536
; __device__ __forceinline__ unsigned cvt_pk_bf16(float lo, float hi) { unsigned r; asm volatile("v_cvt_pk_bf16_f32 %0, %1, %2" : "=v"(r) : "v"(lo), "v"(hi)); return r; }
; __device__ __forceinline__ void load_row_scales(const float* ssp, int row0, int fq, float (&rs)[2][4]) {
;     ...
;             rs[ai][m] = 1.0f / sqrtf(t * (1.0f / 1024.0f) + 1e-6f); }
;     __device__ __forceinline__ void operator()(f32x4 (&acc)[2][2][4][2], const Unit& u, int wr, int wc, int fr, int fq) const {
;     ...
;                       for (int n = 0; n < 2; ++n) acc[ai][bj][m][n] = acc[ai][bj][m][n] * rs[ai][m]; }
;     ...
;             for (int ai = 0; ai < 2; ++ai) {
; #pragma unroll
;                 for (int m = 0; m < 4; ++m) {
;                     float og[4];
; #pragma unroll
;                     for (int j = 0; j < 4; ++j) {
;                         const float vg = acc[ai][0][m][n][j], vv = acc[ai][1][m][n][j];
;                         const float pg = (m > 0) ? acc[ai][0][m - 1][n][j] : 0.f, pv = (m > 0) ? acc[ai][1][m - 1][n][j] : 0.f;
;                         const float g1 = dppf(dppf(0.f, pg, 2), vg, 0), g2 = dppf(dppf(0.f, pg, 3), vg, 1);
;                         const float v1 = dppf(dppf(0.f, pv, 2), vv, 0), v2 = dppf(dppf(0.f, pv, 3), vv, 1);
;                         const float cgate = bg[j] + wg0[j] * g2 + wg1[j] * g1 + wg2[j] * vg;
;                         const float cval = bv[j] + wv0[j] * v2 + wv1[j] * v1 + wv2[j] * vv;
;                         og[j] = cgate * __builtin_amdgcn_rcpf(1.0f + __builtin_amdgcn_exp2f(-1.4426950408889634f * cgate)) * cval; }
;                     const unsigned long long w = (unsigned long long)cvt_pk_bf16(og[0], og[1]) | ((unsigned long long)cvt_pk_bf16(og[2], og[3]) << 32);
;                     if (m == 0) {
;                         if (fr >= 2) *(unsigned long long*)gp = w;
;                         else { *(unsigned long long*)sb = (unsigned long long)cvt_pk_bf16(acc[ai][0][0][n][0], acc[ai][0][0][n][1]) | ((unsigned long long)cvt_pk_bf16(acc[ai][0][0][n][2], acc[ai][0][0][n][3]) << 32);
;                                *(unsigned long long*)(sb + FFc) = (unsigned long long)cvt_pk_bf16(acc[ai][1][0][n][0], acc[ai][1][0][n][1]) | ((unsigned long long)cvt_pk_bf16(acc[ai][1][0][n][2], acc[ai][1][0][n][3]) << 32); }
;                     } else *(unsigned long long*)gp = w;
.LBB0_1356:
	s_or_b64 exec, exec, s[0:1]
	v_add_f32_e32 v106, v244, v245
	v_fmamk_f32 v106, v106, 0x3a800000, v230
	v_lshl_add_u64 v[204:205], v[108:109], 0, s[54:55]
	v_rsq_f32_e32 v106, v106
	s_nop 0
	v_pk_mul_f32 v[210:211], v[90:91], v[106:107] op_sel_hi:[1,0]
	v_lshl_add_u64 v[90:91], v[218:219], 0, s[50:51]
	v_pk_mul_f32 v[206:207], v[92:93], v[106:107] op_sel_hi:[1,0]
	v_mov_b32_e32 v92, v1
	v_lshl_add_u64 v[214:215], v[90:91], 0, s[52:53]
	v_mov_b32_e32 v90, v1
	v_mov_b32_dpp v92, v92 row_ror:2 row_mask:0xf bank_mask:0xf
	v_pk_mul_f32 v[212:213], v[94:95], v[106:107] op_sel_hi:[1,0]
	v_mov_b32_dpp v90, v90 row_ror:1 row_mask:0xf bank_mask:0xf
	v_mov_b32_e32 v93, v92
	v_mov_b32_e32 v91, v90
	v_mov_b32_e32 v95, v92
	v_mov_b32_dpp v93, v212 row_shr:2 row_mask:0xf bank_mask:0xf
	v_mov_b32_dpp v91, v212 row_shr:1 row_mask:0xf bank_mask:0xf
	v_fma_f32 v93, v138, v93, v146
	v_fmac_f32_e32 v93, v142, v91
	v_fmac_f32_e32 v93, v212, v98
	v_mul_f32_e32 v91, 0xbfb8aa3b, v93
	v_exp_f32_e32 v91, v91
	v_mov_b32_e32 v94, v90
	v_mov_b32_dpp v95, v210 row_shr:2 row_mask:0xf bank_mask:0xf
	v_fma_f32 v95, v130, v95, v150
	v_add_f32_e32 v91, 1.0, v91
	v_rcp_f32_e32 v91, v91
	v_mov_b32_dpp v94, v210 row_shr:1 row_mask:0xf bank_mask:0xf
	v_fmac_f32_e32 v95, v134, v94
	v_mov_b32_e32 v94, v92
	v_mul_f32_e32 v91, v93, v91
	v_mov_b32_e32 v93, v90
	v_mov_b32_dpp v94, v213 row_shr:2 row_mask:0xf bank_mask:0xf
	v_fma_f32 v94, v139, v94, v147
	v_mov_b32_dpp v93, v213 row_shr:1 row_mask:0xf bank_mask:0xf
	v_fmac_f32_e32 v94, v143, v93
	v_fmac_f32_e32 v94, v213, v99
	v_mul_f32_e32 v93, 0xbfb8aa3b, v94
	v_exp_f32_e32 v93, v93
	v_pk_mul_f32 v[208:209], v[96:97], v[106:107] op_sel_hi:[1,0]
	v_fmac_f32_e32 v95, v210, v102
	v_mov_b32_e32 v107, v92
	v_add_f32_e32 v93, 1.0, v93
	v_rcp_f32_e32 v93, v93
	v_mul_f32_e32 v91, v95, v91
	v_mov_b32_e32 v95, v90
	v_mov_b32_dpp v107, v211 row_shr:2 row_mask:0xf bank_mask:0xf
	v_fma_f32 v107, v131, v107, v151
	v_mov_b32_dpp v95, v211 row_shr:1 row_mask:0xf bank_mask:0xf
	v_fmac_f32_e32 v107, v135, v95
	v_mov_b32_e32 v95, v92
	v_mul_f32_e32 v93, v94, v93
	v_mov_b32_e32 v94, v90
	v_mov_b32_dpp v95, v208 row_shr:2 row_mask:0xf bank_mask:0xf
	v_fma_f32 v95, v140, v95, v148
	v_mov_b32_dpp v94, v208 row_shr:1 row_mask:0xf bank_mask:0xf
	v_fmac_f32_e32 v95, v144, v94
	v_fmac_f32_e32 v95, v208, v100
	v_mul_f32_e32 v94, 0xbfb8aa3b, v95
	v_exp_f32_e32 v94, v94
	v_fmac_f32_e32 v107, v211, v103
	v_mov_b32_e32 v130, v92
	v_mul_f32_e32 v93, v107, v93
	v_add_f32_e32 v94, 1.0, v94
	v_rcp_f32_e32 v94, v94
	v_mov_b32_e32 v107, v90
	v_mov_b32_dpp v130, v206 row_shr:2 row_mask:0xf bank_mask:0xf
	v_fma_f32 v130, v132, v130, v152
	v_mov_b32_dpp v107, v206 row_shr:1 row_mask:0xf bank_mask:0xf
	v_fmac_f32_e32 v130, v136, v107
	v_mov_b32_e32 v107, v92
	v_mul_f32_e32 v94, v95, v94
	v_mov_b32_e32 v95, v90
	v_mov_b32_dpp v107, v209 row_shr:2 row_mask:0xf bank_mask:0xf
	v_fmac_f32_e32 v149, v141, v107
	v_mov_b32_dpp v95, v209 row_shr:1 row_mask:0xf bank_mask:0xf
	v_fmac_f32_e32 v149, v145, v95
	v_fmac_f32_e32 v149, v209, v101
	v_mul_f32_e32 v95, 0xbfb8aa3b, v149
	v_exp_f32_e32 v95, v95
	v_mov_b32_dpp v92, v207 row_shr:2 row_mask:0xf bank_mask:0xf
	v_mov_b32_dpp v90, v207 row_shr:1 row_mask:0xf bank_mask:0xf
	v_fmac_f32_e32 v153, v133, v92
	v_add_f32_e32 v95, 1.0, v95
	v_rcp_f32_e32 v95, v95
	v_fmac_f32_e32 v153, v137, v90
	v_lshl_add_u64 v[96:97], v[184:185], 0, s[54:55]
	v_fmac_f32_e32 v130, v206, v104
	v_fmac_f32_e32 v153, v207, v105
	v_mul_f32_e32 v90, v149, v95
	v_mul_f32_e32 v94, v130, v94
	v_mul_f32_e32 v92, v153, v90
	v_cvt_pk_bf16_f32 v90, v91, v93
	v_cvt_pk_bf16_f32 v91, v94, v92
	s_and_saveexec_b64 s[0:1], s[6:7]
	s_xor_b64 s[0:1], exec, s[0:1]
	s_cbranch_execz .LBB0_1358
	v_cvt_pk_bf16_f32 v90, v212, v213
	v_cvt_pk_bf16_f32 v91, v208, v209
	v_add_co_u32_e32 v92, vcc, 0x1000, v96
	flat_store_dwordx2 v[96:97], v[90:91]
	v_cvt_pk_bf16_f32 v90, v210, v211
	v_cvt_pk_bf16_f32 v91, v206, v207
	s_nop 0
	v_addc_co_u32_e32 v93, vcc, 0, v97, vcc
	flat_store_dwordx2 v[92:93], v[90:91] offset:1536

; __device__ __forceinline__ void load_row_scales(const float* ssp, int row0, int fq, float (&rs)[2][4]) {
;     ...
;             rs[ai][m] = 1.0f / sqrtf(t * (1.0f / 1024.0f) + 1e-6f); }
;     __device__ __forceinline__ void operator()(f32x4 (&acc)[2][2][4][2], const Unit& u, int wr, int wc, int fr, int fq) const {
;     ...
;                       for (int n = 0; n < 2; ++n) acc[ai][bj][m][n] = acc[ai][bj][m][n] * rs[ai][m]; }
;     ...
;                 for (int m = 0; m < 4; ++m) {
;                     float og[4];
; #pragma unroll
;                     for (int j = 0; j < 4; ++j) {
;                         const float vg = acc[ai][0][m][n][j], vv = acc[ai][1][m][n][j];
;                         const float pg = (m > 0) ? acc[ai][0][m - 1][n][j] : 0.f, pv = (m > 0) ? acc[ai][1][m - 1][n][j] : 0.f;
;                         const float g1 = dppf(dppf(0.f, pg, 2), vg, 0), g2 = dppf(dppf(0.f, pg, 3), vg, 1);
;                         const float v1 = dppf(dppf(0.f, pv, 2), vv, 0), v2 = dppf(dppf(0.f, pv, 3), vv, 1);
;                         const float cgate = bg[j] + wg0[j] * g2 + wg1[j] * g1 + wg2[j] * vg;
;                         const float cval = bv[j] + wv0[j] * v2 + wv1[j] * v1 + wv2[j] * vv;
;                         og[j] = cgate * __builtin_amdgcn_rcpf(1.0f + __builtin_amdgcn_exp2f(-1.4426950408889634f * cgate)) * cval; }
;                     const unsigned long long w = (unsigned long long)cvt_pk_bf16(og[0], og[1]) | ((unsigned long long)cvt_pk_bf16(og[2], og[3]) << 32);
;                     if (m == 0) {
;                         if (fr >= 2) *(unsigned long long*)gp = w;
;                         else { *(unsigned long long*)sb = (unsigned long long)cvt_pk_bf16(acc[ai][0][0][n][0], acc[ai][0][0][n][1]) | ((unsigned long long)cvt_pk_bf16(acc[ai][0][0][n][2], acc[ai][0][0][n][3]) << 32);
;                                *(unsigned long long*)(sb + FFc) = (unsigned long long)cvt_pk_bf16(acc[ai][1][0][n][0], acc[ai][1][0][n][1]) | ((unsigned long long)cvt_pk_bf16(acc[ai][1][0][n][2], acc[ai][1][0][n][3]) << 32); }
;                     } else *(unsigned long long*)gp = w;
;                     if (m == 3 && fr >= 14) {
;                         *(unsigned long long*)hb = (unsigned long long)cvt_pk_bf16(acc[ai][0][3][n][0], acc[ai][0][3][n][1]) | ((unsigned long long)cvt_pk_bf16(acc[ai][0][3][n][2], acc[ai][0][3][n][3]) << 32);
.LBB0_1360:
	s_or_b64 exec, exec, s[0:1]
	v_add_f32_e32 v90, v242, v243
	v_fmamk_f32 v90, v90, 0x3a800000, v230
	v_mov_b32_e32 v135, v1
	v_mov_b32_e32 v134, v1
	s_nop 1
	v_mov_b32_dpp v135, v212 row_ror:2 row_mask:0xf bank_mask:0xf
	v_mov_b32_e32 v136, v102
	s_nop 1
	v_mov_b32_dpp v134, v210 row_ror:2 row_mask:0xf bank_mask:0xf
	v_rsq_f32_e32 v90, v90
	s_nop 0
	v_add_f32_e32 v91, v240, v241
	v_fmamk_f32 v91, v91, 0x3a800000, v230
	v_rsq_f32_e32 v92, v91
	s_nop 0
	v_add_f32_e32 v91, v169, v183
	v_fmamk_f32 v91, v91, 0x3a800000, v230
	v_pk_mul_f32 v[132:133], v[86:87], v[90:91] op_sel_hi:[1,0]
	v_pk_mul_f32 v[86:87], v[80:81], v[90:91] op_sel_hi:[1,0]
	v_mov_b32_e32 v137, v132
	v_rsq_f32_e32 v94, v91
	s_nop 0
	v_pk_mul_f32 v[130:131], v[78:79], v[90:91] op_sel_hi:[1,0]
	v_pk_mul_f32 v[80:81], v[84:85], v[92:93] op_sel_hi:[1,0]
	v_pk_mul_f32 v[84:85], v[82:83], v[92:93] op_sel_hi:[1,0]
	v_pk_mul_f32 v[82:83], v[70:71], v[92:93] op_sel_hi:[1,0]
	v_pk_mul_f32 v[70:71], v[76:77], v[94:95] op_sel_hi:[1,0]
	v_mov_b32_e32 v77, v1
	v_mov_b32_e32 v76, v1
	v_mov_b32_dpp v135, v132 row_shr:2 row_mask:0xf bank_mask:0xf
	v_mov_b32_dpp v77, v212 row_ror:1 row_mask:0xf bank_mask:0xf
	v_mov_b32_dpp v76, v210 row_ror:1 row_mask:0xf bank_mask:0xf
	v_mov_b32_dpp v134, v130 row_shr:2 row_mask:0xf bank_mask:0xf
	v_mov_b32_dpp v77, v132 row_shr:1 row_mask:0xf bank_mask:0xf
	v_mov_b32_dpp v76, v130 row_shr:1 row_mask:0xf bank_mask:0xf
	v_pk_fma_f32 v[134:135], v[110:111], v[134:135], v[112:113]
	v_pk_mul_f32 v[88:89], v[88:89], v[90:91] op_sel_hi:[1,0]
	v_pk_fma_f32 v[76:77], v[114:115], v[76:77], v[134:135]
	v_mov_b32_e32 v134, v130
	v_mov_b32_e32 v135, v98
	v_pk_fma_f32 v[76:77], v[134:135], v[136:137], v[76:77]
	v_mov_b32_e32 v135, v1
	v_mul_f32_e32 v91, 0xbfb8aa3b, v77
	v_exp_f32_e32 v91, v91
	v_mov_b32_e32 v134, v1
	v_mov_b32_dpp v135, v213 row_ror:2 row_mask:0xf bank_mask:0xf
	v_mov_b32_e32 v136, v103
	v_add_f32_e32 v91, 1.0, v91
	v_rcp_f32_e32 v91, v91
	v_mov_b32_dpp v134, v211 row_ror:2 row_mask:0xf bank_mask:0xf
	v_mov_b32_dpp v135, v133 row_shr:2 row_mask:0xf bank_mask:0xf
	v_mov_b32_e32 v137, v133
	v_mul_f32_e32 v77, v77, v91
	v_mul_f32_e32 v91, v76, v77
	v_mov_b32_e32 v77, v1
	v_mov_b32_e32 v76, v1
	v_mov_b32_dpp v134, v131 row_shr:2 row_mask:0xf bank_mask:0xf
	v_mov_b32_dpp v77, v213 row_ror:1 row_mask:0xf bank_mask:0xf
	v_mov_b32_dpp v76, v211 row_ror:1 row_mask:0xf bank_mask:0xf
	v_pk_fma_f32 v[134:135], v[118:119], v[134:135], v[120:121]
	v_mov_b32_dpp v77, v133 row_shr:1 row_mask:0xf bank_mask:0xf
	v_mov_b32_dpp v76, v131 row_shr:1 row_mask:0xf bank_mask:0xf
	v_pk_fma_f32 v[76:77], v[122:123], v[76:77], v[134:135]
	v_mov_b32_e32 v134, v131
	v_mov_b32_e32 v135, v99
	v_pk_fma_f32 v[76:77], v[134:135], v[136:137], v[76:77]
	v_pk_mul_f32 v[78:79], v[72:73], v[92:93] op_sel_hi:[1,0]
	v_mul_f32_e32 v93, 0xbfb8aa3b, v77
	v_exp_f32_e32 v93, v93
	v_mov_b32_e32 v135, v1
	v_mov_b32_e32 v134, v1
	v_mov_b32_e32 v136, v104
	v_add_f32_e32 v93, 1.0, v93
	v_rcp_f32_e32 v93, v93
	v_mov_b32_dpp v135, v208 row_ror:2 row_mask:0xf bank_mask:0xf
	v_mov_b32_dpp v134, v206 row_ror:2 row_mask:0xf bank_mask:0xf
	v_mov_b32_e32 v137, v88
	v_mul_f32_e32 v77, v77, v93
	v_mul_f32_e32 v93, v76, v77
	v_mov_b32_e32 v77, v1
	v_mov_b32_e32 v76, v1
	v_mov_b32_dpp v135, v88 row_shr:2 row_mask:0xf bank_mask:0xf
	v_mov_b32_dpp v77, v208 row_ror:1 row_mask:0xf bank_mask:0xf
	v_mov_b32_dpp v76, v206 row_ror:1 row_mask:0xf bank_mask:0xf
	v_mov_b32_dpp v134, v86 row_shr:2 row_mask:0xf bank_mask:0xf
	v_mov_b32_dpp v77, v88 row_shr:1 row_mask:0xf bank_mask:0xf
	v_mov_b32_dpp v76, v86 row_shr:1 row_mask:0xf bank_mask:0xf
	v_pk_fma_f32 v[134:135], v[126:127], v[134:135], v[128:129]
	v_pk_mul_f32 v[72:73], v[74:75], v[94:95] op_sel_hi:[1,0]
	v_pk_fma_f32 v[76:77], v[196:197], v[76:77], v[134:135]
	v_mov_b32_e32 v134, v86
	v_mov_b32_e32 v135, v100
	v_pk_fma_f32 v[76:77], v[134:135], v[136:137], v[76:77]
	v_pk_mul_f32 v[68:69], v[68:69], v[94:95] op_sel_hi:[1,0]
	v_pk_mul_f32 v[66:67], v[66:67], v[94:95] op_sel_hi:[1,0]
	v_mul_f32_e32 v95, 0xbfb8aa3b, v77
	v_exp_f32_e32 v95, v95
	v_mov_b32_e32 v135, v1
	v_mov_b32_e32 v134, v1
	v_mov_b32_e32 v136, v105
	v_add_f32_e32 v95, 1.0, v95
	v_rcp_f32_e32 v95, v95
	v_mov_b32_dpp v135, v209 row_ror:2 row_mask:0xf bank_mask:0xf
	v_mov_b32_dpp v134, v207 row_ror:2 row_mask:0xf bank_mask:0xf
	v_mov_b32_e32 v137, v89
	v_mul_f32_e32 v77, v77, v95
	v_mul_f32_e32 v95, v76, v77
	v_mov_b32_e32 v77, v1
	v_mov_b32_e32 v76, v1
	v_mov_b32_dpp v135, v89 row_shr:2 row_mask:0xf bank_mask:0xf
	v_mov_b32_dpp v77, v209 row_ror:1 row_mask:0xf bank_mask:0xf
	v_mov_b32_dpp v76, v207 row_ror:1 row_mask:0xf bank_mask:0xf
	v_mov_b32_dpp v134, v87 row_shr:2 row_mask:0xf bank_mask:0xf
	v_mov_b32_dpp v77, v89 row_shr:1 row_mask:0xf bank_mask:0xf
	v_mov_b32_dpp v76, v87 row_shr:1 row_mask:0xf bank_mask:0xf
	v_pk_fma_f32 v[134:135], v[192:193], v[134:135], v[194:195]
	v_lshl_add_u64 v[74:75], v[214:215], 0, s[50:51]
	v_pk_fma_f32 v[76:77], v[200:201], v[76:77], v[134:135]
	v_mov_b32_e32 v134, v87
	v_mov_b32_e32 v135, v101
	v_pk_fma_f32 v[76:77], v[134:135], v[136:137], v[76:77]
	v_mov_b32_e32 v135, v1
	v_mul_f32_e32 v107, 0xbfb8aa3b, v77
	v_exp_f32_e32 v107, v107
	v_mov_b32_e32 v134, v1
	v_mov_b32_dpp v135, v132 row_ror:2 row_mask:0xf bank_mask:0xf
	v_mov_b32_e32 v136, v102
	v_add_f32_e32 v107, 1.0, v107
	v_rcp_f32_e32 v107, v107
	v_mov_b32_dpp v134, v130 row_ror:2 row_mask:0xf bank_mask:0xf
	v_mov_b32_dpp v135, v84 row_shr:2 row_mask:0xf bank_mask:0xf
	v_mov_b32_e32 v137, v84
	v_mul_f32_e32 v77, v77, v107
	v_mul_f32_e32 v77, v76, v77
	v_cvt_pk_bf16_f32 v76, v91, v93
	v_cvt_pk_bf16_f32 v77, v95, v77
;     __device__ __forceinline__ void operator()(f32x4 (&acc)[2][2][4][2], const Unit& u, int wr, int wc, int fr, int fq) const {
;     ...
;                 for (int m = 0; m < 4; ++m) {
;                     float og[4];
; #pragma unroll
;                     for (int j = 0; j < 4; ++j) {
;                         const float vg = acc[ai][0][m][n][j], vv = acc[ai][1][m][n][j];
;                         const float pg = (m > 0) ? acc[ai][0][m - 1][n][j] : 0.f, pv = (m > 0) ? acc[ai][1][m - 1][n][j] : 0.f;
;                         const float g1 = dppf(dppf(0.f, pg, 2), vg, 0), g2 = dppf(dppf(0.f, pg, 3), vg, 1);
;                         const float v1 = dppf(dppf(0.f, pv, 2), vv, 0), v2 = dppf(dppf(0.f, pv, 3), vv, 1);
;                         const float cgate = bg[j] + wg0[j] * g2 + wg1[j] * g1 + wg2[j] * vg;
;                         const float cval = bv[j] + wv0[j] * v2 + wv1[j] * v1 + wv2[j] * vv;
;                         og[j] = cgate * __builtin_amdgcn_rcpf(1.0f + __builtin_amdgcn_exp2f(-1.4426950408889634f * cgate)) * cval; }
;                     const unsigned long long w = (unsigned long long)cvt_pk_bf16(og[0], og[1]) | ((unsigned long long)cvt_pk_bf16(og[2], og[3]) << 32);
;                     if (m == 0) {
;                         if (fr >= 2) *(unsigned long long*)gp = w;
;                         else { *(unsigned long long*)sb = (unsigned long long)cvt_pk_bf16(acc[ai][0][0][n][0], acc[ai][0][0][n][1]) | ((unsigned long long)cvt_pk_bf16(acc[ai][0][0][n][2], acc[ai][0][0][n][3]) << 32);
;                                *(unsigned long long*)(sb + FFc) = (unsigned long long)cvt_pk_bf16(acc[ai][1][0][n][0], acc[ai][1][0][n][1]) | ((unsigned long long)cvt_pk_bf16(acc[ai][1][0][n][2], acc[ai][1][0][n][3]) << 32); }
;                     } else *(unsigned long long*)gp = w;
;                     if (m == 3 && fr >= 14) {
;                         *(unsigned long long*)hb = (unsigned long long)cvt_pk_bf16(acc[ai][0][3][n][0], acc[ai][0][3][n][1]) | ((unsigned long long)cvt_pk_bf16(acc[ai][0][3][n][2], acc[ai][0][3][n][3]) << 32);
;                         *(unsigned long long*)(hb + FFc) = (unsigned long long)cvt_pk_bf16(acc[ai][1][3][n][0], acc[ai][1][3][n][1]) | ((unsigned long long)cvt_pk_bf16(acc[ai][1][3][n][2], acc[ai][1][3][n][3]) << 32); }
;                     gp += (size_t)16 * FFc; asm volatile("" : "+v"(gp) :: "memory"); }
	flat_store_dwordx2 v[74:75], v[76:77]
	v_mov_b32_e32 v77, v1
	v_mov_b32_e32 v76, v1
	v_mov_b32_dpp v134, v82 row_shr:2 row_mask:0xf bank_mask:0xf
	v_mov_b32_dpp v77, v132 row_ror:1 row_mask:0xf bank_mask:0xf
	v_mov_b32_dpp v76, v130 row_ror:1 row_mask:0xf bank_mask:0xf
	v_pk_fma_f32 v[134:135], v[110:111], v[134:135], v[112:113]
	v_mov_b32_dpp v77, v84 row_shr:1 row_mask:0xf bank_mask:0xf
	v_mov_b32_dpp v76, v82 row_shr:1 row_mask:0xf bank_mask:0xf
	v_pk_fma_f32 v[76:77], v[114:115], v[76:77], v[134:135]
	v_mov_b32_e32 v134, v82
	v_mov_b32_e32 v135, v98
	v_pk_fma_f32 v[76:77], v[134:135], v[136:137], v[76:77]
	v_mov_b32_e32 v135, v1
	v_mul_f32_e32 v91, 0xbfb8aa3b, v77
	v_exp_f32_e32 v91, v91
	v_mov_b32_e32 v134, v1
	v_mov_b32_dpp v135, v133 row_ror:2 row_mask:0xf bank_mask:0xf
	v_mov_b32_e32 v98, v83
	v_add_f32_e32 v91, 1.0, v91
	v_rcp_f32_e32 v91, v91
	v_mov_b32_dpp v134, v131 row_ror:2 row_mask:0xf bank_mask:0xf
	v_mov_b32_dpp v135, v85 row_shr:2 row_mask:0xf bank_mask:0xf
	v_mov_b32_e32 v102, v103
	v_mul_f32_e32 v77, v77, v91
	v_mul_f32_e32 v91, v76, v77
	v_mov_b32_e32 v77, v1
	v_mov_b32_e32 v76, v1
	v_mov_b32_dpp v134, v83 row_shr:2 row_mask:0xf bank_mask:0xf
	v_mov_b32_dpp v77, v133 row_ror:1 row_mask:0xf bank_mask:0xf
	v_mov_b32_dpp v76, v131 row_ror:1 row_mask:0xf bank_mask:0xf
	v_pk_fma_f32 v[130:131], v[118:119], v[134:135], v[120:121]
	v_mov_b32_dpp v77, v85 row_shr:1 row_mask:0xf bank_mask:0xf
	v_mov_b32_dpp v76, v83 row_shr:1 row_mask:0xf bank_mask:0xf
	v_pk_fma_f32 v[76:77], v[122:123], v[76:77], v[130:131]
	v_mov_b32_e32 v103, v85
	v_pk_fma_f32 v[76:77], v[98:99], v[102:103], v[76:77]
	v_mov_b32_e32 v99, v1
	v_mul_f32_e32 v93, 0xbfb8aa3b, v77
	v_exp_f32_e32 v93, v93
	v_mov_b32_e32 v98, v1
	v_mov_b32_dpp v99, v88 row_ror:2 row_mask:0xf bank_mask:0xf
	v_mov_b32_e32 v102, v104
	v_add_f32_e32 v93, 1.0, v93
	v_rcp_f32_e32 v93, v93
	v_mov_b32_dpp v98, v86 row_ror:2 row_mask:0xf bank_mask:0xf
	v_mov_b32_dpp v99, v80 row_shr:2 row_mask:0xf bank_mask:0xf
	v_mov_b32_e32 v103, v80
	v_mul_f32_e32 v77, v77, v93
	v_mul_f32_e32 v93, v76, v77
	v_mov_b32_e32 v77, v1
	v_mov_b32_e32 v76, v1
	v_mov_b32_dpp v98, v78 row_shr:2 row_mask:0xf bank_mask:0xf
	v_mov_b32_dpp v77, v88 row_ror:1 row_mask:0xf bank_mask:0xf
	v_mov_b32_dpp v76, v86 row_ror:1 row_mask:0xf bank_mask:0xf
	v_pk_fma_f32 v[98:99], v[126:127], v[98:99], v[128:129]
	v_mov_b32_dpp v77, v80 row_shr:1 row_mask:0xf bank_mask:0xf
	v_mov_b32_dpp v76, v78 row_shr:1 row_mask:0xf bank_mask:0xf
	v_pk_fma_f32 v[76:77], v[196:197], v[76:77], v[98:99]
	v_mov_b32_e32 v98, v78
	v_mov_b32_e32 v99, v100
	v_pk_fma_f32 v[76:77], v[98:99], v[102:103], v[76:77]
	v_mov_b32_e32 v99, v1
	v_mul_f32_e32 v86, 0xbfb8aa3b, v77
	v_exp_f32_e32 v86, v86
	v_mov_b32_e32 v98, v1
	v_mov_b32_dpp v99, v89 row_ror:2 row_mask:0xf bank_mask:0xf
	v_mov_b32_e32 v100, v79
	v_add_f32_e32 v86, 1.0, v86
	v_rcp_f32_e32 v86, v86
	v_mov_b32_dpp v98, v87 row_ror:2 row_mask:0xf bank_mask:0xf
	v_mov_b32_dpp v99, v81 row_shr:2 row_mask:0xf bank_mask:0xf
	v_lshl_add_u64 v[74:75], v[74:75], 0, s[50:51]
	v_mul_f32_e32 v77, v77, v86
	v_mul_f32_e32 v88, v76, v77
	v_mov_b32_e32 v77, v1
	v_mov_b32_e32 v76, v1
	v_mov_b32_dpp v98, v79 row_shr:2 row_mask:0xf bank_mask:0xf
	v_mov_b32_dpp v77, v89 row_ror:1 row_mask:0xf bank_mask:0xf
	v_mov_b32_dpp v76, v87 row_ror:1 row_mask:0xf bank_mask:0xf
	v_pk_fma_f32 v[86:87], v[192:193], v[98:99], v[194:195]
	v_mov_b32_dpp v77, v81 row_shr:1 row_mask:0xf bank_mask:0xf
	v_mov_b32_dpp v76, v79 row_shr:1 row_mask:0xf bank_mask:0xf
	v_pk_fma_f32 v[76:77], v[200:201], v[76:77], v[86:87]
	v_mov_b32_e32 v86, v105
	v_mov_b32_e32 v87, v81
	v_pk_fma_f32 v[76:77], v[100:101], v[86:87], v[76:77]
	v_mov_b32_e32 v87, v1
	v_mul_f32_e32 v86, 0xbfb8aa3b, v77
	v_exp_f32_e32 v86, v86
	v_mov_b32_dpp v87, v84 row_ror:2 row_mask:0xf bank_mask:0xf
	v_add_f32_e32 v86, 1.0, v86
	v_rcp_f32_e32 v86, v86
	v_mov_b32_dpp v87, v72 row_shr:2 row_mask:0xf bank_mask:0xf
	v_mul_f32_e32 v77, v77, v86
	v_mul_f32_e32 v77, v76, v77
	v_cvt_pk_bf16_f32 v76, v91, v93
	v_cvt_pk_bf16_f32 v77, v88, v77
	v_mov_b32_e32 v86, v1
	flat_store_dwordx2 v[74:75], v[76:77]
	v_mov_b32_e32 v77, v1
	v_mov_b32_e32 v76, v1
;     __device__ __forceinline__ void operator()(f32x4 (&acc)[2][2][4][2], const Unit& u, int wr, int wc, int fr, int fq) const {
;     ...
;                 for (int m = 0; m < 4; ++m) {
;                     float og[4];
; #pragma unroll
;                     for (int j = 0; j < 4; ++j) {
;                         const float vg = acc[ai][0][m][n][j], vv = acc[ai][1][m][n][j];
;                         const float pg = (m > 0) ? acc[ai][0][m - 1][n][j] : 0.f, pv = (m > 0) ? acc[ai][1][m - 1][n][j] : 0.f;
;                         const float g1 = dppf(dppf(0.f, pg, 2), vg, 0), g2 = dppf(dppf(0.f, pg, 3), vg, 1);
;                         const float v1 = dppf(dppf(0.f, pv, 2), vv, 0), v2 = dppf(dppf(0.f, pv, 3), vv, 1);
;                         const float cgate = bg[j] + wg0[j] * g2 + wg1[j] * g1 + wg2[j] * vg;
;                         const float cval = bv[j] + wv0[j] * v2 + wv1[j] * v1 + wv2[j] * vv;
;                         og[j] = cgate * __builtin_amdgcn_rcpf(1.0f + __builtin_amdgcn_exp2f(-1.4426950408889634f * cgate)) * cval; }
;                     const unsigned long long w = (unsigned long long)cvt_pk_bf16(og[0], og[1]) | ((unsigned long long)cvt_pk_bf16(og[2], og[3]) << 32);
;                     if (m == 0) {
;                         if (fr >= 2) *(unsigned long long*)gp = w;
;                         else { *(unsigned long long*)sb = (unsigned long long)cvt_pk_bf16(acc[ai][0][0][n][0], acc[ai][0][0][n][1]) | ((unsigned long long)cvt_pk_bf16(acc[ai][0][0][n][2], acc[ai][0][0][n][3]) << 32);
;                                *(unsigned long long*)(sb + FFc) = (unsigned long long)cvt_pk_bf16(acc[ai][1][0][n][0], acc[ai][1][0][n][1]) | ((unsigned long long)cvt_pk_bf16(acc[ai][1][0][n][2], acc[ai][1][0][n][3]) << 32); }
;                     } else *(unsigned long long*)gp = w;
;                     if (m == 3 && fr >= 14) {
;                         *(unsigned long long*)hb = (unsigned long long)cvt_pk_bf16(acc[ai][0][3][n][0], acc[ai][0][3][n][1]) | ((unsigned long long)cvt_pk_bf16(acc[ai][0][3][n][2], acc[ai][0][3][n][3]) << 32);
;                         *(unsigned long long*)(hb + FFc) = (unsigned long long)cvt_pk_bf16(acc[ai][1][3][n][0], acc[ai][1][3][n][1]) | ((unsigned long long)cvt_pk_bf16(acc[ai][1][3][n][2], acc[ai][1][3][n][3]) << 32); }
	v_mov_b32_dpp v86, v82 row_ror:2 row_mask:0xf bank_mask:0xf
	v_mov_b32_dpp v77, v84 row_ror:1 row_mask:0xf bank_mask:0xf
	v_mov_b32_dpp v76, v82 row_ror:1 row_mask:0xf bank_mask:0xf
	v_mov_b32_dpp v86, v66 row_shr:2 row_mask:0xf bank_mask:0xf
	v_mov_b32_dpp v77, v72 row_shr:1 row_mask:0xf bank_mask:0xf
	v_mov_b32_dpp v76, v66 row_shr:1 row_mask:0xf bank_mask:0xf
	v_pk_fma_f32 v[86:87], v[110:111], v[86:87], v[112:113]
	v_lshl_add_u64 v[74:75], v[74:75], 0, s[50:51]
	v_pk_fma_f32 v[76:77], v[114:115], v[76:77], v[86:87]
	v_mov_b32_e32 v86, v66
	v_mov_b32_e32 v87, v72
	v_pk_fma_f32 v[76:77], v[116:117], v[86:87], v[76:77]
	v_mov_b32_e32 v87, v1
	v_mul_f32_e32 v82, 0xbfb8aa3b, v77
	v_exp_f32_e32 v82, v82
	v_mov_b32_e32 v86, v1
	v_mov_b32_dpp v87, v85 row_ror:2 row_mask:0xf bank_mask:0xf
	v_add_f32_e32 v82, 1.0, v82
	v_rcp_f32_e32 v82, v82
	v_mov_b32_dpp v86, v83 row_ror:2 row_mask:0xf bank_mask:0xf
	v_mov_b32_dpp v87, v73 row_shr:2 row_mask:0xf bank_mask:0xf
	v_mul_f32_e32 v77, v77, v82
	v_mul_f32_e32 v84, v76, v77
	v_mov_b32_e32 v77, v1
	v_mov_b32_e32 v76, v1
	v_mov_b32_dpp v86, v67 row_shr:2 row_mask:0xf bank_mask:0xf
	v_mov_b32_dpp v77, v85 row_ror:1 row_mask:0xf bank_mask:0xf
	v_mov_b32_dpp v76, v83 row_ror:1 row_mask:0xf bank_mask:0xf
	v_pk_fma_f32 v[82:83], v[118:119], v[86:87], v[120:121]
	v_mov_b32_dpp v77, v73 row_shr:1 row_mask:0xf bank_mask:0xf
	v_mov_b32_dpp v76, v67 row_shr:1 row_mask:0xf bank_mask:0xf
	v_pk_fma_f32 v[76:77], v[122:123], v[76:77], v[82:83]
	v_mov_b32_e32 v82, v67
	v_mov_b32_e32 v83, v73
	v_pk_fma_f32 v[76:77], v[124:125], v[82:83], v[76:77]
	v_mov_b32_e32 v83, v1
	v_mul_f32_e32 v82, 0xbfb8aa3b, v77
	v_exp_f32_e32 v82, v82
	v_mov_b32_dpp v83, v80 row_ror:2 row_mask:0xf bank_mask:0xf
	v_add_f32_e32 v82, 1.0, v82
	v_rcp_f32_e32 v82, v82
	v_mov_b32_dpp v83, v70 row_shr:2 row_mask:0xf bank_mask:0xf
	v_mul_f32_e32 v77, v77, v82
	v_mov_b32_e32 v82, v1
	v_mul_f32_e32 v85, v76, v77
	v_mov_b32_e32 v77, v1
	v_mov_b32_e32 v76, v1
	v_mov_b32_dpp v82, v78 row_ror:2 row_mask:0xf bank_mask:0xf
	v_mov_b32_dpp v77, v80 row_ror:1 row_mask:0xf bank_mask:0xf
	v_mov_b32_dpp v76, v78 row_ror:1 row_mask:0xf bank_mask:0xf
	v_mov_b32_dpp v82, v68 row_shr:2 row_mask:0xf bank_mask:0xf
	v_mov_b32_dpp v77, v70 row_shr:1 row_mask:0xf bank_mask:0xf
	v_mov_b32_dpp v76, v68 row_shr:1 row_mask:0xf bank_mask:0xf
	v_pk_fma_f32 v[82:83], v[126:127], v[82:83], v[128:129]
	s_nop 0
	v_pk_fma_f32 v[76:77], v[196:197], v[76:77], v[82:83]
	v_mov_b32_e32 v82, v68
	v_mov_b32_e32 v83, v70
	v_pk_fma_f32 v[76:77], v[198:199], v[82:83], v[76:77]
	v_mov_b32_e32 v83, v1
	v_mul_f32_e32 v78, 0xbfb8aa3b, v77
	v_exp_f32_e32 v78, v78
	v_mov_b32_e32 v82, v1
	v_mov_b32_dpp v83, v81 row_ror:2 row_mask:0xf bank_mask:0xf
	v_add_f32_e32 v78, 1.0, v78
	v_rcp_f32_e32 v78, v78
	v_mov_b32_dpp v82, v79 row_ror:2 row_mask:0xf bank_mask:0xf
	v_mov_b32_dpp v83, v71 row_shr:2 row_mask:0xf bank_mask:0xf
	v_mul_f32_e32 v77, v77, v78
	v_mul_f32_e32 v80, v76, v77
	v_mov_b32_e32 v77, v1
	v_mov_b32_e32 v76, v1
	v_mov_b32_dpp v82, v69 row_shr:2 row_mask:0xf bank_mask:0xf
	v_mov_b32_dpp v77, v81 row_ror:1 row_mask:0xf bank_mask:0xf
	v_mov_b32_dpp v76, v79 row_ror:1 row_mask:0xf bank_mask:0xf
	v_pk_fma_f32 v[78:79], v[192:193], v[82:83], v[194:195]
	v_mov_b32_dpp v77, v71 row_shr:1 row_mask:0xf bank_mask:0xf
	v_mov_b32_dpp v76, v69 row_shr:1 row_mask:0xf bank_mask:0xf
	v_pk_fma_f32 v[76:77], v[200:201], v[76:77], v[78:79]
	v_mov_b32_e32 v78, v69
	v_mov_b32_e32 v79, v71
	v_pk_fma_f32 v[76:77], v[202:203], v[78:79], v[76:77]
	s_nop 0
	v_mul_f32_e32 v78, 0xbfb8aa3b, v77
	v_exp_f32_e32 v78, v78
	s_nop 0
	v_add_f32_e32 v78, 1.0, v78
	v_rcp_f32_e32 v78, v78
	s_nop 0
	v_mul_f32_e32 v77, v77, v78
	v_mul_f32_e32 v77, v76, v77
	v_cvt_pk_bf16_f32 v76, v84, v85
	v_cvt_pk_bf16_f32 v77, v80, v77
	flat_store_dwordx2 v[74:75], v[76:77]
	s_and_saveexec_b64 s[0:1], s[8:9]
	s_cbranch_execz .LBB0_1362
	v_cvt_pk_bf16_f32 v72, v72, v73
	v_cvt_pk_bf16_f32 v73, v70, v71
	flat_store_dwordx2 v[204:205], v[72:73]
	v_cvt_pk_bf16_f32 v66, v66, v67
	v_cvt_pk_bf16_f32 v67, v68, v69
	v_add_co_u32_e32 v68, vcc, 0x1000, v204
	s_nop 1
	v_addc_co_u32_e32 v69, vcc, 0, v205, vcc
	flat_store_dwordx2 v[68:69], v[66:67] offset:1536
